# LN statistics via LDS + coalesced flush; p3b gated-merge epilogue loads issued up front; S5 scan recurrence with hoisted LDS reads and 2-level FMA form
# speedup vs baseline: 1.0803x; 1.0141x over previous
.LBB0_1298:
	s_or_b64 exec, exec, s[6:7]
	s_movk_i32 s2, 0x2100
	v_lshlrev_b32_e32 v62, 23, v55
	v_mov_b32_e32 v63, v5
	v_mul_lo_u32 v61, v242, s2
	v_lshl_add_u64 v[64:65], s[76:77], 0, v[62:63]
	v_add_u32_e32 v66, 32, v61
	s_movk_i32 s2, 0x210
	v_lshlrev_b64 v[52:53], 1, v[52:53]
	v_lshl_add_u32 v73, v243, 2, v66
	v_lshl_add_u32 v70, v244, 2, v66
	v_mad_u32_u24 v74, v243, s2, v66
	v_lshl_add_u64 v[64:65], v[64:65], 0, v[52:53]
	v_lshlrev_b32_e32 v66, 1, v243
	v_mov_b32_e32 v67, v5
	v_lshl_add_u64 v[52:53], s[36:37], 0, v[52:53]
	v_lshlrev_b32_e32 v61, 2, v54
	v_lshlrev_b32_e32 v75, 5, v54
	v_lshl_add_u64 v[64:65], v[64:65], 0, v[66:67]
	v_mul_u32_u24_e32 v54, 0x840, v54
	v_lshl_add_u64 v[66:67], v[52:53], 0, v[4:5]
	v_sub_u32_e32 v52, v241, v243
	v_cmp_eq_u32_e64 s[4:5], 0, v55
	v_subrev_u32_e32 v72, 17, v52
	v_add_u32_e32 v73, v73, v54
	s_waitcnt vmcnt(0)
	v_mov_b64_e32 v[52:53], v[56:57]
	v_lshrrev_b32_e32 v7, 4, v241
	v_pk_mov_b32 v[62:63], v[228:229], v[228:229] op_sel:[1,0]
	s_mov_b32 s2, 0
	v_xad_u32 v4, v61, -1, v241
	v_or_b32_e32 v71, 16, v243
	s_mov_b64 s[8:9], 0
	v_add_u32_e32 v74, v74, v75
	s_mov_b32 s10, 0
	v_mov_b64_e32 v[54:55], v[58:59]
	v_mov_b32_e32 v158, v70
	v_add_u32_e32 v159, 16, v70
	v_add_u32_e32 v176, 32, v70
	v_add_u32_e32 v177, 48, v70
	v_add_u32_e32 v178, 64, v70
	v_add_u32_e32 v179, 80, v70
	v_add_u32_e32 v180, 96, v70
	v_add_u32_e32 v181, 112, v70
	v_add_u32_e32 v182, 128, v70
	v_add_u32_e32 v183, 144, v70
	v_add_u32_e32 v184, 160, v70
	v_add_u32_e32 v185, 176, v70
	v_add_u32_e32 v186, 192, v70
	v_add_u32_e32 v187, 208, v70
	v_add_u32_e32 v188, 224, v70
	v_add_u32_e32 v189, 240, v70
	s_branch .LBB0_1300
.LBB0_1299:
	s_or_b64 exec, exec, s[6:7]
	v_mfma_f32_16x16x32_bf16 v[76:79], v[56:59], v[8:11], 0
	v_add_u32_e32 v75, 0x400, v73
	v_cmp_eq_u32_e64 s[6:7], s10, v7
	v_add_u32_e32 v72, -16, v72
	v_mfma_f32_16x16x32_bf16 v[80:83], v[56:59], v[12:15], 0
	s_nop 7
	ds_write2_b32 v73, v76, v80 offset1:16
	ds_write2_b32 v73, v77, v81 offset0:132 offset1:148
	ds_write2_b32 v75, v78, v82 offset0:8 offset1:24
	ds_write2_b32 v75, v79, v83 offset0:140 offset1:156
	v_mfma_f32_16x16x32_bf16 v[76:79], v[56:59], v[16:19], 0
	v_mfma_f32_16x16x32_bf16 v[80:83], v[56:59], v[20:23], 0
	s_nop 7
	ds_write2_b32 v73, v76, v80 offset0:32 offset1:48
	ds_write2_b32 v73, v77, v81 offset0:164 offset1:180
	ds_write2_b32 v75, v78, v82 offset0:40 offset1:56
	ds_write2_b32 v75, v79, v83 offset0:172 offset1:188
	v_mfma_f32_16x16x32_bf16 v[76:79], v[56:59], v[24:27], 0
	v_mfma_f32_16x16x32_bf16 v[80:83], v[56:59], v[28:31], 0
	s_nop 7
	ds_write2_b32 v73, v76, v80 offset0:64 offset1:80
	ds_write2_b32 v73, v77, v81 offset0:196 offset1:212
	ds_write2_b32 v75, v78, v82 offset0:72 offset1:88
	ds_write2_b32 v75, v79, v83 offset0:204 offset1:220
	v_mfma_f32_16x16x32_bf16 v[76:79], v[56:59], v[32:35], 0
	v_mfma_f32_16x16x32_bf16 v[56:59], v[56:59], v[36:39], 0
	s_nop 7
	ds_write2_b32 v73, v76, v56 offset0:96 offset1:112
	ds_write2_b32 v73, v77, v57 offset0:228 offset1:244
	ds_write2_b32 v75, v78, v58 offset0:104 offset1:120
	ds_write2_b32 v75, v79, v59 offset0:236 offset1:252
	ds_read2st64_b32 v[122:123], v158 offset1:1
	ds_read2st64_b32 v[124:125], v159 offset0:2 offset1:3
	ds_read2st64_b32 v[126:127], v176 offset0:4 offset1:5
	ds_read2st64_b32 v[128:129], v177 offset0:6 offset1:7
	ds_read2st64_b32 v[130:131], v178 offset0:8 offset1:9
	ds_read2st64_b32 v[132:133], v179 offset0:10 offset1:11
	ds_read2st64_b32 v[134:135], v180 offset0:12 offset1:13
	ds_read2st64_b32 v[136:137], v181 offset0:14 offset1:15
	ds_read2st64_b32 v[138:139], v182 offset0:16 offset1:17
	ds_read2st64_b32 v[140:141], v183 offset0:18 offset1:19
	ds_read2st64_b32 v[142:143], v184 offset0:20 offset1:21
	ds_read2st64_b32 v[144:145], v185 offset0:22 offset1:23
	s_waitcnt lgkmcnt(10)
	v_fma_f32 v156, -v229, v69, v122
	v_fma_f32 v157, v229, v68, v123
	v_fma_f32 v154, v228, v68, v156
	v_fma_f32 v155, v228, v69, v157
	ds_write2st64_b32 v158, v154, v155 offset1:1
	ds_read2st64_b32 v[146:147], v186 offset0:24 offset1:25
	v_fma_f32 v156, -v229, v155, v124
	v_fma_f32 v157, v229, v154, v125
	v_fma_f32 v68, v228, v154, v156
	v_fma_f32 v69, v228, v155, v157
	ds_write2st64_b32 v159, v68, v69 offset0:2 offset1:3
	s_waitcnt lgkmcnt(11)
	ds_read2st64_b32 v[148:149], v187 offset0:26 offset1:27
	v_fma_f32 v156, -v229, v69, v126
	v_fma_f32 v157, v229, v68, v127
	v_fma_f32 v154, v228, v68, v156
	v_fma_f32 v155, v228, v69, v157
	ds_write2st64_b32 v176, v154, v155 offset0:4 offset1:5
	s_waitcnt lgkmcnt(11)
	ds_read2st64_b32 v[150:151], v188 offset0:28 offset1:29
	v_fma_f32 v156, -v229, v155, v128
	v_fma_f32 v157, v229, v154, v129
	v_fma_f32 v68, v228, v154, v156
	v_fma_f32 v69, v228, v155, v157
	ds_write2st64_b32 v177, v68, v69 offset0:6 offset1:7
	s_waitcnt lgkmcnt(11)
	ds_read2st64_b32 v[152:153], v189 offset0:30 offset1:31
	v_fma_f32 v156, -v229, v69, v130
	v_fma_f32 v157, v229, v68, v131
	v_fma_f32 v154, v228, v68, v156
	v_fma_f32 v155, v228, v69, v157
	ds_write2st64_b32 v178, v154, v155 offset0:8 offset1:9
	v_fma_f32 v156, -v229, v155, v132
	v_fma_f32 v157, v229, v154, v133
	v_fma_f32 v68, v228, v154, v156
	v_fma_f32 v69, v228, v155, v157
	ds_write2st64_b32 v179, v68, v69 offset0:10 offset1:11
	v_fma_f32 v156, -v229, v69, v134
	v_fma_f32 v157, v229, v68, v135
	v_fma_f32 v154, v228, v68, v156
	v_fma_f32 v155, v228, v69, v157
	ds_write2st64_b32 v180, v154, v155 offset0:12 offset1:13
	v_fma_f32 v156, -v229, v155, v136
	v_fma_f32 v157, v229, v154, v137
	v_fma_f32 v68, v228, v154, v156
	v_fma_f32 v69, v228, v155, v157
	ds_write2st64_b32 v181, v68, v69 offset0:14 offset1:15
	s_waitcnt lgkmcnt(14)
	v_fma_f32 v156, -v229, v69, v138
	v_fma_f32 v157, v229, v68, v139
	v_fma_f32 v154, v228, v68, v156
	v_fma_f32 v155, v228, v69, v157
	ds_write2st64_b32 v182, v154, v155 offset0:16 offset1:17
	v_fma_f32 v156, -v229, v155, v140
	v_fma_f32 v157, v229, v154, v141
	v_fma_f32 v68, v228, v154, v156
	v_fma_f32 v69, v228, v155, v157
	ds_write2st64_b32 v183, v68, v69 offset0:18 offset1:19
	s_waitcnt lgkmcnt(14)
	v_fma_f32 v156, -v229, v69, v142
	v_fma_f32 v157, v229, v68, v143
	v_fma_f32 v154, v228, v68, v156
	v_fma_f32 v155, v228, v69, v157
	ds_write2st64_b32 v184, v154, v155 offset0:20 offset1:21
	v_fma_f32 v156, -v229, v155, v144
	v_fma_f32 v157, v229, v154, v145
	v_fma_f32 v68, v228, v154, v156
	v_fma_f32 v69, v228, v155, v157
	ds_write2st64_b32 v185, v68, v69 offset0:22 offset1:23
	s_waitcnt lgkmcnt(12)
	v_fma_f32 v156, -v229, v69, v146
	v_fma_f32 v157, v229, v68, v147
	v_fma_f32 v154, v228, v68, v156
	v_fma_f32 v155, v228, v69, v157
	ds_write2st64_b32 v186, v154, v155 offset0:24 offset1:25
	v_fma_f32 v156, -v229, v155, v148
	v_fma_f32 v157, v229, v154, v149
	v_fma_f32 v68, v228, v154, v156
	v_fma_f32 v69, v228, v155, v157
	ds_write2st64_b32 v187, v68, v69 offset0:26 offset1:27
	s_waitcnt lgkmcnt(10)
	v_fma_f32 v156, -v229, v69, v150
	v_fma_f32 v157, v229, v68, v151
	v_fma_f32 v154, v228, v68, v156
	v_fma_f32 v155, v228, v69, v157
	ds_write2st64_b32 v188, v154, v155 offset0:28 offset1:29
	v_fma_f32 v156, -v229, v155, v152
	v_fma_f32 v157, v229, v154, v153
	v_fma_f32 v68, v228, v154, v156
	v_fma_f32 v69, v228, v155, v157
	ds_write2st64_b32 v189, v68, v69 offset0:30 offset1:31
	v_add_u32_e32 v75, s2, v61
	s_add_i32 s2, s2, 16
	ds_read_b128 v[124:127], v74
	ds_read_b128 v[128:131], v74 offset:16
	ds_read_b128 v[132:135], v74 offset:128
	ds_read_b128 v[136:139], v74 offset:144
	ds_read_b128 v[140:143], v74 offset:256
	ds_read_b128 v[144:147], v74 offset:272
	ds_read_b128 v[148:151], v74 offset:384
	ds_read_b128 v[152:155], v74 offset:400
	s_or_b64 s[8:9], s[6:7], s[8:9]
	s_waitcnt lgkmcnt(6)
	v_cvt_pk_bf16_f32 v160, v124, v125
	v_cvt_pk_bf16_f32 v161, v126, v127
	v_cvt_pk_bf16_f32 v162, v128, v129
	v_cvt_pk_bf16_f32 v163, v130, v131
	s_waitcnt lgkmcnt(4)
	v_cvt_pk_bf16_f32 v164, v132, v133
	v_cvt_pk_bf16_f32 v165, v134, v135
	v_cvt_pk_bf16_f32 v166, v136, v137
	v_cvt_pk_bf16_f32 v167, v138, v139
	v_mfma_f32_16x16x32_bf16 v[56:59], v[160:163], v[0:3], 0
	s_waitcnt lgkmcnt(2)
	v_cvt_pk_bf16_f32 v168, v140, v141
	v_cvt_pk_bf16_f32 v169, v142, v143
	v_cvt_pk_bf16_f32 v170, v144, v145
	v_cvt_pk_bf16_f32 v171, v146, v147
	v_mfma_f32_16x16x32_bf16 v[56:59], v[164:167], v[40:43], v[56:59]
	s_waitcnt lgkmcnt(0)
	v_cvt_pk_bf16_f32 v172, v148, v149
	v_cvt_pk_bf16_f32 v173, v150, v151
	v_cvt_pk_bf16_f32 v174, v152, v153
	v_cvt_pk_bf16_f32 v175, v154, v155
	v_mfma_f32_16x16x32_bf16 v[56:59], v[168:171], v[44:47], v[56:59]
	s_nop 1
	v_mfma_f32_16x16x32_bf16 v[56:59], v[172:175], v[48:51], v[56:59]
	v_cndmask_b32_e64 v76, v4, v75, s[4:5]
	v_add_u32_e32 v76, v76, v240
	v_ashrrev_i32_e32 v77, 31, v76
	v_lshlrev_b64 v[76:77], 10, v[76:77]
	s_nop 3
	v_cvt_pk_bf16_f32 v56, v56, s0
	v_lshl_add_u64 v[76:77], v[64:65], 0, v[76:77]
	global_store_short v[76:77], v56, off
	v_add_u32_e32 v56, 1, v75
	v_xad_u32 v76, v75, -2, v241
	v_cndmask_b32_e64 v56, v76, v56, s[4:5]
	v_add_u32_e32 v56, v56, v240
	v_cvt_pk_bf16_f32 v76, v57, s0
	v_ashrrev_i32_e32 v57, 31, v56
	v_lshlrev_b64 v[56:57], 10, v[56:57]
	v_lshl_add_u64 v[56:57], v[64:65], 0, v[56:57]
	global_store_short v[56:57], v76, off
	v_add_u32_e32 v56, 2, v75
	v_xad_u32 v57, v75, -3, v241
	v_cndmask_b32_e64 v56, v57, v56, s[4:5]
	v_add_u32_e32 v56, v56, v240
	v_ashrrev_i32_e32 v57, 31, v56
	v_lshlrev_b64 v[56:57], 10, v[56:57]
	v_cvt_pk_bf16_f32 v58, v58, s0
	v_lshl_add_u64 v[56:57], v[64:65], 0, v[56:57]
	global_store_short v[56:57], v58, off
	v_add_u32_e32 v56, 3, v75
	v_xad_u32 v57, v75, -4, v241
	v_cndmask_b32_e64 v56, v57, v56, s[4:5]
	v_add_u32_e32 v56, v56, v240
	v_ashrrev_i32_e32 v57, 31, v56
	v_lshlrev_b64 v[56:57], 10, v[56:57]
	v_cvt_pk_bf16_f32 v58, v59, s0
	v_lshl_add_u64 v[56:57], v[64:65], 0, v[56:57]
	global_store_short v[56:57], v58, off
	s_waitcnt vmcnt(4)
	v_mov_b64_e32 v[58:59], v[54:55]
	v_add_u32_e32 v4, -16, v4
	v_mov_b64_e32 v[56:57], v[52:53]
	s_andn2_b64 exec, exec, s[8:9]
	s_cbranch_execz .LBB0_1314

.LBB0_1584:
	s_or_b64 exec, exec, s[6:7]
	s_movk_i32 s2, 0x2100
	v_lshlrev_b32_e32 v62, 23, v55
	v_mov_b32_e32 v63, v5
	v_mul_lo_u32 v61, v242, s2
	v_lshl_add_u64 v[64:65], s[76:77], 0, v[62:63]
	v_add_u32_e32 v66, 32, v61
	s_movk_i32 s2, 0x210
	v_lshlrev_b64 v[52:53], 1, v[52:53]
	v_lshl_add_u32 v73, v243, 2, v66
	v_lshl_add_u32 v70, v244, 2, v66
	v_mad_u32_u24 v74, v243, s2, v66
	v_lshl_add_u64 v[64:65], v[64:65], 0, v[52:53]
	v_lshlrev_b32_e32 v66, 1, v243
	v_mov_b32_e32 v67, v5
	v_lshl_add_u64 v[52:53], s[36:37], 0, v[52:53]
	v_lshlrev_b32_e32 v61, 2, v54
	v_lshlrev_b32_e32 v75, 5, v54
	v_lshl_add_u64 v[64:65], v[64:65], 0, v[66:67]
	v_mul_u32_u24_e32 v54, 0x840, v54
	v_lshl_add_u64 v[66:67], v[52:53], 0, v[4:5]
	v_sub_u32_e32 v52, v241, v243
	v_cmp_eq_u32_e64 s[4:5], 0, v55
	v_subrev_u32_e32 v72, 17, v52
	v_add_u32_e32 v73, v73, v54
	s_waitcnt vmcnt(0)
	v_mov_b64_e32 v[52:53], v[56:57]
	v_lshrrev_b32_e32 v7, 4, v241
	v_pk_mov_b32 v[62:63], v[228:229], v[228:229] op_sel:[1,0]
	s_mov_b32 s2, 0
	v_xad_u32 v4, v61, -1, v241
	v_or_b32_e32 v71, 16, v243
	s_mov_b64 s[8:9], 0
	v_add_u32_e32 v74, v74, v75
	s_mov_b32 s3, 0
	v_mov_b64_e32 v[54:55], v[58:59]
	v_mov_b32_e32 v136, v70
	v_add_u32_e32 v137, 16, v70
	v_add_u32_e32 v138, 32, v70
	v_add_u32_e32 v139, 48, v70
	v_add_u32_e32 v140, 64, v70
	v_add_u32_e32 v141, 80, v70
	v_add_u32_e32 v142, 96, v70
	v_add_u32_e32 v143, 112, v70
	v_add_u32_e32 v144, 128, v70
	v_add_u32_e32 v145, 144, v70
	v_add_u32_e32 v146, 160, v70
	v_add_u32_e32 v147, 176, v70
	v_add_u32_e32 v148, 192, v70
	v_add_u32_e32 v149, 208, v70
	v_add_u32_e32 v150, 224, v70
	v_add_u32_e32 v151, 240, v70
	s_branch .LBB0_1586
.LBB0_1585:
	s_or_b64 exec, exec, s[6:7]
	v_mfma_f32_16x16x32_bf16 v[76:79], v[56:59], v[8:11], 0
	v_add_u32_e32 v75, 0x400, v73
	v_cmp_eq_u32_e64 s[6:7], s3, v7
	v_add_u32_e32 v72, -16, v72
	v_mfma_f32_16x16x32_bf16 v[80:83], v[56:59], v[12:15], 0
	s_nop 7
	ds_write2_b32 v73, v76, v80 offset1:16
	ds_write2_b32 v73, v77, v81 offset0:132 offset1:148
	ds_write2_b32 v75, v78, v82 offset0:8 offset1:24
	ds_write2_b32 v75, v79, v83 offset0:140 offset1:156
	v_mfma_f32_16x16x32_bf16 v[76:79], v[56:59], v[16:19], 0
	v_mfma_f32_16x16x32_bf16 v[80:83], v[56:59], v[20:23], 0
	s_nop 7
	ds_write2_b32 v73, v76, v80 offset0:32 offset1:48
	ds_write2_b32 v73, v77, v81 offset0:164 offset1:180
	ds_write2_b32 v75, v78, v82 offset0:40 offset1:56
	ds_write2_b32 v75, v79, v83 offset0:172 offset1:188
	v_mfma_f32_16x16x32_bf16 v[76:79], v[56:59], v[24:27], 0
	v_mfma_f32_16x16x32_bf16 v[80:83], v[56:59], v[28:31], 0
	s_nop 7
	ds_write2_b32 v73, v76, v80 offset0:64 offset1:80
	ds_write2_b32 v73, v77, v81 offset0:196 offset1:212
	ds_write2_b32 v75, v78, v82 offset0:72 offset1:88
	ds_write2_b32 v75, v79, v83 offset0:204 offset1:220
	v_mfma_f32_16x16x32_bf16 v[76:79], v[56:59], v[32:35], 0
	v_mfma_f32_16x16x32_bf16 v[56:59], v[56:59], v[36:39], 0
	s_nop 7
	ds_write2_b32 v73, v76, v56 offset0:96 offset1:112
	ds_write2_b32 v73, v77, v57 offset0:228 offset1:244
	ds_write2_b32 v75, v78, v58 offset0:104 offset1:120
	ds_write2_b32 v75, v79, v59 offset0:236 offset1:252
	ds_read2st64_b32 v[84:85], v136 offset1:1
	ds_read2st64_b32 v[86:87], v137 offset0:2 offset1:3
	ds_read2st64_b32 v[88:89], v138 offset0:4 offset1:5
	ds_read2st64_b32 v[90:91], v139 offset0:6 offset1:7
	ds_read2st64_b32 v[92:93], v140 offset0:8 offset1:9
	ds_read2st64_b32 v[94:95], v141 offset0:10 offset1:11
	ds_read2st64_b32 v[96:97], v142 offset0:12 offset1:13
	ds_read2st64_b32 v[98:99], v143 offset0:14 offset1:15
	ds_read2st64_b32 v[100:101], v144 offset0:16 offset1:17
	ds_read2st64_b32 v[102:103], v145 offset0:18 offset1:19
	ds_read2st64_b32 v[104:105], v146 offset0:20 offset1:21
	ds_read2st64_b32 v[106:107], v147 offset0:22 offset1:23
	s_waitcnt lgkmcnt(10)
	v_fma_f32 v118, -v229, v69, v84
	v_fma_f32 v119, v229, v68, v85
	v_fma_f32 v116, v228, v68, v118
	v_fma_f32 v117, v228, v69, v119
	ds_write2st64_b32 v136, v116, v117 offset1:1
	ds_read2st64_b32 v[108:109], v148 offset0:24 offset1:25
	v_fma_f32 v118, -v229, v117, v86
	v_fma_f32 v119, v229, v116, v87
	v_fma_f32 v68, v228, v116, v118
	v_fma_f32 v69, v228, v117, v119
	ds_write2st64_b32 v137, v68, v69 offset0:2 offset1:3
	s_waitcnt lgkmcnt(11)
	ds_read2st64_b32 v[110:111], v149 offset0:26 offset1:27
	v_fma_f32 v118, -v229, v69, v88
	v_fma_f32 v119, v229, v68, v89
	v_fma_f32 v116, v228, v68, v118
	v_fma_f32 v117, v228, v69, v119
	ds_write2st64_b32 v138, v116, v117 offset0:4 offset1:5
	s_waitcnt lgkmcnt(11)
	ds_read2st64_b32 v[112:113], v150 offset0:28 offset1:29
	v_fma_f32 v118, -v229, v117, v90
	v_fma_f32 v119, v229, v116, v91
	v_fma_f32 v68, v228, v116, v118
	v_fma_f32 v69, v228, v117, v119
	ds_write2st64_b32 v139, v68, v69 offset0:6 offset1:7
	s_waitcnt lgkmcnt(11)
	ds_read2st64_b32 v[114:115], v151 offset0:30 offset1:31
	v_fma_f32 v118, -v229, v69, v92
	v_fma_f32 v119, v229, v68, v93
	v_fma_f32 v116, v228, v68, v118
	v_fma_f32 v117, v228, v69, v119
	ds_write2st64_b32 v140, v116, v117 offset0:8 offset1:9
	v_fma_f32 v118, -v229, v117, v94
	v_fma_f32 v119, v229, v116, v95
	v_fma_f32 v68, v228, v116, v118
	v_fma_f32 v69, v228, v117, v119
	ds_write2st64_b32 v141, v68, v69 offset0:10 offset1:11
	v_fma_f32 v118, -v229, v69, v96
	v_fma_f32 v119, v229, v68, v97
	v_fma_f32 v116, v228, v68, v118
	v_fma_f32 v117, v228, v69, v119
	ds_write2st64_b32 v142, v116, v117 offset0:12 offset1:13
	v_fma_f32 v118, -v229, v117, v98
	v_fma_f32 v119, v229, v116, v99
	v_fma_f32 v68, v228, v116, v118
	v_fma_f32 v69, v228, v117, v119
	ds_write2st64_b32 v143, v68, v69 offset0:14 offset1:15
	s_waitcnt lgkmcnt(14)
	v_fma_f32 v118, -v229, v69, v100
	v_fma_f32 v119, v229, v68, v101
	v_fma_f32 v116, v228, v68, v118
	v_fma_f32 v117, v228, v69, v119
	ds_write2st64_b32 v144, v116, v117 offset0:16 offset1:17
	v_fma_f32 v118, -v229, v117, v102
	v_fma_f32 v119, v229, v116, v103
	v_fma_f32 v68, v228, v116, v118
	v_fma_f32 v69, v228, v117, v119
	ds_write2st64_b32 v145, v68, v69 offset0:18 offset1:19
	s_waitcnt lgkmcnt(14)
	v_fma_f32 v118, -v229, v69, v104
	v_fma_f32 v119, v229, v68, v105
	v_fma_f32 v116, v228, v68, v118
	v_fma_f32 v117, v228, v69, v119
	ds_write2st64_b32 v146, v116, v117 offset0:20 offset1:21
	v_fma_f32 v118, -v229, v117, v106
	v_fma_f32 v119, v229, v116, v107
	v_fma_f32 v68, v228, v116, v118
	v_fma_f32 v69, v228, v117, v119
	ds_write2st64_b32 v147, v68, v69 offset0:22 offset1:23
	s_waitcnt lgkmcnt(12)
	v_fma_f32 v118, -v229, v69, v108
	v_fma_f32 v119, v229, v68, v109
	v_fma_f32 v116, v228, v68, v118
	v_fma_f32 v117, v228, v69, v119
	ds_write2st64_b32 v148, v116, v117 offset0:24 offset1:25
	v_fma_f32 v118, -v229, v117, v110
	v_fma_f32 v119, v229, v116, v111
	v_fma_f32 v68, v228, v116, v118
	v_fma_f32 v69, v228, v117, v119
	ds_write2st64_b32 v149, v68, v69 offset0:26 offset1:27
	s_waitcnt lgkmcnt(10)
	v_fma_f32 v118, -v229, v69, v112
	v_fma_f32 v119, v229, v68, v113
	v_fma_f32 v116, v228, v68, v118
	v_fma_f32 v117, v228, v69, v119
	ds_write2st64_b32 v150, v116, v117 offset0:28 offset1:29
	v_fma_f32 v118, -v229, v117, v114
	v_fma_f32 v119, v229, v116, v115
	v_fma_f32 v68, v228, v116, v118
	v_fma_f32 v69, v228, v117, v119
	ds_write2st64_b32 v151, v68, v69 offset0:30 offset1:31
	v_add_u32_e32 v75, s2, v61
	s_add_i32 s2, s2, 16
	ds_read_b128 v[84:87], v74
	ds_read_b128 v[88:91], v74 offset:16
	ds_read_b128 v[92:95], v74 offset:128
	ds_read_b128 v[96:99], v74 offset:144
	ds_read_b128 v[100:103], v74 offset:256
	ds_read_b128 v[104:107], v74 offset:272
	ds_read_b128 v[108:111], v74 offset:384
	ds_read_b128 v[112:115], v74 offset:400
	s_or_b64 s[8:9], s[6:7], s[8:9]
	s_waitcnt lgkmcnt(6)
	v_cvt_pk_bf16_f32 v120, v84, v85
	v_cvt_pk_bf16_f32 v121, v86, v87
	v_cvt_pk_bf16_f32 v122, v88, v89
	v_cvt_pk_bf16_f32 v123, v90, v91
	s_waitcnt lgkmcnt(4)
	v_cvt_pk_bf16_f32 v124, v92, v93
	v_cvt_pk_bf16_f32 v125, v94, v95
	v_cvt_pk_bf16_f32 v126, v96, v97
	v_cvt_pk_bf16_f32 v127, v98, v99
	v_mfma_f32_16x16x32_bf16 v[56:59], v[120:123], v[0:3], 0
	s_waitcnt lgkmcnt(2)
	v_cvt_pk_bf16_f32 v128, v100, v101
	v_cvt_pk_bf16_f32 v129, v102, v103
	v_cvt_pk_bf16_f32 v130, v104, v105
	v_cvt_pk_bf16_f32 v131, v106, v107
	v_mfma_f32_16x16x32_bf16 v[56:59], v[124:127], v[40:43], v[56:59]
	s_waitcnt lgkmcnt(0)
	v_cvt_pk_bf16_f32 v132, v108, v109
	v_cvt_pk_bf16_f32 v133, v110, v111
	v_cvt_pk_bf16_f32 v134, v112, v113
	v_cvt_pk_bf16_f32 v135, v114, v115
	v_mfma_f32_16x16x32_bf16 v[56:59], v[128:131], v[44:47], v[56:59]
	s_nop 1
	v_mfma_f32_16x16x32_bf16 v[56:59], v[132:135], v[48:51], v[56:59]
	v_cndmask_b32_e64 v76, v4, v75, s[4:5]
	v_add_u32_e32 v76, v76, v240
	v_ashrrev_i32_e32 v77, 31, v76
	v_lshlrev_b64 v[76:77], 10, v[76:77]
	s_nop 3
	v_cvt_pk_bf16_f32 v56, v56, s0
	v_lshl_add_u64 v[76:77], v[64:65], 0, v[76:77]
	global_store_short v[76:77], v56, off
	v_add_u32_e32 v56, 1, v75
	v_xad_u32 v76, v75, -2, v241
	v_cndmask_b32_e64 v56, v76, v56, s[4:5]
	v_add_u32_e32 v56, v56, v240
	v_cvt_pk_bf16_f32 v76, v57, s0
	v_ashrrev_i32_e32 v57, 31, v56
	v_lshlrev_b64 v[56:57], 10, v[56:57]
	v_lshl_add_u64 v[56:57], v[64:65], 0, v[56:57]
	global_store_short v[56:57], v76, off
	v_add_u32_e32 v56, 2, v75
	v_xad_u32 v57, v75, -3, v241
	v_cndmask_b32_e64 v56, v57, v56, s[4:5]
	v_add_u32_e32 v56, v56, v240
	v_ashrrev_i32_e32 v57, 31, v56
	v_lshlrev_b64 v[56:57], 10, v[56:57]
	v_cvt_pk_bf16_f32 v58, v58, s0
	v_lshl_add_u64 v[56:57], v[64:65], 0, v[56:57]
	global_store_short v[56:57], v58, off
	v_add_u32_e32 v56, 3, v75
	v_xad_u32 v57, v75, -4, v241
	v_cndmask_b32_e64 v56, v57, v56, s[4:5]
	v_add_u32_e32 v56, v56, v240
	v_ashrrev_i32_e32 v57, 31, v56
	v_lshlrev_b64 v[56:57], 10, v[56:57]
	v_cvt_pk_bf16_f32 v58, v59, s0
	v_lshl_add_u64 v[56:57], v[64:65], 0, v[56:57]
	global_store_short v[56:57], v58, off
	s_waitcnt vmcnt(4)
	v_mov_b64_e32 v[58:59], v[54:55]
	v_add_u32_e32 v4, -16, v4
	v_mov_b64_e32 v[56:57], v[52:53]
	s_andn2_b64 exec, exec, s[8:9]
	s_cbranch_execz .LBB0_1600

.LBB0_1745:
	s_setprio 1
	ds_read_b128 v[148:151], v144
	ds_read_b128 v[152:155], v145 offset:36864
	ds_read_b128 v[156:159], v145 offset:41472
	s_waitcnt lgkmcnt(1)
	v_mfma_f32_32x32x16_bf16 v[48:63], v[148:151], v[152:155], v[48:63]
	global_load_dwordx4 v[96:99], v160, s[98:99] offset:256
	global_load_dwordx4 v[100:103], v164, s[98:99] offset:256
	s_waitcnt lgkmcnt(0)
	v_mfma_f32_32x32x16_bf16 v[32:47], v[148:151], v[156:159], v[32:47]
	global_load_dwordx4 v[104:107], v166, s[98:99] offset:256
	global_load_dwordx4 v[108:111], v168, s[98:99] offset:256
	ds_read_b128 v[148:151], v144 offset:4608
	s_waitcnt lgkmcnt(0)
	v_mfma_f32_32x32x16_bf16 v[16:31], v[148:151], v[152:155], v[16:31]
	global_load_dwordx4 v[112:115], v162, s[98:99]
	global_load_dwordx4 v[116:119], v130, s[98:99]
	v_mfma_f32_32x32x16_bf16 v[0:15], v[148:151], v[156:159], v[0:15]
	global_load_dwordx4 v[120:123], v170, s[98:99]
	global_load_dwordx4 v[124:127], v172, s[98:99] offset:-128
	ds_read_b128 v[148:151], v144 offset:32
	ds_read_b128 v[152:155], v145 offset:36896
	ds_read_b128 v[156:159], v145 offset:41504
	s_waitcnt lgkmcnt(1)
	v_mfma_f32_32x32x16_bf16 v[48:63], v[148:151], v[152:155], v[48:63]
	s_waitcnt lgkmcnt(0)
	v_mfma_f32_32x32x16_bf16 v[32:47], v[148:151], v[156:159], v[32:47]
	ds_read_b128 v[148:151], v144 offset:4640
	s_waitcnt lgkmcnt(0)
	v_mfma_f32_32x32x16_bf16 v[16:31], v[148:151], v[152:155], v[16:31]
	v_mfma_f32_32x32x16_bf16 v[0:15], v[148:151], v[156:159], v[0:15]
	s_waitcnt vmcnt(15)
	ds_write_b128 v146, v[64:67] offset:18432
	ds_read_b128 v[148:151], v144 offset:64
	ds_read_b128 v[152:155], v145 offset:36928
	ds_read_b128 v[156:159], v145 offset:41536
	s_waitcnt lgkmcnt(1)
	v_mfma_f32_32x32x16_bf16 v[48:63], v[148:151], v[152:155], v[48:63]
	s_waitcnt vmcnt(14)
	ds_write_b128 v146, v[68:71] offset:23040
	s_waitcnt lgkmcnt(1)
	v_mfma_f32_32x32x16_bf16 v[32:47], v[148:151], v[156:159], v[32:47]
	s_waitcnt vmcnt(13)
	ds_write_b128 v146, v[72:75] offset:27648
	ds_read_b128 v[148:151], v144 offset:4672
	s_waitcnt lgkmcnt(0)
	v_mfma_f32_32x32x16_bf16 v[16:31], v[148:151], v[152:155], v[16:31]
	s_waitcnt vmcnt(12)
	ds_write_b128 v146, v[76:79] offset:32256
	v_mfma_f32_32x32x16_bf16 v[0:15], v[148:151], v[156:159], v[0:15]
	s_waitcnt vmcnt(11)
	ds_write_b128 v146, v[80:83] offset:55296
	ds_read_b128 v[148:151], v144 offset:96
	ds_read_b128 v[152:155], v145 offset:36960
	ds_read_b128 v[156:159], v145 offset:41568
	s_waitcnt lgkmcnt(1)
	v_mfma_f32_32x32x16_bf16 v[48:63], v[148:151], v[152:155], v[48:63]
	s_waitcnt vmcnt(10)
	ds_write_b128 v146, v[84:87] offset:59904
	s_waitcnt lgkmcnt(1)
	v_mfma_f32_32x32x16_bf16 v[32:47], v[148:151], v[156:159], v[32:47]
	s_waitcnt vmcnt(9)
	ds_write_b128 v146, v[88:91] offset:64512
	ds_read_b128 v[148:151], v144 offset:4704
	s_waitcnt lgkmcnt(0)
	v_mfma_f32_32x32x16_bf16 v[16:31], v[148:151], v[152:155], v[16:31]
	s_waitcnt vmcnt(8)
	ds_write_b128 v147, v[92:95] offset:13824
	v_mfma_f32_32x32x16_bf16 v[0:15], v[148:151], v[156:159], v[0:15]
	s_setprio 0
	s_waitcnt lgkmcnt(0)
	s_barrier
	s_setprio 1
	ds_read_b128 v[148:151], v144 offset:18432
	ds_read_b128 v[152:155], v145 offset:55296
	ds_read_b128 v[156:159], v145 offset:59904
	s_waitcnt lgkmcnt(1)
	v_mfma_f32_32x32x16_bf16 v[48:63], v[148:151], v[152:155], v[48:63]
	global_load_dwordx4 v[64:67], v160, s[98:99] offset:384
	global_load_dwordx4 v[68:71], v164, s[98:99] offset:384
	s_waitcnt lgkmcnt(0)
	v_mfma_f32_32x32x16_bf16 v[32:47], v[148:151], v[156:159], v[32:47]
	global_load_dwordx4 v[72:75], v166, s[98:99] offset:384
	global_load_dwordx4 v[76:79], v168, s[98:99] offset:384
	ds_read_b128 v[148:151], v144 offset:23040
	s_waitcnt lgkmcnt(0)
	v_mfma_f32_32x32x16_bf16 v[16:31], v[148:151], v[152:155], v[16:31]
	global_load_dwordx4 v[80:83], v162, s[98:99] offset:128
	global_load_dwordx4 v[84:87], v131, s[98:99]
	v_mfma_f32_32x32x16_bf16 v[0:15], v[148:151], v[156:159], v[0:15]
	global_load_dwordx4 v[88:91], v170, s[98:99] offset:128
	global_load_dwordx4 v[92:95], v172, s[98:99]
	ds_read_b128 v[148:151], v144 offset:18464
	ds_read_b128 v[152:155], v145 offset:55328
	ds_read_b128 v[156:159], v145 offset:59936
	s_waitcnt lgkmcnt(1)
	v_mfma_f32_32x32x16_bf16 v[48:63], v[148:151], v[152:155], v[48:63]
	s_waitcnt lgkmcnt(0)
	v_mfma_f32_32x32x16_bf16 v[32:47], v[148:151], v[156:159], v[32:47]
	ds_read_b128 v[148:151], v144 offset:23072
	s_waitcnt lgkmcnt(0)
	v_mfma_f32_32x32x16_bf16 v[16:31], v[148:151], v[152:155], v[16:31]
	v_mfma_f32_32x32x16_bf16 v[0:15], v[148:151], v[156:159], v[0:15]
	s_add_u32 s98, s98, 0x100
	s_addc_u32 s99, s99, 0
	s_add_i32 s0, s0, 2
	s_cmp_lt_u32 s0, 3
	s_waitcnt vmcnt(15)
	ds_write_b128 v146, v[96:99]
	ds_read_b128 v[148:151], v144 offset:18496
	ds_read_b128 v[152:155], v145 offset:55360
	ds_read_b128 v[156:159], v145 offset:59968
	s_waitcnt lgkmcnt(1)
	v_mfma_f32_32x32x16_bf16 v[48:63], v[148:151], v[152:155], v[48:63]
	s_waitcnt vmcnt(14)
	ds_write_b128 v146, v[100:103] offset:4608
	s_waitcnt lgkmcnt(1)
	v_mfma_f32_32x32x16_bf16 v[32:47], v[148:151], v[156:159], v[32:47]
	s_waitcnt vmcnt(13)
	ds_write_b128 v146, v[104:107] offset:9216
	ds_read_b128 v[148:151], v144 offset:23104
	s_waitcnt lgkmcnt(0)
	v_mfma_f32_32x32x16_bf16 v[16:31], v[148:151], v[152:155], v[16:31]
	s_waitcnt vmcnt(12)
	ds_write_b128 v146, v[108:111] offset:13824
	v_mfma_f32_32x32x16_bf16 v[0:15], v[148:151], v[156:159], v[0:15]
	s_waitcnt vmcnt(11)
	ds_write_b128 v146, v[112:115] offset:36864
	ds_read_b128 v[148:151], v144 offset:18528
	ds_read_b128 v[152:155], v145 offset:55392
	ds_read_b128 v[156:159], v145 offset:60000
	s_waitcnt lgkmcnt(1)
	v_mfma_f32_32x32x16_bf16 v[48:63], v[148:151], v[152:155], v[48:63]
	s_waitcnt vmcnt(10)
	ds_write_b128 v146, v[116:119] offset:41472
	s_waitcnt lgkmcnt(1)
	v_mfma_f32_32x32x16_bf16 v[32:47], v[148:151], v[156:159], v[32:47]
	s_waitcnt vmcnt(9)
	ds_write_b128 v146, v[120:123] offset:46080
	ds_read_b128 v[148:151], v144 offset:23136
	s_waitcnt lgkmcnt(0)
	v_mfma_f32_32x32x16_bf16 v[16:31], v[148:151], v[152:155], v[16:31]
	s_waitcnt vmcnt(8)
	ds_write_b128 v146, v[124:127] offset:50688
	v_mfma_f32_32x32x16_bf16 v[0:15], v[148:151], v[156:159], v[0:15]
	s_setprio 0
	s_waitcnt lgkmcnt(0)
	s_barrier
	s_cbranch_scc1 .LBB0_1745
	s_setprio 1
	ds_read_b128 v[96:99], v144
	ds_read_b128 v[100:103], v145 offset:36864
	ds_read_b128 v[104:107], v145 offset:41472
	s_waitcnt lgkmcnt(1)
	v_mfma_f32_32x32x16_bf16 v[48:63], v[96:99], v[100:103], v[48:63]
	s_waitcnt lgkmcnt(0)
	v_mfma_f32_32x32x16_bf16 v[32:47], v[96:99], v[104:107], v[32:47]
	ds_read_b128 v[96:99], v144 offset:4608
	s_waitcnt lgkmcnt(0)
	v_mfma_f32_32x32x16_bf16 v[16:31], v[96:99], v[100:103], v[16:31]
	v_mfma_f32_32x32x16_bf16 v[0:15], v[96:99], v[104:107], v[0:15]
	ds_read_b128 v[96:99], v144 offset:32
	ds_read_b128 v[100:103], v145 offset:36896
	ds_read_b128 v[104:107], v145 offset:41504
	s_waitcnt lgkmcnt(1)
	v_mfma_f32_32x32x16_bf16 v[48:63], v[96:99], v[100:103], v[48:63]
	s_waitcnt lgkmcnt(0)
	v_mfma_f32_32x32x16_bf16 v[32:47], v[96:99], v[104:107], v[32:47]
	ds_read_b128 v[96:99], v144 offset:4640
	s_waitcnt lgkmcnt(0)
	v_mfma_f32_32x32x16_bf16 v[16:31], v[96:99], v[100:103], v[16:31]
	v_mfma_f32_32x32x16_bf16 v[0:15], v[96:99], v[104:107], v[0:15]
	s_waitcnt vmcnt(7)
	ds_write_b128 v146, v[64:67] offset:18432
	ds_read_b128 v[96:99], v144 offset:64
	ds_read_b128 v[100:103], v145 offset:36928
	ds_read_b128 v[104:107], v145 offset:41536
	s_waitcnt lgkmcnt(1)
	v_mfma_f32_32x32x16_bf16 v[48:63], v[96:99], v[100:103], v[48:63]
	s_waitcnt vmcnt(6)
	ds_write_b128 v146, v[68:71] offset:23040
	s_waitcnt lgkmcnt(1)
	v_mfma_f32_32x32x16_bf16 v[32:47], v[96:99], v[104:107], v[32:47]
	s_waitcnt vmcnt(5)
	ds_write_b128 v146, v[72:75] offset:27648
	ds_read_b128 v[96:99], v144 offset:4672
	s_waitcnt lgkmcnt(0)
	v_mfma_f32_32x32x16_bf16 v[16:31], v[96:99], v[100:103], v[16:31]
	s_waitcnt vmcnt(4)
	ds_write_b128 v146, v[76:79] offset:32256
	v_mfma_f32_32x32x16_bf16 v[0:15], v[96:99], v[104:107], v[0:15]
	s_waitcnt vmcnt(3)
	ds_write_b128 v146, v[80:83] offset:55296
	ds_read_b128 v[96:99], v144 offset:96
	ds_read_b128 v[100:103], v145 offset:36960
	ds_read_b128 v[104:107], v145 offset:41568
	s_waitcnt lgkmcnt(1)
	v_mfma_f32_32x32x16_bf16 v[48:63], v[96:99], v[100:103], v[48:63]
	s_waitcnt vmcnt(2)
	ds_write_b128 v146, v[84:87] offset:59904
	s_waitcnt lgkmcnt(1)
	v_mfma_f32_32x32x16_bf16 v[32:47], v[96:99], v[104:107], v[32:47]
	s_waitcnt vmcnt(1)
	ds_write_b128 v146, v[88:91] offset:64512
	ds_read_b128 v[96:99], v144 offset:4704
	s_waitcnt lgkmcnt(0)
	v_mfma_f32_32x32x16_bf16 v[16:31], v[96:99], v[100:103], v[16:31]
	s_waitcnt vmcnt(0)
	ds_write_b128 v147, v[92:95] offset:13824
	v_mfma_f32_32x32x16_bf16 v[0:15], v[96:99], v[104:107], v[0:15]
	s_setprio 0
	s_waitcnt lgkmcnt(0)
	s_barrier
	s_setprio 1
	ds_read_b128 v[64:67], v144 offset:18432
	ds_read_b128 v[68:71], v145 offset:55296
	ds_read_b128 v[72:75], v145 offset:59904
	s_waitcnt lgkmcnt(1)
	v_mfma_f32_32x32x16_bf16 v[48:63], v[64:67], v[68:71], v[48:63]
	s_waitcnt lgkmcnt(0)
	v_mfma_f32_32x32x16_bf16 v[32:47], v[64:67], v[72:75], v[32:47]
	ds_read_b128 v[64:67], v144 offset:23040
	s_waitcnt lgkmcnt(0)
	v_mfma_f32_32x32x16_bf16 v[16:31], v[64:67], v[68:71], v[16:31]
	v_mfma_f32_32x32x16_bf16 v[0:15], v[64:67], v[72:75], v[0:15]
	ds_read_b128 v[64:67], v144 offset:18464
	ds_read_b128 v[68:71], v145 offset:55328
	ds_read_b128 v[72:75], v145 offset:59936
	s_waitcnt lgkmcnt(1)
	v_mfma_f32_32x32x16_bf16 v[48:63], v[64:67], v[68:71], v[48:63]
	s_waitcnt lgkmcnt(0)
	v_mfma_f32_32x32x16_bf16 v[32:47], v[64:67], v[72:75], v[32:47]
	ds_read_b128 v[64:67], v144 offset:23072
	s_waitcnt lgkmcnt(0)
	v_mfma_f32_32x32x16_bf16 v[16:31], v[64:67], v[68:71], v[16:31]
	v_mfma_f32_32x32x16_bf16 v[0:15], v[64:67], v[72:75], v[0:15]
	ds_read_b128 v[64:67], v144 offset:18496
	ds_read_b128 v[68:71], v145 offset:55360
	ds_read_b128 v[72:75], v145 offset:59968
	s_waitcnt lgkmcnt(1)
	v_mfma_f32_32x32x16_bf16 v[48:63], v[64:67], v[68:71], v[48:63]
	s_waitcnt lgkmcnt(0)
	v_mfma_f32_32x32x16_bf16 v[32:47], v[64:67], v[72:75], v[32:47]
	ds_read_b128 v[64:67], v144 offset:23104
	s_waitcnt lgkmcnt(0)
	v_mfma_f32_32x32x16_bf16 v[16:31], v[64:67], v[68:71], v[16:31]
	v_mfma_f32_32x32x16_bf16 v[0:15], v[64:67], v[72:75], v[0:15]
	ds_read_b128 v[64:67], v144 offset:18528
	ds_read_b128 v[68:71], v145 offset:55392
	ds_read_b128 v[72:75], v145 offset:60000
	s_waitcnt lgkmcnt(1)
	v_mfma_f32_32x32x16_bf16 v[48:63], v[64:67], v[68:71], v[48:63]
	s_waitcnt lgkmcnt(0)
	v_mfma_f32_32x32x16_bf16 v[32:47], v[64:67], v[72:75], v[32:47]
	ds_read_b128 v[64:67], v144 offset:23136
	s_waitcnt lgkmcnt(0)
	v_mfma_f32_32x32x16_bf16 v[16:31], v[64:67], v[68:71], v[16:31]
	v_mfma_f32_32x32x16_bf16 v[0:15], v[64:67], v[72:75], v[0:15]
	s_setprio 0
	s_nop 6
	v_cvt_pk_bf16_f32 v32, v32, s0
	s_nop 2
	v_cvt_pk_bf16_f32 v0, v0, s0
	s_barrier
	ds_write_b16 v143, v32 offset:64
	v_cvt_pk_bf16_f32 v32, v49, s0
	ds_write_b16 v143, v0 offset:8768
	v_cvt_pk_bf16_f32 v0, v17, s0
	ds_write_b16 v143, v32 offset:272
	v_cvt_pk_bf16_f32 v32, v33, s0
	ds_write_b16 v143, v0 offset:8976
	v_cvt_pk_bf16_f32 v0, v1, s0
	ds_write_b16 v143, v32 offset:336
	v_cvt_pk_bf16_f32 v32, v50, s0
	ds_write_b16 v143, v0 offset:9040
	v_cvt_pk_bf16_f32 v0, v18, s0
	ds_write_b16 v143, v32 offset:544
	v_cvt_pk_bf16_f32 v32, v34, s0
	ds_write_b16 v143, v0 offset:9248
	v_cvt_pk_bf16_f32 v0, v2, s0
	ds_write_b16 v143, v32 offset:608
	v_cvt_pk_bf16_f32 v32, v51, s0
	ds_write_b16 v143, v0 offset:9312
	v_cvt_pk_bf16_f32 v0, v19, s0
	ds_write_b16 v143, v32 offset:816
	v_cvt_pk_bf16_f32 v32, v35, s0
	ds_write_b16 v143, v0 offset:9520
	v_cvt_pk_bf16_f32 v0, v3, s0
	ds_write_b16 v143, v32 offset:880
	v_cvt_pk_bf16_f32 v32, v52, s0
	ds_write_b16 v143, v0 offset:9584
	v_cvt_pk_bf16_f32 v0, v20, s0
	ds_write_b16 v143, v32 offset:2176
	v_cvt_pk_bf16_f32 v32, v36, s0
	ds_write_b16 v143, v0 offset:10880
	v_cvt_pk_bf16_f32 v0, v4, s0
	ds_write_b16 v143, v32 offset:2240
	v_cvt_pk_bf16_f32 v32, v53, s0
	ds_write_b16 v143, v0 offset:10944
	v_cvt_pk_bf16_f32 v0, v21, s0
	ds_write_b16 v143, v32 offset:2448
	v_cvt_pk_bf16_f32 v32, v37, s0
	ds_write_b16 v143, v0 offset:11152
	v_cvt_pk_bf16_f32 v0, v5, s0
	ds_write_b16 v143, v32 offset:2512
	v_cvt_pk_bf16_f32 v32, v54, s0
	ds_write_b16 v143, v0 offset:11216
	v_cvt_pk_bf16_f32 v0, v22, s0
	ds_write_b16 v143, v32 offset:2720
	v_cvt_pk_bf16_f32 v32, v38, s0
	ds_write_b16 v143, v0 offset:11424
	v_cvt_pk_bf16_f32 v0, v6, s0
	ds_write_b16 v143, v32 offset:2784
	v_cvt_pk_bf16_f32 v32, v55, s0
	ds_write_b16 v143, v0 offset:11488
	v_cvt_pk_bf16_f32 v0, v23, s0
	ds_write_b16 v143, v32 offset:2992
	v_cvt_pk_bf16_f32 v32, v39, s0
	ds_write_b16 v143, v0 offset:11696
	v_cvt_pk_bf16_f32 v0, v7, s0
	ds_write_b16 v143, v32 offset:3056
	v_cvt_pk_bf16_f32 v32, v56, s0
	ds_write_b16 v143, v0 offset:11760
	v_cvt_pk_bf16_f32 v0, v24, s0
	ds_write_b16 v143, v32 offset:4352
	v_cvt_pk_bf16_f32 v32, v40, s0
	ds_write_b16 v143, v0 offset:13056
	v_cvt_pk_bf16_f32 v0, v8, s0
	ds_write_b16 v143, v32 offset:4416
	v_cvt_pk_bf16_f32 v32, v57, s0
	ds_write_b16 v143, v0 offset:13120
	v_cvt_pk_bf16_f32 v0, v25, s0
	ds_write_b16 v143, v32 offset:4624
	v_cvt_pk_bf16_f32 v32, v41, s0
	ds_write_b16 v143, v0 offset:13328
	v_cvt_pk_bf16_f32 v0, v9, s0
	ds_write_b16 v143, v32 offset:4688
	v_cvt_pk_bf16_f32 v32, v58, s0
	ds_write_b16 v143, v0 offset:13392
	v_cvt_pk_bf16_f32 v0, v26, s0
	ds_write_b16 v143, v32 offset:4896
	v_cvt_pk_bf16_f32 v32, v42, s0
	ds_write_b16 v143, v0 offset:13600
	v_cvt_pk_bf16_f32 v0, v10, s0
	ds_write_b16 v143, v32 offset:4960
	v_cvt_pk_bf16_f32 v32, v59, s0
	ds_write_b16 v143, v0 offset:13664
	v_cvt_pk_bf16_f32 v0, v27, s0
	ds_write_b16 v143, v32 offset:5168
	v_cvt_pk_bf16_f32 v32, v43, s0
	ds_write_b16 v143, v0 offset:13872
	v_cvt_pk_bf16_f32 v0, v11, s0
	ds_write_b16 v143, v32 offset:5232
	v_cvt_pk_bf16_f32 v32, v60, s0
	ds_write_b16 v143, v0 offset:13936
	v_cvt_pk_bf16_f32 v0, v28, s0
	ds_write_b16 v143, v32 offset:6528
	v_cvt_pk_bf16_f32 v32, v44, s0
	ds_write_b16 v143, v0 offset:15232
	v_cvt_pk_bf16_f32 v0, v12, s0
	ds_write_b16 v143, v32 offset:6592
	v_cvt_pk_bf16_f32 v32, v61, s0
	ds_write_b16 v143, v0 offset:15296
	v_cvt_pk_bf16_f32 v0, v29, s0
	ds_write_b16 v143, v32 offset:6800
	v_cvt_pk_bf16_f32 v32, v45, s0
	ds_write_b16 v143, v0 offset:15504
	v_cvt_pk_bf16_f32 v0, v13, s0
	ds_write_b16 v143, v32 offset:6864
	v_cvt_pk_bf16_f32 v32, v62, s0
	ds_write_b16 v143, v0 offset:15568
	v_cvt_pk_bf16_f32 v0, v30, s0
	ds_write_b16 v143, v32 offset:7072
	v_cvt_pk_bf16_f32 v32, v46, s0
	ds_write_b16 v143, v0 offset:15776
	v_cvt_pk_bf16_f32 v0, v14, s0
	ds_write_b16 v143, v32 offset:7136
	v_cvt_pk_bf16_f32 v32, v63, s0
	ds_write_b16 v143, v0 offset:15840
	v_cvt_pk_bf16_f32 v0, v31, s0
	v_cvt_pk_bf16_f32 v48, v48, s0
	ds_write_b16 v143, v32 offset:7344
	v_cvt_pk_bf16_f32 v32, v47, s0
	v_cvt_pk_bf16_f32 v16, v16, s0
	ds_write_b16 v143, v0 offset:16048
	v_cvt_pk_bf16_f32 v0, v15, s0
	v_mov_b32_e32 v15, v142
	ds_write_b16 v143, v48
	ds_write_b16 v143, v32 offset:7408
	ds_write_b16 v143, v16 offset:8704
	ds_write_b16 v143, v0 offset:16112
	s_waitcnt lgkmcnt(0)
	s_barrier
	v_mov_b64_e32 v[2:3], s[4:5]
	v_lshlrev_b32_e32 v0, 3, v15
	v_and_b32_e32 v0, 0x78, v0
	v_ashrrev_i32_e32 v1, 4, v15
	v_lshlrev_b32_e32 v128, 1, v0
	v_add_u32_e32 v0, s69, v1
	s_lshl_b32 s16, s26, 10
	v_mad_i64_i32 v[2:3], s[0:1], v0, s66, v[2:3]
	v_lshl_add_u64 v[2:3], s[16:17], 1, v[2:3]
	v_lshl_add_u64 v[2:3], s[22:23], 1, v[2:3]
	v_lshl_add_u64 v[2:3], v[2:3], 0, v[128:129]
	global_load_dwordx4 v[6:9], v[2:3], off
	v_add_co_u32_e32 v80, vcc, 0x18000, v2
	s_nop 1
	v_addc_co_u32_e32 v81, vcc, 0, v3, vcc
	global_load_dwordx4 v[24:27], v[80:81], off
	v_add_co_u32_e32 v80, vcc, 0x30000, v2
	s_nop 1
	v_addc_co_u32_e32 v81, vcc, 0, v3, vcc
	global_load_dwordx4 v[28:31], v[80:81], off
	v_add_co_u32_e32 v80, vcc, 0x48000, v2
	s_nop 1
	v_addc_co_u32_e32 v81, vcc, 0, v3, vcc
	global_load_dwordx4 v[32:35], v[80:81], off
	v_add_co_u32_e32 v80, vcc, 0x60000, v2
	s_nop 1
	v_addc_co_u32_e32 v81, vcc, 0, v3, vcc
	global_load_dwordx4 v[36:39], v[80:81], off
	v_add_co_u32_e32 v80, vcc, 0x78000, v2
	s_nop 1
	v_addc_co_u32_e32 v81, vcc, 0, v3, vcc
	global_load_dwordx4 v[40:43], v[80:81], off
	v_add_co_u32_e32 v80, vcc, 0x90000, v2
	s_nop 1
	v_addc_co_u32_e32 v81, vcc, 0, v3, vcc
	global_load_dwordx4 v[44:47], v[80:81], off
	v_add_co_u32_e32 v80, vcc, 0xa8000, v2
	s_nop 1
	v_addc_co_u32_e32 v81, vcc, 0, v3, vcc
	global_load_dwordx4 v[48:51], v[80:81], off
	v_add_u32_e32 v14, 32, v128
	v_mad_u64_u32 v[2:3], s[0:1], v1, s60, v[14:15]
	ds_read_b128 v[2:5], v2
	v_ashrrev_i32_e32 v1, 31, v0
	v_lshlrev_b64 v[0:1], 11, v[0:1]
	v_lshl_add_u64 v[0:1], s[24:25], 0, v[0:1]
	v_lshl_add_u64 v[16:17], v[0:1], 0, v[128:129]
	v_cndmask_b32_e64 v1, 0, 1, s[50:51]
	v_mov_b32_e32 v0, 0
	v_cmp_ne_u32_e64 s[0:1], 1, v1
	s_andn2_b64 vcc, exec, s[50:51]
	v_mov_b32_e32 v10, 0
	v_mov_b32_e32 v11, 0
	v_mov_b32_e32 v12, 0
	v_mov_b32_e32 v13, 0
	s_cbranch_vccnz .LBB0_1748
	global_load_dwordx4 v[10:13], v[16:17], off
	v_add_co_u32_e32 v80, vcc, 0x8000, v16
	s_nop 1
	v_addc_co_u32_e32 v81, vcc, 0, v17, vcc
	global_load_dwordx4 v[52:55], v[80:81], off
	v_add_co_u32_e32 v80, vcc, 0x10000, v16
	s_nop 1
	v_addc_co_u32_e32 v81, vcc, 0, v17, vcc
	global_load_dwordx4 v[56:59], v[80:81], off
	v_add_co_u32_e32 v80, vcc, 0x18000, v16
	s_nop 1
	v_addc_co_u32_e32 v81, vcc, 0, v17, vcc
	global_load_dwordx4 v[60:63], v[80:81], off
	v_add_co_u32_e32 v80, vcc, 0x20000, v16
	s_nop 1
	v_addc_co_u32_e32 v81, vcc, 0, v17, vcc
	global_load_dwordx4 v[64:67], v[80:81], off
	v_add_co_u32_e32 v80, vcc, 0x28000, v16
	s_nop 1
	v_addc_co_u32_e32 v81, vcc, 0, v17, vcc
	global_load_dwordx4 v[68:71], v[80:81], off
	v_add_co_u32_e32 v80, vcc, 0x30000, v16
	s_nop 1
	v_addc_co_u32_e32 v81, vcc, 0, v17, vcc
	global_load_dwordx4 v[72:75], v[80:81], off
	v_add_co_u32_e32 v80, vcc, 0x38000, v16
	s_nop 1
	v_addc_co_u32_e32 v81, vcc, 0, v17, vcc
	global_load_dwordx4 v[76:79], v[80:81], off
.LBB0_1748:
	s_waitcnt vmcnt(0)
	v_lshlrev_b32_e32 v18, 16, v6
	v_and_b32_e32 v19, 0xffff0000, v6
	s_waitcnt lgkmcnt(0)
	v_lshlrev_b32_e32 v20, 16, v2
	v_and_b32_e32 v21, 0xffff0000, v2
	v_lshlrev_b32_e32 v22, 16, v10
	v_and_b32_e32 v23, 0xffff0000, v10
	v_pk_fma_f32 v[18:19], v[18:19], v[20:21], v[22:23]
	v_lshlrev_b32_e32 v6, 16, v7
	v_cvt_pk_bf16_f32 v2, v18, v19
	v_and_b32_e32 v7, 0xffff0000, v7
	v_lshlrev_b32_e32 v18, 16, v3
	v_and_b32_e32 v19, 0xffff0000, v3
	v_lshlrev_b32_e32 v10, 16, v11
	v_and_b32_e32 v11, 0xffff0000, v11
	v_pk_fma_f32 v[6:7], v[6:7], v[18:19], v[10:11]
	v_lshlrev_b32_e32 v10, 16, v4
	v_cvt_pk_bf16_f32 v3, v6, v7
	v_lshlrev_b32_e32 v6, 16, v8
	v_and_b32_e32 v7, 0xffff0000, v8
	v_and_b32_e32 v11, 0xffff0000, v4
	v_lshlrev_b32_e32 v18, 16, v12
	v_and_b32_e32 v19, 0xffff0000, v12
	v_pk_fma_f32 v[6:7], v[6:7], v[10:11], v[18:19]
	v_lshlrev_b32_e32 v8, 16, v5
	v_cvt_pk_bf16_f32 v4, v6, v7
	v_lshlrev_b32_e32 v6, 16, v9
	v_and_b32_e32 v7, 0xffff0000, v9
	v_and_b32_e32 v9, 0xffff0000, v5
	v_lshlrev_b32_e32 v10, 16, v13
	v_and_b32_e32 v11, 0xffff0000, v13
	v_pk_fma_f32 v[6:7], v[6:7], v[8:9], v[10:11]
	v_add_u32_e32 v1, 0x100, v15
	v_cvt_pk_bf16_f32 v5, v6, v7
	v_ashrrev_i32_e32 v1, 4, v1
	global_store_dwordx4 v[16:17], v[2:5], off
	s_and_b64 vcc, exec, s[0:1]
	s_nop 0
	v_add_u32_e32 v2, s69, v1
	v_mov_b64_e32 v[4:5], s[4:5]
	v_mad_i64_i32 v[4:5], s[50:51], v2, s66, v[4:5]
	v_lshl_add_u64 v[4:5], s[16:17], 1, v[4:5]
	v_lshl_add_u64 v[4:5], s[22:23], 1, v[4:5]
	v_lshl_add_u64 v[4:5], v[4:5], 0, v[128:129]
	v_mov_b64_e32 v[8:9], v[24:25]
	v_mov_b64_e32 v[10:11], v[26:27]
	v_mad_u64_u32 v[4:5], s[50:51], v1, s60, v[14:15]
	ds_read_b128 v[4:7], v4
	v_ashrrev_i32_e32 v3, 31, v2
	v_lshlrev_b64 v[2:3], 11, v[2:3]
	v_lshl_add_u64 v[2:3], s[24:25], 0, v[2:3]
	v_lshl_add_u64 v[12:13], v[2:3], 0, v[128:129]
	v_mov_b32_e32 v1, 0
	v_mov_b32_e32 v2, 0
	v_mov_b32_e32 v3, 0
	s_cbranch_vccnz .LBB0_1750
	v_mov_b64_e32 v[0:1], v[52:53]
	v_mov_b64_e32 v[2:3], v[54:55]
.LBB0_1750:
	s_waitcnt vmcnt(0)
	v_lshlrev_b32_e32 v16, 16, v8
	v_and_b32_e32 v17, 0xffff0000, v8
	s_waitcnt lgkmcnt(0)
	v_lshlrev_b32_e32 v18, 16, v4
	v_and_b32_e32 v19, 0xffff0000, v4
	v_lshlrev_b32_e32 v20, 16, v0
	v_and_b32_e32 v21, 0xffff0000, v0
	v_pk_fma_f32 v[16:17], v[16:17], v[18:19], v[20:21]
	v_lshlrev_b32_e32 v8, 16, v9
	v_cvt_pk_bf16_f32 v0, v16, v17
	v_and_b32_e32 v9, 0xffff0000, v9
	v_lshlrev_b32_e32 v4, 16, v5
	v_and_b32_e32 v5, 0xffff0000, v5
	v_lshlrev_b32_e32 v16, 16, v1
	v_and_b32_e32 v17, 0xffff0000, v1
	v_pk_fma_f32 v[4:5], v[8:9], v[4:5], v[16:17]
	v_lshlrev_b32_e32 v8, 16, v6
	v_cvt_pk_bf16_f32 v1, v4, v5
	v_lshlrev_b32_e32 v4, 16, v10
	v_and_b32_e32 v5, 0xffff0000, v10
	v_and_b32_e32 v9, 0xffff0000, v6
	v_lshlrev_b32_e32 v16, 16, v2
	v_and_b32_e32 v17, 0xffff0000, v2
	v_pk_fma_f32 v[4:5], v[4:5], v[8:9], v[16:17]
	v_lshlrev_b32_e32 v6, 16, v7
	v_cvt_pk_bf16_f32 v2, v4, v5
	v_lshlrev_b32_e32 v4, 16, v11
	v_and_b32_e32 v5, 0xffff0000, v11
	v_and_b32_e32 v7, 0xffff0000, v7
	v_lshlrev_b32_e32 v8, 16, v3
	v_and_b32_e32 v9, 0xffff0000, v3
	v_pk_fma_f32 v[4:5], v[4:5], v[6:7], v[8:9]
	s_and_b64 vcc, exec, s[0:1]
	v_cvt_pk_bf16_f32 v3, v4, v5
	global_store_dwordx4 v[12:13], v[0:3], off
	v_mov_b32_e32 v10, 0
	v_mov_b32_e32 v11, 0
	v_add_u32_e32 v0, 0x200, v15
	v_ashrrev_i32_e32 v1, 4, v0
	v_add_u32_e32 v0, s69, v1
	v_mov_b64_e32 v[2:3], s[4:5]
	v_mad_i64_i32 v[2:3], s[50:51], v0, s66, v[2:3]
	v_lshl_add_u64 v[2:3], s[16:17], 1, v[2:3]
	v_lshl_add_u64 v[2:3], s[22:23], 1, v[2:3]
	v_lshl_add_u64 v[2:3], v[2:3], 0, v[128:129]
	v_mov_b64_e32 v[6:7], v[28:29]
	v_mov_b64_e32 v[8:9], v[30:31]
	v_mad_u64_u32 v[2:3], s[50:51], v1, s60, v[14:15]
	ds_read_b128 v[2:5], v2
	v_ashrrev_i32_e32 v1, 31, v0
	v_lshlrev_b64 v[0:1], 11, v[0:1]
	v_lshl_add_u64 v[0:1], s[24:25], 0, v[0:1]
	v_lshl_add_u64 v[16:17], v[0:1], 0, v[128:129]
	v_mov_b32_e32 v0, 0
	v_mov_b32_e32 v12, 0
	v_mov_b32_e32 v13, 0
	s_cbranch_vccnz .LBB0_1752
	v_mov_b64_e32 v[10:11], v[56:57]
	v_mov_b64_e32 v[12:13], v[58:59]
.LBB0_1752:
	s_waitcnt vmcnt(0)
	v_lshlrev_b32_e32 v18, 16, v6
	v_and_b32_e32 v19, 0xffff0000, v6
	s_waitcnt lgkmcnt(0)
	v_lshlrev_b32_e32 v20, 16, v2
	v_and_b32_e32 v21, 0xffff0000, v2
	v_lshlrev_b32_e32 v22, 16, v10
	v_and_b32_e32 v23, 0xffff0000, v10
	v_pk_fma_f32 v[18:19], v[18:19], v[20:21], v[22:23]
	v_lshlrev_b32_e32 v6, 16, v7
	v_cvt_pk_bf16_f32 v2, v18, v19
	v_and_b32_e32 v7, 0xffff0000, v7
	v_lshlrev_b32_e32 v18, 16, v3
	v_and_b32_e32 v19, 0xffff0000, v3
	v_lshlrev_b32_e32 v10, 16, v11
	v_and_b32_e32 v11, 0xffff0000, v11
	v_pk_fma_f32 v[6:7], v[6:7], v[18:19], v[10:11]
	v_lshlrev_b32_e32 v10, 16, v4
	v_cvt_pk_bf16_f32 v3, v6, v7
	v_lshlrev_b32_e32 v6, 16, v8
	v_and_b32_e32 v7, 0xffff0000, v8
	v_and_b32_e32 v11, 0xffff0000, v4
	v_lshlrev_b32_e32 v18, 16, v12
	v_and_b32_e32 v19, 0xffff0000, v12
	v_pk_fma_f32 v[6:7], v[6:7], v[10:11], v[18:19]
	v_lshlrev_b32_e32 v8, 16, v5
	v_cvt_pk_bf16_f32 v4, v6, v7
	v_lshlrev_b32_e32 v6, 16, v9
	v_and_b32_e32 v7, 0xffff0000, v9
	v_and_b32_e32 v9, 0xffff0000, v5
	v_lshlrev_b32_e32 v10, 16, v13
	v_and_b32_e32 v11, 0xffff0000, v13
	v_pk_fma_f32 v[6:7], v[6:7], v[8:9], v[10:11]
	v_add_u32_e32 v1, 0x300, v15
	v_cvt_pk_bf16_f32 v5, v6, v7
	v_ashrrev_i32_e32 v1, 4, v1
	global_store_dwordx4 v[16:17], v[2:5], off
	s_and_b64 vcc, exec, s[0:1]
	s_nop 0
	v_add_u32_e32 v2, s69, v1
	v_mov_b64_e32 v[4:5], s[4:5]
	v_mad_i64_i32 v[4:5], s[50:51], v2, s66, v[4:5]
	v_lshl_add_u64 v[4:5], s[16:17], 1, v[4:5]
	v_lshl_add_u64 v[4:5], s[22:23], 1, v[4:5]
	v_lshl_add_u64 v[4:5], v[4:5], 0, v[128:129]
	v_mov_b64_e32 v[8:9], v[32:33]
	v_mov_b64_e32 v[10:11], v[34:35]
	v_mad_u64_u32 v[4:5], s[50:51], v1, s60, v[14:15]
	ds_read_b128 v[4:7], v4
	v_ashrrev_i32_e32 v3, 31, v2
	v_lshlrev_b64 v[2:3], 11, v[2:3]
	v_lshl_add_u64 v[2:3], s[24:25], 0, v[2:3]
	v_lshl_add_u64 v[12:13], v[2:3], 0, v[128:129]
	v_mov_b32_e32 v1, 0
	v_mov_b32_e32 v2, 0
	v_mov_b32_e32 v3, 0
	s_cbranch_vccnz .LBB0_1754
	v_mov_b64_e32 v[0:1], v[60:61]
	v_mov_b64_e32 v[2:3], v[62:63]
.LBB0_1754:
	s_waitcnt vmcnt(0)
	v_lshlrev_b32_e32 v16, 16, v8
	v_and_b32_e32 v17, 0xffff0000, v8
	s_waitcnt lgkmcnt(0)
	v_lshlrev_b32_e32 v18, 16, v4
	v_and_b32_e32 v19, 0xffff0000, v4
	v_lshlrev_b32_e32 v20, 16, v0
	v_and_b32_e32 v21, 0xffff0000, v0
	v_pk_fma_f32 v[16:17], v[16:17], v[18:19], v[20:21]
	v_lshlrev_b32_e32 v8, 16, v9
	v_cvt_pk_bf16_f32 v0, v16, v17
	v_and_b32_e32 v9, 0xffff0000, v9
	v_lshlrev_b32_e32 v4, 16, v5
	v_and_b32_e32 v5, 0xffff0000, v5
	v_lshlrev_b32_e32 v16, 16, v1
	v_and_b32_e32 v17, 0xffff0000, v1
	v_pk_fma_f32 v[4:5], v[8:9], v[4:5], v[16:17]
	v_lshlrev_b32_e32 v8, 16, v6
	v_cvt_pk_bf16_f32 v1, v4, v5
	v_lshlrev_b32_e32 v4, 16, v10
	v_and_b32_e32 v5, 0xffff0000, v10
	v_and_b32_e32 v9, 0xffff0000, v6
	v_lshlrev_b32_e32 v16, 16, v2
	v_and_b32_e32 v17, 0xffff0000, v2
	v_pk_fma_f32 v[4:5], v[4:5], v[8:9], v[16:17]
	v_lshlrev_b32_e32 v6, 16, v7
	v_cvt_pk_bf16_f32 v2, v4, v5
	v_lshlrev_b32_e32 v4, 16, v11
	v_and_b32_e32 v5, 0xffff0000, v11
	v_and_b32_e32 v7, 0xffff0000, v7
	v_lshlrev_b32_e32 v8, 16, v3
	v_and_b32_e32 v9, 0xffff0000, v3
	v_pk_fma_f32 v[4:5], v[4:5], v[6:7], v[8:9]
	s_and_b64 vcc, exec, s[0:1]
	v_cvt_pk_bf16_f32 v3, v4, v5
	global_store_dwordx4 v[12:13], v[0:3], off
	v_mov_b32_e32 v10, 0
	v_mov_b32_e32 v11, 0
	v_add_u32_e32 v0, 0x400, v15
	v_ashrrev_i32_e32 v1, 4, v0
	v_add_u32_e32 v0, s69, v1
	v_mov_b64_e32 v[2:3], s[4:5]
	v_mad_i64_i32 v[2:3], s[50:51], v0, s66, v[2:3]
	v_lshl_add_u64 v[2:3], s[16:17], 1, v[2:3]
	v_lshl_add_u64 v[2:3], s[22:23], 1, v[2:3]
	v_lshl_add_u64 v[2:3], v[2:3], 0, v[128:129]
	v_mov_b64_e32 v[6:7], v[36:37]
	v_mov_b64_e32 v[8:9], v[38:39]
	v_mad_u64_u32 v[2:3], s[50:51], v1, s60, v[14:15]
	ds_read_b128 v[2:5], v2
	v_ashrrev_i32_e32 v1, 31, v0
	v_lshlrev_b64 v[0:1], 11, v[0:1]
	v_lshl_add_u64 v[0:1], s[24:25], 0, v[0:1]
	v_lshl_add_u64 v[16:17], v[0:1], 0, v[128:129]
	v_mov_b32_e32 v0, 0
	v_mov_b32_e32 v12, 0
	v_mov_b32_e32 v13, 0
	s_cbranch_vccnz .LBB0_1756
	v_mov_b64_e32 v[10:11], v[64:65]
	v_mov_b64_e32 v[12:13], v[66:67]
.LBB0_1756:
	s_waitcnt vmcnt(0)
	v_lshlrev_b32_e32 v18, 16, v6
	v_and_b32_e32 v19, 0xffff0000, v6
	s_waitcnt lgkmcnt(0)
	v_lshlrev_b32_e32 v20, 16, v2
	v_and_b32_e32 v21, 0xffff0000, v2
	v_lshlrev_b32_e32 v22, 16, v10
	v_and_b32_e32 v23, 0xffff0000, v10
	v_pk_fma_f32 v[18:19], v[18:19], v[20:21], v[22:23]
	v_lshlrev_b32_e32 v6, 16, v7
	v_cvt_pk_bf16_f32 v2, v18, v19
	v_and_b32_e32 v7, 0xffff0000, v7
	v_lshlrev_b32_e32 v18, 16, v3
	v_and_b32_e32 v19, 0xffff0000, v3
	v_lshlrev_b32_e32 v10, 16, v11
	v_and_b32_e32 v11, 0xffff0000, v11
	v_pk_fma_f32 v[6:7], v[6:7], v[18:19], v[10:11]
	v_lshlrev_b32_e32 v10, 16, v4
	v_cvt_pk_bf16_f32 v3, v6, v7
	v_lshlrev_b32_e32 v6, 16, v8
	v_and_b32_e32 v7, 0xffff0000, v8
	v_and_b32_e32 v11, 0xffff0000, v4
	v_lshlrev_b32_e32 v18, 16, v12
	v_and_b32_e32 v19, 0xffff0000, v12
	v_pk_fma_f32 v[6:7], v[6:7], v[10:11], v[18:19]
	v_lshlrev_b32_e32 v8, 16, v5
	v_cvt_pk_bf16_f32 v4, v6, v7
	v_lshlrev_b32_e32 v6, 16, v9
	v_and_b32_e32 v7, 0xffff0000, v9
	v_and_b32_e32 v9, 0xffff0000, v5
	v_lshlrev_b32_e32 v10, 16, v13
	v_and_b32_e32 v11, 0xffff0000, v13
	v_pk_fma_f32 v[6:7], v[6:7], v[8:9], v[10:11]
	v_add_u32_e32 v1, 0x500, v15
	v_cvt_pk_bf16_f32 v5, v6, v7
	v_ashrrev_i32_e32 v1, 4, v1
	global_store_dwordx4 v[16:17], v[2:5], off
	s_and_b64 vcc, exec, s[0:1]
	s_nop 0
	v_add_u32_e32 v2, s69, v1
	v_mov_b64_e32 v[4:5], s[4:5]
	v_mad_i64_i32 v[4:5], s[50:51], v2, s66, v[4:5]
	v_lshl_add_u64 v[4:5], s[16:17], 1, v[4:5]
	v_lshl_add_u64 v[4:5], s[22:23], 1, v[4:5]
	v_lshl_add_u64 v[4:5], v[4:5], 0, v[128:129]
	v_mov_b64_e32 v[8:9], v[40:41]
	v_mov_b64_e32 v[10:11], v[42:43]
	v_mad_u64_u32 v[4:5], s[50:51], v1, s60, v[14:15]
	ds_read_b128 v[4:7], v4
	v_ashrrev_i32_e32 v3, 31, v2
	v_lshlrev_b64 v[2:3], 11, v[2:3]
	v_lshl_add_u64 v[2:3], s[24:25], 0, v[2:3]
	v_lshl_add_u64 v[12:13], v[2:3], 0, v[128:129]
	v_mov_b32_e32 v1, 0
	v_mov_b32_e32 v2, 0
	v_mov_b32_e32 v3, 0
	s_cbranch_vccnz .LBB0_1758
	v_mov_b64_e32 v[0:1], v[68:69]
	v_mov_b64_e32 v[2:3], v[70:71]
.LBB0_1758:
	s_waitcnt vmcnt(0)
	v_lshlrev_b32_e32 v16, 16, v8
	v_and_b32_e32 v17, 0xffff0000, v8
	s_waitcnt lgkmcnt(0)
	v_lshlrev_b32_e32 v18, 16, v4
	v_and_b32_e32 v19, 0xffff0000, v4
	v_lshlrev_b32_e32 v20, 16, v0
	v_and_b32_e32 v21, 0xffff0000, v0
	v_pk_fma_f32 v[16:17], v[16:17], v[18:19], v[20:21]
	v_lshlrev_b32_e32 v8, 16, v9
	v_cvt_pk_bf16_f32 v0, v16, v17
	v_and_b32_e32 v9, 0xffff0000, v9
	v_lshlrev_b32_e32 v4, 16, v5
	v_and_b32_e32 v5, 0xffff0000, v5
	v_lshlrev_b32_e32 v16, 16, v1
	v_and_b32_e32 v17, 0xffff0000, v1
	v_pk_fma_f32 v[4:5], v[8:9], v[4:5], v[16:17]
	v_lshlrev_b32_e32 v8, 16, v6
	v_cvt_pk_bf16_f32 v1, v4, v5
	v_lshlrev_b32_e32 v4, 16, v10
	v_and_b32_e32 v5, 0xffff0000, v10
	v_and_b32_e32 v9, 0xffff0000, v6
	v_lshlrev_b32_e32 v16, 16, v2
	v_and_b32_e32 v17, 0xffff0000, v2
	v_pk_fma_f32 v[4:5], v[4:5], v[8:9], v[16:17]
	v_lshlrev_b32_e32 v6, 16, v7
	v_cvt_pk_bf16_f32 v2, v4, v5
	v_lshlrev_b32_e32 v4, 16, v11
	v_and_b32_e32 v5, 0xffff0000, v11
	v_and_b32_e32 v7, 0xffff0000, v7
	v_lshlrev_b32_e32 v8, 16, v3
	v_and_b32_e32 v9, 0xffff0000, v3
	v_pk_fma_f32 v[4:5], v[4:5], v[6:7], v[8:9]
	s_and_b64 vcc, exec, s[0:1]
	v_cvt_pk_bf16_f32 v3, v4, v5
	global_store_dwordx4 v[12:13], v[0:3], off
	v_mov_b32_e32 v10, 0
	v_mov_b32_e32 v11, 0
	v_add_u32_e32 v0, 0x600, v15
	v_ashrrev_i32_e32 v1, 4, v0
	v_add_u32_e32 v0, s69, v1
	v_mov_b64_e32 v[2:3], s[4:5]
	v_mad_i64_i32 v[2:3], s[50:51], v0, s66, v[2:3]
	v_lshl_add_u64 v[2:3], s[16:17], 1, v[2:3]
	v_lshl_add_u64 v[2:3], s[22:23], 1, v[2:3]
	v_lshl_add_u64 v[2:3], v[2:3], 0, v[128:129]
	v_mov_b64_e32 v[6:7], v[44:45]
	v_mov_b64_e32 v[8:9], v[46:47]
	v_mad_u64_u32 v[2:3], s[50:51], v1, s60, v[14:15]
	ds_read_b128 v[2:5], v2
	v_ashrrev_i32_e32 v1, 31, v0
	v_lshlrev_b64 v[0:1], 11, v[0:1]
	v_lshl_add_u64 v[0:1], s[24:25], 0, v[0:1]
	v_lshl_add_u64 v[16:17], v[0:1], 0, v[128:129]
	v_mov_b32_e32 v0, 0
	v_mov_b32_e32 v12, 0
	v_mov_b32_e32 v13, 0
	s_cbranch_vccnz .LBB0_1760
	v_mov_b64_e32 v[10:11], v[72:73]
	v_mov_b64_e32 v[12:13], v[74:75]
.LBB0_1760:
	s_waitcnt vmcnt(0)
	v_lshlrev_b32_e32 v18, 16, v6
	v_and_b32_e32 v19, 0xffff0000, v6
	s_waitcnt lgkmcnt(0)
	v_lshlrev_b32_e32 v20, 16, v2
	v_and_b32_e32 v21, 0xffff0000, v2
	v_lshlrev_b32_e32 v22, 16, v10
	v_and_b32_e32 v23, 0xffff0000, v10
	v_pk_fma_f32 v[18:19], v[18:19], v[20:21], v[22:23]
	v_lshlrev_b32_e32 v6, 16, v7
	v_cvt_pk_bf16_f32 v2, v18, v19
	v_and_b32_e32 v7, 0xffff0000, v7
	v_lshlrev_b32_e32 v18, 16, v3
	v_and_b32_e32 v19, 0xffff0000, v3
	v_lshlrev_b32_e32 v10, 16, v11
	v_and_b32_e32 v11, 0xffff0000, v11
	v_pk_fma_f32 v[6:7], v[6:7], v[18:19], v[10:11]
	v_lshlrev_b32_e32 v10, 16, v4
	v_cvt_pk_bf16_f32 v3, v6, v7
	v_lshlrev_b32_e32 v6, 16, v8
	v_and_b32_e32 v7, 0xffff0000, v8
	v_and_b32_e32 v11, 0xffff0000, v4
	v_lshlrev_b32_e32 v18, 16, v12
	v_and_b32_e32 v19, 0xffff0000, v12
	v_pk_fma_f32 v[6:7], v[6:7], v[10:11], v[18:19]
	v_lshlrev_b32_e32 v8, 16, v5
	v_cvt_pk_bf16_f32 v4, v6, v7
	v_lshlrev_b32_e32 v6, 16, v9
	v_and_b32_e32 v7, 0xffff0000, v9
	v_and_b32_e32 v9, 0xffff0000, v5
	v_lshlrev_b32_e32 v10, 16, v13
	v_and_b32_e32 v11, 0xffff0000, v13
	v_pk_fma_f32 v[6:7], v[6:7], v[8:9], v[10:11]
	v_add_u32_e32 v1, 0x700, v15
	v_cvt_pk_bf16_f32 v5, v6, v7
	v_ashrrev_i32_e32 v1, 4, v1
	global_store_dwordx4 v[16:17], v[2:5], off
	s_and_b64 vcc, exec, s[0:1]
	s_nop 0
	v_add_u32_e32 v2, s69, v1
	v_mov_b64_e32 v[4:5], s[4:5]
	v_mad_i64_i32 v[4:5], s[50:51], v2, s66, v[4:5]
	v_lshl_add_u64 v[4:5], s[16:17], 1, v[4:5]
	v_lshl_add_u64 v[4:5], s[22:23], 1, v[4:5]
	v_lshl_add_u64 v[4:5], v[4:5], 0, v[128:129]
	v_mov_b64_e32 v[8:9], v[48:49]
	v_mov_b64_e32 v[10:11], v[50:51]
	v_mad_u64_u32 v[4:5], s[50:51], v1, s60, v[14:15]
	ds_read_b128 v[4:7], v4
	v_ashrrev_i32_e32 v3, 31, v2
	v_lshlrev_b64 v[2:3], 11, v[2:3]
	v_lshl_add_u64 v[2:3], s[24:25], 0, v[2:3]
	v_lshl_add_u64 v[12:13], v[2:3], 0, v[128:129]
	v_mov_b32_e32 v1, 0
	v_mov_b32_e32 v2, 0
	v_mov_b32_e32 v3, 0
	s_cbranch_vccnz .LBB0_1743
	v_mov_b64_e32 v[0:1], v[76:77]
	v_mov_b64_e32 v[2:3], v[78:79]
	s_branch .LBB0_1743

.LBB0_1820:
	v_lshl_add_u64 v[18:19], v[0:1], 0, s[18:19]
	s_waitcnt lgkmcnt(0)
	global_load_dwordx4 v[26:29], v[18:19], off
	ds_read_b128 v[30:33], v25
	s_waitcnt vmcnt(0) lgkmcnt(0)
	v_pk_fma_f32 v[30:31], v[26:27], s[16:17], v[30:31] op_sel_hi:[1,0,1]
	v_pk_fma_f32 v[32:33], v[28:29], s[16:17], v[32:33] op_sel_hi:[1,0,1]
	v_pk_mul_f32 v[26:27], v[30:31], v[30:31]
	v_add_f32_e32 v34, v30, v31
	v_pk_mul_f32 v[28:29], v[32:33], v[32:33]
	v_add_f32_e32 v26, v26, v27
	v_add_f32_e32 v34, v32, v34
	v_add_f32_e32 v26, v28, v26
	v_add_f32_e32 v27, v33, v34
	v_add_f32_e32 v26, v29, v26
	ds_bpermute_b32 v28, v20, v27
	ds_bpermute_b32 v29, v20, v26
	v_lshl_add_u64 v[34:35], v[14:15], 0, s[18:19]
	v_add_co_u32_e32 v34, vcc, s56, v34
	s_waitcnt lgkmcnt(1)
	v_add_f32_e32 v27, v27, v28
	s_waitcnt lgkmcnt(0)
	v_add_f32_e32 v26, v26, v29
	ds_bpermute_b32 v28, v21, v27
	ds_bpermute_b32 v29, v21, v26
	v_addc_co_u32_e32 v35, vcc, 0, v35, vcc
	global_store_dwordx4 v[34:35], v[30:33], off offset:3584
	s_waitcnt lgkmcnt(1)
	v_add_f32_e32 v27, v27, v28
	s_waitcnt lgkmcnt(0)
	v_add_f32_e32 v26, v26, v29
	ds_bpermute_b32 v28, v22, v27
	ds_bpermute_b32 v29, v22, v26
	s_waitcnt lgkmcnt(1)
	v_add_f32_e32 v27, v27, v28
	s_waitcnt lgkmcnt(0)
	v_add_f32_e32 v28, v26, v29
	ds_bpermute_b32 v26, v23, v27
	ds_bpermute_b32 v29, v23, v28
	s_waitcnt lgkmcnt(1)
	v_add_f32_e32 v26, v27, v26
	s_waitcnt lgkmcnt(0)
	v_add_f32_e32 v27, v28, v29
	ds_bpermute_b32 v28, v24, v26
	ds_bpermute_b32 v29, v24, v27
	s_and_saveexec_b64 s[22:23], s[0:1]
	s_cbranch_execz .LBB0_1822
	s_waitcnt lgkmcnt(0)
	v_add_f32_e32 v29, v27, v29
	v_add_f32_e32 v28, v26, v28
	v_lshl_add_u64 v[26:27], s[20:21], 0, v[16:17]
	v_add_co_u32_e32 v26, vcc, 0x3c000, v26
	s_nop 1
	v_addc_co_u32_e32 v27, vcc, 0, v27, vcc
	v_mov_b32_e32 v92, v26
	v_mov_b32_e32 v93, v27
	v_and_b32_e32 v90, 0x3ff, v26
	v_add_u32_e32 v90, 68608, v90
	ds_write2_b32 v90, v28, v29 offset1:1
.LBB0_1822:
	s_or_b64 exec, exec, s[22:23]
	v_add_co_u32_e32 v26, vcc, 0x8000, v18
	ds_read_b128 v[30:33], v25 offset:4224
	s_nop 0
	v_addc_co_u32_e32 v27, vcc, 0, v19, vcc
	s_waitcnt lgkmcnt(1)
	global_load_dwordx4 v[26:29], v[26:27], off
	s_waitcnt vmcnt(0) lgkmcnt(0)
	v_pk_fma_f32 v[30:31], v[26:27], s[16:17], v[30:31] op_sel_hi:[1,0,1]
	v_pk_fma_f32 v[32:33], v[28:29], s[16:17], v[32:33] op_sel_hi:[1,0,1]
	v_pk_mul_f32 v[26:27], v[30:31], v[30:31]
	v_add_f32_e32 v34, v30, v31
	v_pk_mul_f32 v[28:29], v[32:33], v[32:33]
	v_add_f32_e32 v26, v26, v27
	v_add_f32_e32 v34, v32, v34
	v_add_f32_e32 v26, v28, v26
	v_add_f32_e32 v27, v33, v34
	v_add_f32_e32 v26, v29, v26
	ds_bpermute_b32 v28, v20, v27
	ds_bpermute_b32 v29, v20, v26
	v_lshl_add_u64 v[34:35], v[12:13], 0, s[18:19]
	v_add_co_u32_e32 v34, vcc, s56, v34
	s_waitcnt lgkmcnt(1)
	v_add_f32_e32 v27, v27, v28
	s_waitcnt lgkmcnt(0)
	v_add_f32_e32 v26, v26, v29
	ds_bpermute_b32 v28, v21, v27
	ds_bpermute_b32 v29, v21, v26
	v_addc_co_u32_e32 v35, vcc, 0, v35, vcc
	global_store_dwordx4 v[34:35], v[30:33], off offset:3584
	s_waitcnt lgkmcnt(1)
	v_add_f32_e32 v27, v27, v28
	s_waitcnt lgkmcnt(0)
	v_add_f32_e32 v26, v26, v29
	ds_bpermute_b32 v28, v22, v27
	ds_bpermute_b32 v29, v22, v26
	s_waitcnt lgkmcnt(1)
	v_add_f32_e32 v27, v27, v28
	s_waitcnt lgkmcnt(0)
	v_add_f32_e32 v28, v26, v29
	ds_bpermute_b32 v26, v23, v27
	ds_bpermute_b32 v29, v23, v28
	s_waitcnt lgkmcnt(1)
	v_add_f32_e32 v26, v27, v26
	s_waitcnt lgkmcnt(0)
	v_add_f32_e32 v27, v28, v29
	ds_bpermute_b32 v28, v24, v26
	ds_bpermute_b32 v29, v24, v27
	s_and_saveexec_b64 s[22:23], s[0:1]
	s_cbranch_execz .LBB0_1824
	s_waitcnt lgkmcnt(0)
	v_add_f32_e32 v29, v27, v29
	v_add_f32_e32 v28, v26, v28
	v_lshl_add_u64 v[26:27], s[20:21], 0, v[10:11]
	v_add_co_u32_e32 v26, vcc, 0x3c000, v26
	s_nop 1
	v_addc_co_u32_e32 v27, vcc, 0, v27, vcc
	v_mov_b32_e32 v92, v26
	v_mov_b32_e32 v93, v27
	v_and_b32_e32 v90, 0x3ff, v26
	v_add_u32_e32 v90, 68608, v90
	ds_write2_b32 v90, v28, v29 offset1:1
.LBB0_1824:
	s_or_b64 exec, exec, s[22:23]
	v_add_co_u32_e32 v26, vcc, 0x10000, v18
	ds_read_b128 v[30:33], v25 offset:8448
	s_nop 0
	v_addc_co_u32_e32 v27, vcc, 0, v19, vcc
	s_waitcnt lgkmcnt(1)
	global_load_dwordx4 v[26:29], v[26:27], off
	s_waitcnt vmcnt(0) lgkmcnt(0)
	v_pk_fma_f32 v[30:31], v[26:27], s[16:17], v[30:31] op_sel_hi:[1,0,1]
	v_pk_fma_f32 v[32:33], v[28:29], s[16:17], v[32:33] op_sel_hi:[1,0,1]
	v_pk_mul_f32 v[26:27], v[30:31], v[30:31]
	v_add_f32_e32 v34, v30, v31
	v_pk_mul_f32 v[28:29], v[32:33], v[32:33]
	v_add_f32_e32 v26, v26, v27
	v_add_f32_e32 v34, v32, v34
	v_add_f32_e32 v26, v28, v26
	v_add_f32_e32 v27, v33, v34
	v_add_f32_e32 v26, v29, v26
	ds_bpermute_b32 v28, v20, v27
	ds_bpermute_b32 v29, v20, v26
	v_lshl_add_u64 v[34:35], v[8:9], 0, s[18:19]
	v_add_co_u32_e32 v34, vcc, s56, v34
	s_waitcnt lgkmcnt(1)
	v_add_f32_e32 v27, v27, v28
	s_waitcnt lgkmcnt(0)
	v_add_f32_e32 v26, v26, v29
	ds_bpermute_b32 v28, v21, v27
	ds_bpermute_b32 v29, v21, v26
	v_addc_co_u32_e32 v35, vcc, 0, v35, vcc
	global_store_dwordx4 v[34:35], v[30:33], off offset:3584
	s_waitcnt lgkmcnt(1)
	v_add_f32_e32 v27, v27, v28
	s_waitcnt lgkmcnt(0)
	v_add_f32_e32 v26, v26, v29
	ds_bpermute_b32 v28, v22, v27
	ds_bpermute_b32 v29, v22, v26
	s_waitcnt lgkmcnt(1)
	v_add_f32_e32 v27, v27, v28
	s_waitcnt lgkmcnt(0)
	v_add_f32_e32 v28, v26, v29
	ds_bpermute_b32 v26, v23, v27
	ds_bpermute_b32 v29, v23, v28
	s_waitcnt lgkmcnt(1)
	v_add_f32_e32 v26, v27, v26
	s_waitcnt lgkmcnt(0)
	v_add_f32_e32 v27, v28, v29
	ds_bpermute_b32 v28, v24, v26
	ds_bpermute_b32 v29, v24, v27
	s_and_saveexec_b64 s[22:23], s[0:1]
	s_cbranch_execz .LBB0_1826
	s_waitcnt lgkmcnt(0)
	v_add_f32_e32 v29, v27, v29
	v_add_f32_e32 v28, v26, v28
	v_lshl_add_u64 v[26:27], s[20:21], 0, v[6:7]
	v_add_co_u32_e32 v26, vcc, 0x3c000, v26
	s_nop 1
	v_addc_co_u32_e32 v27, vcc, 0, v27, vcc
	v_mov_b32_e32 v92, v26
	v_mov_b32_e32 v93, v27
	v_and_b32_e32 v90, 0x3ff, v26
	v_add_u32_e32 v90, 68608, v90
	ds_write2_b32 v90, v28, v29 offset1:1
.LBB0_1826:
	s_or_b64 exec, exec, s[22:23]
	v_add_co_u32_e32 v18, vcc, 0x18000, v18
	ds_read_b128 v[30:33], v25 offset:12672
	s_nop 0
	v_addc_co_u32_e32 v19, vcc, 0, v19, vcc
	s_waitcnt lgkmcnt(1)
	global_load_dwordx4 v[26:29], v[18:19], off
	s_waitcnt vmcnt(0) lgkmcnt(0)
	v_pk_fma_f32 v[30:31], v[26:27], s[16:17], v[30:31] op_sel_hi:[1,0,1]
	v_pk_fma_f32 v[32:33], v[28:29], s[16:17], v[32:33] op_sel_hi:[1,0,1]
	v_pk_mul_f32 v[18:19], v[30:31], v[30:31]
	v_add_f32_e32 v28, v30, v31
	v_pk_mul_f32 v[26:27], v[32:33], v[32:33]
	v_add_f32_e32 v18, v18, v19
	v_add_f32_e32 v28, v32, v28
	v_add_f32_e32 v18, v26, v18
	v_add_f32_e32 v19, v33, v28
	v_add_f32_e32 v18, v27, v18
	ds_bpermute_b32 v26, v20, v19
	ds_bpermute_b32 v27, v20, v18
	v_lshl_add_u64 v[28:29], v[4:5], 0, s[18:19]
	v_add_co_u32_e32 v28, vcc, s56, v28
	s_waitcnt lgkmcnt(1)
	v_add_f32_e32 v19, v19, v26
	s_waitcnt lgkmcnt(0)
	v_add_f32_e32 v18, v18, v27
	ds_bpermute_b32 v26, v21, v19
	ds_bpermute_b32 v27, v21, v18
	v_addc_co_u32_e32 v29, vcc, 0, v29, vcc
	global_store_dwordx4 v[28:29], v[30:33], off offset:3584
	s_waitcnt lgkmcnt(1)
	v_add_f32_e32 v19, v19, v26
	s_waitcnt lgkmcnt(0)
	v_add_f32_e32 v18, v18, v27
	ds_bpermute_b32 v26, v22, v19
	ds_bpermute_b32 v27, v22, v18
	s_waitcnt lgkmcnt(1)
	v_add_f32_e32 v19, v19, v26
	s_waitcnt lgkmcnt(0)
	v_add_f32_e32 v26, v18, v27
	ds_bpermute_b32 v18, v23, v19
	ds_bpermute_b32 v27, v23, v26
	s_waitcnt lgkmcnt(1)
	v_add_f32_e32 v18, v19, v18
	s_waitcnt lgkmcnt(0)
	v_add_f32_e32 v19, v26, v27
	ds_bpermute_b32 v26, v24, v18
	ds_bpermute_b32 v27, v24, v19
	s_and_saveexec_b64 s[22:23], s[0:1]
	s_cbranch_execz .LBB0_1819
	s_waitcnt lgkmcnt(0)
	v_add_f32_e32 v27, v19, v27
	v_add_f32_e32 v26, v18, v26
	v_lshl_add_u64 v[18:19], s[20:21], 0, v[2:3]
	v_add_co_u32_e32 v18, vcc, 0x3c000, v18
	s_nop 1
	v_addc_co_u32_e32 v19, vcc, 0, v19, vcc
	v_mov_b32_e32 v92, v18
	v_mov_b32_e32 v93, v19
	v_and_b32_e32 v90, 0x3ff, v18
	v_add_u32_e32 v90, 68608, v90
	ds_write2_b32 v90, v26, v27 offset1:1
	s_branch .LBB0_1819
.Lstats_flush_0:
	s_waitcnt lgkmcnt(0)
	s_barrier
	v_readfirstlane_b32 s100, v92
	v_readfirstlane_b32 s101, v93
	v_lshlrev_b32_e32 v91, 2, v234
	s_and_b32 s100, s100, 0xfffffc00
	v_add_u32_e32 v94, 68608, v91
	ds_read_b32 v90, v94
	s_nop 4
	s_waitcnt lgkmcnt(0)
	global_atomic_add_f32 v91, v90, s[100:101]
	s_branch .LBB0_1815

.LBB0_2065:
	v_lshl_add_u64 v[30:31], v[12:13], 0, s[20:21]
	v_add_co_u32_e32 v28, vcc, 0x3c000, v30
	s_nop 1
	v_addc_co_u32_e32 v29, vcc, 0, v31, vcc
	global_load_dwordx2 v[42:43], v[28:29], off
	v_lshl_add_u64 v[28:29], v[10:11], 0, v[8:9]
	s_waitcnt lgkmcnt(0)
	global_load_dwordx4 v[38:41], v[28:29], off
	s_waitcnt vmcnt(1)
	v_pk_mul_f32 v[46:47], v[42:43], s[14:15] op_sel:[1,0] op_sel_hi:[0,0]
	v_fma_f32 v42, -v47, v47, v46
	v_max_f32_e32 v42, 0, v42
	v_add_f32_e32 v42, 0x3727c5ac, v42
	v_mul_f32_e32 v43, 0x4b800000, v42
	v_cmp_gt_f32_e32 vcc, s53, v42
	s_waitcnt vmcnt(0)
	v_pk_add_f32 v[38:39], v[38:39], v[46:47] op_sel:[0,1] neg_lo:[0,1] neg_hi:[0,1]
	v_pk_add_f32 v[40:41], v[40:41], v[46:47] op_sel:[0,1] neg_lo:[0,1] neg_hi:[0,1]
	v_cndmask_b32_e32 v42, v42, v43, vcc
	v_rsq_f32_e32 v48, v42
	ds_read_b128 v[42:45], v37
	v_mul_f32_e32 v46, 0x45800000, v48
	v_cndmask_b32_e32 v46, v48, v46, vcc
	v_pk_mul_f32 v[38:39], v[38:39], v[46:47] op_sel_hi:[1,0]
	v_pk_mul_f32 v[40:41], v[40:41], v[46:47] op_sel_hi:[1,0]
	v_pk_fma_f32 v[38:39], v[0:1], v[38:39], v[4:5]
	v_pk_fma_f32 v[40:41], v[2:3], v[40:41], v[6:7]
	s_waitcnt lgkmcnt(0)
	v_pk_fma_f32 v[42:43], v[38:39], s[16:17], v[42:43] op_sel_hi:[1,0,1]
	v_pk_fma_f32 v[44:45], v[40:41], s[16:17], v[44:45] op_sel_hi:[1,0,1]
	v_pk_mul_f32 v[38:39], v[42:43], v[42:43]
	v_add_f32_e32 v46, v43, v42
	v_pk_mul_f32 v[40:41], v[44:45], v[44:45]
	v_add_f32_e32 v38, v39, v38
	v_add_f32_e32 v46, v44, v46
	v_add_f32_e32 v38, v40, v38
	v_add_f32_e32 v39, v45, v46
	v_add_f32_e32 v38, v41, v38
	ds_bpermute_b32 v40, v32, v39
	ds_bpermute_b32 v41, v32, v38
	v_lshl_add_u64 v[46:47], v[26:27], 0, v[8:9]
	global_store_dwordx4 v[46:47], v[42:45], off offset:-8
	s_waitcnt lgkmcnt(1)
	v_add_f32_e32 v39, v39, v40
	s_waitcnt lgkmcnt(0)
	v_add_f32_e32 v38, v38, v41
	ds_bpermute_b32 v40, v33, v39
	ds_bpermute_b32 v41, v33, v38
	s_waitcnt lgkmcnt(1)
	v_add_f32_e32 v39, v39, v40
	s_waitcnt lgkmcnt(0)
	v_add_f32_e32 v38, v38, v41
	ds_bpermute_b32 v40, v34, v39
	ds_bpermute_b32 v41, v34, v38
	s_waitcnt lgkmcnt(1)
	v_add_f32_e32 v39, v39, v40
	s_waitcnt lgkmcnt(0)
	v_add_f32_e32 v40, v38, v41
	ds_bpermute_b32 v38, v35, v39
	ds_bpermute_b32 v41, v35, v40
	s_waitcnt lgkmcnt(1)
	v_add_f32_e32 v38, v39, v38
	s_waitcnt lgkmcnt(0)
	v_add_f32_e32 v39, v40, v41
	ds_bpermute_b32 v40, v36, v38
	ds_bpermute_b32 v41, v36, v39
	s_and_saveexec_b64 s[22:23], s[0:1]
	s_cbranch_execz .LBB0_2067
	v_add_co_u32_e32 v30, vcc, 0x4c000, v30
	s_waitcnt lgkmcnt(1)
	v_add_f32_e32 v38, v38, v40
	v_addc_co_u32_e32 v31, vcc, 0, v31, vcc
	s_waitcnt lgkmcnt(0)
	v_add_f32_e32 v39, v39, v41
	v_mov_b32_e32 v92, v30
	v_mov_b32_e32 v93, v31
	v_and_b32_e32 v90, 0x3ff, v30
	v_add_u32_e32 v90, 68608, v90
	ds_write2_b32 v90, v38, v39 offset1:1
.LBB0_2067:
	s_or_b64 exec, exec, s[22:23]
	v_lshl_add_u64 v[30:31], v[24:25], 0, s[20:21]
	v_add_co_u32_e32 v38, vcc, 0x3c000, v30
	s_nop 1
	v_addc_co_u32_e32 v39, vcc, 0, v31, vcc
	global_load_dwordx2 v[42:43], v[38:39], off
	v_add_co_u32_e32 v38, vcc, s54, v28
	s_waitcnt vmcnt(0)
	v_pk_mul_f32 v[46:47], v[42:43], s[14:15] op_sel:[1,0] op_sel_hi:[0,0]
	v_addc_co_u32_e32 v39, vcc, 0, v29, vcc
	s_waitcnt lgkmcnt(0)
	global_load_dwordx4 v[38:41], v[38:39], off
	v_fma_f32 v42, -v47, v47, v46
	v_max_f32_e32 v42, 0, v42
	v_add_f32_e32 v42, 0x3727c5ac, v42
	v_mul_f32_e32 v43, 0x4b800000, v42
	v_cmp_gt_f32_e32 vcc, s53, v42
	s_waitcnt vmcnt(0)
	v_pk_add_f32 v[38:39], v[38:39], v[46:47] op_sel:[0,1] neg_lo:[0,1] neg_hi:[0,1]
	v_cndmask_b32_e32 v42, v42, v43, vcc
	v_rsq_f32_e32 v48, v42
	ds_read_b128 v[42:45], v37 offset:4224
	v_pk_add_f32 v[40:41], v[40:41], v[46:47] op_sel:[0,1] neg_lo:[0,1] neg_hi:[0,1]
	v_mul_f32_e32 v46, 0x45800000, v48
	v_cndmask_b32_e32 v46, v48, v46, vcc
	v_pk_mul_f32 v[38:39], v[38:39], v[46:47] op_sel_hi:[1,0]
	v_pk_mul_f32 v[40:41], v[40:41], v[46:47] op_sel_hi:[1,0]
	v_pk_fma_f32 v[38:39], v[0:1], v[38:39], v[4:5]
	v_pk_fma_f32 v[40:41], v[2:3], v[40:41], v[6:7]
	s_waitcnt lgkmcnt(0)
	v_pk_fma_f32 v[42:43], v[38:39], s[16:17], v[42:43] op_sel_hi:[1,0,1]
	v_pk_fma_f32 v[44:45], v[40:41], s[16:17], v[44:45] op_sel_hi:[1,0,1]
	v_pk_mul_f32 v[38:39], v[42:43], v[42:43]
	v_add_f32_e32 v46, v43, v42
	v_pk_mul_f32 v[40:41], v[44:45], v[44:45]
	v_add_f32_e32 v38, v39, v38
	v_add_f32_e32 v46, v44, v46
	v_add_f32_e32 v38, v40, v38
	v_add_f32_e32 v39, v45, v46
	v_add_f32_e32 v38, v41, v38
	ds_bpermute_b32 v40, v32, v39
	ds_bpermute_b32 v41, v32, v38
	v_lshl_add_u64 v[46:47], v[22:23], 0, v[8:9]
	global_store_dwordx4 v[46:47], v[42:45], off
	s_waitcnt lgkmcnt(1)
	v_add_f32_e32 v39, v39, v40
	s_waitcnt lgkmcnt(0)
	v_add_f32_e32 v38, v38, v41
	ds_bpermute_b32 v40, v33, v39
	ds_bpermute_b32 v41, v33, v38
	s_waitcnt lgkmcnt(1)
	v_add_f32_e32 v39, v39, v40
	s_waitcnt lgkmcnt(0)
	v_add_f32_e32 v38, v38, v41
	ds_bpermute_b32 v40, v34, v39
	ds_bpermute_b32 v41, v34, v38
	s_waitcnt lgkmcnt(1)
	v_add_f32_e32 v39, v39, v40
	s_waitcnt lgkmcnt(0)
	v_add_f32_e32 v40, v38, v41
	ds_bpermute_b32 v38, v35, v39
	ds_bpermute_b32 v41, v35, v40
	s_waitcnt lgkmcnt(1)
	v_add_f32_e32 v38, v39, v38
	s_waitcnt lgkmcnt(0)
	v_add_f32_e32 v39, v40, v41
	ds_bpermute_b32 v40, v36, v38
	ds_bpermute_b32 v41, v36, v39
	s_and_saveexec_b64 s[22:23], s[0:1]
	s_cbranch_execz .LBB0_2069
	v_add_co_u32_e32 v30, vcc, 0x4c000, v30
	s_waitcnt lgkmcnt(1)
	v_add_f32_e32 v38, v38, v40
	v_addc_co_u32_e32 v31, vcc, 0, v31, vcc
	s_waitcnt lgkmcnt(0)
	v_add_f32_e32 v39, v39, v41
	v_mov_b32_e32 v92, v30
	v_mov_b32_e32 v93, v31
	v_and_b32_e32 v90, 0x3ff, v30
	v_add_u32_e32 v90, 68608, v90
	ds_write2_b32 v90, v38, v39 offset1:1
.LBB0_2069:
	s_or_b64 exec, exec, s[22:23]
	v_lshl_add_u64 v[30:31], v[20:21], 0, s[20:21]
	v_add_co_u32_e32 v38, vcc, 0x3c000, v30
	s_nop 1
	v_addc_co_u32_e32 v39, vcc, 0, v31, vcc
	global_load_dwordx2 v[42:43], v[38:39], off
	v_add_co_u32_e32 v38, vcc, s55, v28
	s_waitcnt vmcnt(0)
	v_pk_mul_f32 v[46:47], v[42:43], s[14:15] op_sel:[1,0] op_sel_hi:[0,0]
	v_addc_co_u32_e32 v39, vcc, 0, v29, vcc
	s_waitcnt lgkmcnt(0)
	global_load_dwordx4 v[38:41], v[38:39], off
	v_fma_f32 v42, -v47, v47, v46
	v_max_f32_e32 v42, 0, v42
	v_add_f32_e32 v42, 0x3727c5ac, v42
	v_mul_f32_e32 v43, 0x4b800000, v42
	v_cmp_gt_f32_e32 vcc, s53, v42
	s_waitcnt vmcnt(0)
	v_pk_add_f32 v[38:39], v[38:39], v[46:47] op_sel:[0,1] neg_lo:[0,1] neg_hi:[0,1]
	v_cndmask_b32_e32 v42, v42, v43, vcc
	v_rsq_f32_e32 v48, v42
	ds_read_b128 v[42:45], v37 offset:8448
	v_pk_add_f32 v[40:41], v[40:41], v[46:47] op_sel:[0,1] neg_lo:[0,1] neg_hi:[0,1]
	v_mul_f32_e32 v46, 0x45800000, v48
	v_cndmask_b32_e32 v46, v48, v46, vcc
	v_pk_mul_f32 v[38:39], v[38:39], v[46:47] op_sel_hi:[1,0]
	v_pk_mul_f32 v[40:41], v[40:41], v[46:47] op_sel_hi:[1,0]
	v_pk_fma_f32 v[38:39], v[0:1], v[38:39], v[4:5]
	v_pk_fma_f32 v[40:41], v[2:3], v[40:41], v[6:7]
	s_waitcnt lgkmcnt(0)
	v_pk_fma_f32 v[42:43], v[38:39], s[16:17], v[42:43] op_sel_hi:[1,0,1]
	v_pk_fma_f32 v[44:45], v[40:41], s[16:17], v[44:45] op_sel_hi:[1,0,1]
	v_pk_mul_f32 v[38:39], v[42:43], v[42:43]
	v_add_f32_e32 v46, v43, v42
	v_pk_mul_f32 v[40:41], v[44:45], v[44:45]
	v_add_f32_e32 v38, v39, v38
	v_add_f32_e32 v46, v44, v46
	v_add_f32_e32 v38, v40, v38
	v_add_f32_e32 v39, v45, v46
	v_add_f32_e32 v38, v41, v38
	ds_bpermute_b32 v40, v32, v39
	ds_bpermute_b32 v41, v32, v38
	v_lshl_add_u64 v[46:47], v[18:19], 0, v[8:9]
	global_store_dwordx4 v[46:47], v[42:45], off
	s_waitcnt lgkmcnt(1)
	v_add_f32_e32 v39, v39, v40
	s_waitcnt lgkmcnt(0)
	v_add_f32_e32 v38, v38, v41
	ds_bpermute_b32 v40, v33, v39
	ds_bpermute_b32 v41, v33, v38
	s_waitcnt lgkmcnt(1)
	v_add_f32_e32 v39, v39, v40
	s_waitcnt lgkmcnt(0)
	v_add_f32_e32 v38, v38, v41
	ds_bpermute_b32 v40, v34, v39
	ds_bpermute_b32 v41, v34, v38
	s_waitcnt lgkmcnt(1)
	v_add_f32_e32 v39, v39, v40
	s_waitcnt lgkmcnt(0)
	v_add_f32_e32 v40, v38, v41
	ds_bpermute_b32 v38, v35, v39
	ds_bpermute_b32 v41, v35, v40
	s_waitcnt lgkmcnt(1)
	v_add_f32_e32 v38, v39, v38
	s_waitcnt lgkmcnt(0)
	v_add_f32_e32 v39, v40, v41
	ds_bpermute_b32 v40, v36, v38
	ds_bpermute_b32 v41, v36, v39
	s_and_saveexec_b64 s[22:23], s[0:1]
	s_cbranch_execz .LBB0_2071
	v_add_co_u32_e32 v30, vcc, 0x4c000, v30
	s_waitcnt lgkmcnt(1)
	v_add_f32_e32 v38, v38, v40
	v_addc_co_u32_e32 v31, vcc, 0, v31, vcc
	s_waitcnt lgkmcnt(0)
	v_add_f32_e32 v39, v39, v41
	v_mov_b32_e32 v92, v30
	v_mov_b32_e32 v93, v31
	v_and_b32_e32 v90, 0x3ff, v30
	v_add_u32_e32 v90, 68608, v90
	ds_write2_b32 v90, v38, v39 offset1:1
.LBB0_2071:
	s_or_b64 exec, exec, s[22:23]
	v_lshl_add_u64 v[30:31], v[16:17], 0, s[20:21]
	v_add_co_u32_e32 v38, vcc, 0x3c000, v30
	s_nop 1
	v_addc_co_u32_e32 v39, vcc, 0, v31, vcc
	global_load_dwordx2 v[42:43], v[38:39], off
	v_add_co_u32_e32 v28, vcc, s56, v28
	s_nop 1
	v_addc_co_u32_e32 v29, vcc, 0, v29, vcc
	s_waitcnt lgkmcnt(0)
	global_load_dwordx4 v[38:41], v[28:29], off
	s_waitcnt vmcnt(1)
	v_pk_mul_f32 v[28:29], v[42:43], s[14:15] op_sel:[1,0] op_sel_hi:[0,0]
	v_fma_f32 v42, -v29, v29, v28
	v_max_f32_e32 v42, 0, v42
	v_add_f32_e32 v42, 0x3727c5ac, v42
	v_mul_f32_e32 v43, 0x4b800000, v42
	v_cmp_gt_f32_e32 vcc, s53, v42
	s_waitcnt vmcnt(0)
	v_pk_add_f32 v[38:39], v[38:39], v[28:29] op_sel:[0,1] neg_lo:[0,1] neg_hi:[0,1]
	v_pk_add_f32 v[28:29], v[40:41], v[28:29] op_sel:[0,1] neg_lo:[0,1] neg_hi:[0,1]
	v_cndmask_b32_e32 v42, v42, v43, vcc
	v_rsq_f32_e32 v46, v42
	ds_read_b128 v[42:45], v37 offset:12672
	v_mul_f32_e32 v40, 0x45800000, v46
	v_cndmask_b32_e32 v40, v46, v40, vcc
	v_pk_mul_f32 v[38:39], v[38:39], v[40:41] op_sel_hi:[1,0]
	v_pk_mul_f32 v[28:29], v[28:29], v[40:41] op_sel_hi:[1,0]
	v_pk_fma_f32 v[38:39], v[0:1], v[38:39], v[4:5]
	v_pk_fma_f32 v[28:29], v[2:3], v[28:29], v[6:7]
	s_waitcnt lgkmcnt(0)
	v_pk_fma_f32 v[40:41], v[38:39], s[16:17], v[42:43] op_sel_hi:[1,0,1]
	v_pk_fma_f32 v[42:43], v[28:29], s[16:17], v[44:45] op_sel_hi:[1,0,1]
	v_pk_mul_f32 v[28:29], v[40:41], v[40:41]
	v_add_f32_e32 v44, v41, v40
	v_pk_mul_f32 v[38:39], v[42:43], v[42:43]
	v_add_f32_e32 v28, v29, v28
	v_add_f32_e32 v44, v42, v44
	v_add_f32_e32 v28, v38, v28
	v_add_f32_e32 v29, v43, v44
	v_add_f32_e32 v28, v39, v28
	ds_bpermute_b32 v38, v32, v29
	ds_bpermute_b32 v39, v32, v28
	v_lshl_add_u64 v[44:45], v[14:15], 0, v[8:9]
	global_store_dwordx4 v[44:45], v[40:43], off
	s_waitcnt lgkmcnt(1)
	v_add_f32_e32 v29, v29, v38
	s_waitcnt lgkmcnt(0)
	v_add_f32_e32 v28, v28, v39
	ds_bpermute_b32 v38, v33, v29
	ds_bpermute_b32 v39, v33, v28
	s_waitcnt lgkmcnt(1)
	v_add_f32_e32 v29, v29, v38
	s_waitcnt lgkmcnt(0)
	v_add_f32_e32 v28, v28, v39
	ds_bpermute_b32 v38, v34, v29
	ds_bpermute_b32 v39, v34, v28
	s_waitcnt lgkmcnt(1)
	v_add_f32_e32 v29, v29, v38
	s_waitcnt lgkmcnt(0)
	v_add_f32_e32 v38, v28, v39
	ds_bpermute_b32 v28, v35, v29
	ds_bpermute_b32 v39, v35, v38
	s_waitcnt lgkmcnt(1)
	v_add_f32_e32 v28, v29, v28
	s_waitcnt lgkmcnt(0)
	v_add_f32_e32 v29, v38, v39
	ds_bpermute_b32 v38, v36, v28
	ds_bpermute_b32 v39, v36, v29
	s_and_saveexec_b64 s[22:23], s[0:1]
	s_cbranch_execz .LBB0_2064
	s_waitcnt lgkmcnt(1)
	v_add_f32_e32 v38, v28, v38
	v_add_co_u32_e32 v28, vcc, 0x4c000, v30
	s_waitcnt lgkmcnt(0)
	v_add_f32_e32 v39, v29, v39
	v_addc_co_u32_e32 v29, vcc, 0, v31, vcc
	v_mov_b32_e32 v92, v28
	v_mov_b32_e32 v93, v29
	v_and_b32_e32 v90, 0x3ff, v28
	v_add_u32_e32 v90, 68608, v90
	ds_write2_b32 v90, v38, v39 offset1:1
	s_branch .LBB0_2064

.LBB0_3286:
	s_or_b64 exec, exec, s[6:7]
	v_lshlrev_b32_e32 v60, 23, v55
	v_mov_b32_e32 v61, v5
	s_movk_i32 s2, 0x2100
	v_lshl_add_u64 v[62:63], s[52:53], 0, v[60:61]
	v_mul_lo_u32 v60, v243, s2
	v_readlane_b32 s6, v250, 22
	v_add_u32_e32 v64, 32, v60
	s_movk_i32 s2, 0x210
	v_lshlrev_b64 v[52:53], 1, v[52:53]
	v_readlane_b32 s7, v250, 23
	v_lshl_add_u32 v74, v242, 2, v64
	v_lshl_add_u32 v71, v244, 2, v64
	v_mad_u32_u24 v75, v242, s2, v64
	v_lshl_add_u64 v[62:63], v[62:63], 0, v[52:53]
	v_lshlrev_b32_e32 v64, 1, v242
	v_mov_b32_e32 v65, v5
	v_lshl_add_u64 v[52:53], s[6:7], 0, v[52:53]
	v_lshlrev_b32_e32 v70, 2, v54
	v_lshlrev_b32_e32 v76, 5, v54
	v_lshl_add_u64 v[62:63], v[62:63], 0, v[64:65]
	v_mul_u32_u24_e32 v54, 0x840, v54
	v_lshl_add_u64 v[64:65], v[52:53], 0, v[4:5]
	v_sub_u32_e32 v52, v241, v242
	v_cmp_eq_u32_e64 s[4:5], 0, v55
	v_subrev_u32_e32 v73, 17, v52
	v_add_u32_e32 v74, v74, v54
	s_waitcnt vmcnt(0)
	v_mov_b64_e32 v[52:53], v[56:57]
	v_lshrrev_b32_e32 v7, 4, v241
	v_pk_mov_b32 v[60:61], v[228:229], v[228:229] op_sel:[1,0]
	s_mov_b32 s2, 0
	v_xad_u32 v4, v70, -1, v241
	v_or_b32_e32 v72, 16, v242
	s_mov_b64 s[8:9], 0
	v_add_u32_e32 v75, v75, v76
	s_mov_b32 s10, 0
	v_mov_b64_e32 v[54:55], v[58:59]
	v_mov_b32_e32 v158, v71
	v_add_u32_e32 v159, 16, v71
	v_add_u32_e32 v176, 32, v71
	v_add_u32_e32 v177, 48, v71
	v_add_u32_e32 v178, 64, v71
	v_add_u32_e32 v179, 80, v71
	v_add_u32_e32 v180, 96, v71
	v_add_u32_e32 v181, 112, v71
	v_add_u32_e32 v182, 128, v71
	v_add_u32_e32 v183, 144, v71
	v_add_u32_e32 v184, 160, v71
	v_add_u32_e32 v185, 176, v71
	v_add_u32_e32 v186, 192, v71
	v_add_u32_e32 v187, 208, v71
	v_add_u32_e32 v188, 224, v71
	v_add_u32_e32 v189, 240, v71
	s_branch .LBB0_3288
.LBB0_3287:
	s_or_b64 exec, exec, s[6:7]
	v_mfma_f32_16x16x32_bf16 v[76:79], v[56:59], v[8:11], 0
	v_add_u32_e32 v84, 0x400, v74
	v_cmp_eq_u32_e64 s[6:7], s10, v7
	v_add_u32_e32 v73, -16, v73
	v_mfma_f32_16x16x32_bf16 v[80:83], v[56:59], v[12:15], 0
	s_nop 7
	ds_write2_b32 v74, v76, v80 offset1:16
	ds_write2_b32 v74, v77, v81 offset0:132 offset1:148
	ds_write2_b32 v84, v78, v82 offset0:8 offset1:24
	ds_write2_b32 v84, v79, v83 offset0:140 offset1:156
	v_mfma_f32_16x16x32_bf16 v[76:79], v[56:59], v[16:19], 0
	v_mfma_f32_16x16x32_bf16 v[80:83], v[56:59], v[20:23], 0
	s_nop 7
	ds_write2_b32 v74, v76, v80 offset0:32 offset1:48
	ds_write2_b32 v74, v77, v81 offset0:164 offset1:180
	ds_write2_b32 v84, v78, v82 offset0:40 offset1:56
	ds_write2_b32 v84, v79, v83 offset0:172 offset1:188
	v_mfma_f32_16x16x32_bf16 v[76:79], v[56:59], v[24:27], 0
	v_mfma_f32_16x16x32_bf16 v[80:83], v[56:59], v[28:31], 0
	s_nop 7
	ds_write2_b32 v74, v76, v80 offset0:64 offset1:80
	ds_write2_b32 v74, v77, v81 offset0:196 offset1:212
	ds_write2_b32 v84, v78, v82 offset0:72 offset1:88
	ds_write2_b32 v84, v79, v83 offset0:204 offset1:220
	v_mfma_f32_16x16x32_bf16 v[76:79], v[56:59], v[32:35], 0
	v_add_u32_e32 v80, 32, v71
	v_mfma_f32_16x16x32_bf16 v[56:59], v[56:59], v[36:39], 0
	s_nop 7
	ds_write2_b32 v74, v76, v56 offset0:96 offset1:112
	ds_write2_b32 v74, v77, v57 offset0:228 offset1:244
	ds_write2_b32 v84, v78, v58 offset0:104 offset1:120
	ds_write2_b32 v84, v79, v59 offset0:236 offset1:252
	ds_read2st64_b32 v[122:123], v158 offset1:1
	ds_read2st64_b32 v[124:125], v159 offset0:2 offset1:3
	ds_read2st64_b32 v[126:127], v176 offset0:4 offset1:5
	ds_read2st64_b32 v[128:129], v177 offset0:6 offset1:7
	ds_read2st64_b32 v[130:131], v178 offset0:8 offset1:9
	ds_read2st64_b32 v[132:133], v179 offset0:10 offset1:11
	ds_read2st64_b32 v[134:135], v180 offset0:12 offset1:13
	ds_read2st64_b32 v[136:137], v181 offset0:14 offset1:15
	ds_read2st64_b32 v[138:139], v182 offset0:16 offset1:17
	ds_read2st64_b32 v[140:141], v183 offset0:18 offset1:19
	ds_read2st64_b32 v[142:143], v184 offset0:20 offset1:21
	ds_read2st64_b32 v[144:145], v185 offset0:22 offset1:23
	s_waitcnt lgkmcnt(10)
	v_fma_f32 v156, -v229, v67, v122
	v_fma_f32 v157, v229, v66, v123
	v_fma_f32 v154, v228, v66, v156
	v_fma_f32 v155, v228, v67, v157
	ds_write2st64_b32 v158, v154, v155 offset1:1
	ds_read2st64_b32 v[146:147], v186 offset0:24 offset1:25
	v_fma_f32 v156, -v229, v155, v124
	v_fma_f32 v157, v229, v154, v125
	v_fma_f32 v66, v228, v154, v156
	v_fma_f32 v67, v228, v155, v157
	ds_write2st64_b32 v159, v66, v67 offset0:2 offset1:3
	s_waitcnt lgkmcnt(11)
	ds_read2st64_b32 v[148:149], v187 offset0:26 offset1:27
	v_fma_f32 v156, -v229, v67, v126
	v_fma_f32 v157, v229, v66, v127
	v_fma_f32 v154, v228, v66, v156
	v_fma_f32 v155, v228, v67, v157
	ds_write2st64_b32 v176, v154, v155 offset0:4 offset1:5
	s_waitcnt lgkmcnt(11)
	ds_read2st64_b32 v[150:151], v188 offset0:28 offset1:29
	v_fma_f32 v156, -v229, v155, v128
	v_fma_f32 v157, v229, v154, v129
	v_fma_f32 v66, v228, v154, v156
	v_fma_f32 v67, v228, v155, v157
	ds_write2st64_b32 v177, v66, v67 offset0:6 offset1:7
	s_waitcnt lgkmcnt(11)
	ds_read2st64_b32 v[152:153], v189 offset0:30 offset1:31
	v_fma_f32 v156, -v229, v67, v130
	v_fma_f32 v157, v229, v66, v131
	v_fma_f32 v154, v228, v66, v156
	v_fma_f32 v155, v228, v67, v157
	ds_write2st64_b32 v178, v154, v155 offset0:8 offset1:9
	v_fma_f32 v156, -v229, v155, v132
	v_fma_f32 v157, v229, v154, v133
	v_fma_f32 v66, v228, v154, v156
	v_fma_f32 v67, v228, v155, v157
	ds_write2st64_b32 v179, v66, v67 offset0:10 offset1:11
	v_fma_f32 v156, -v229, v67, v134
	v_fma_f32 v157, v229, v66, v135
	v_fma_f32 v154, v228, v66, v156
	v_fma_f32 v155, v228, v67, v157
	ds_write2st64_b32 v180, v154, v155 offset0:12 offset1:13
	v_fma_f32 v156, -v229, v155, v136
	v_fma_f32 v157, v229, v154, v137
	v_fma_f32 v66, v228, v154, v156
	v_fma_f32 v67, v228, v155, v157
	ds_write2st64_b32 v181, v66, v67 offset0:14 offset1:15
	s_waitcnt lgkmcnt(14)
	v_fma_f32 v156, -v229, v67, v138
	v_fma_f32 v157, v229, v66, v139
	v_fma_f32 v154, v228, v66, v156
	v_fma_f32 v155, v228, v67, v157
	ds_write2st64_b32 v182, v154, v155 offset0:16 offset1:17
	v_fma_f32 v156, -v229, v155, v140
	v_fma_f32 v157, v229, v154, v141
	v_fma_f32 v66, v228, v154, v156
	v_fma_f32 v67, v228, v155, v157
	ds_write2st64_b32 v183, v66, v67 offset0:18 offset1:19
	s_waitcnt lgkmcnt(14)
	v_fma_f32 v156, -v229, v67, v142
	v_fma_f32 v157, v229, v66, v143
	v_fma_f32 v154, v228, v66, v156
	v_fma_f32 v155, v228, v67, v157
	ds_write2st64_b32 v184, v154, v155 offset0:20 offset1:21
	v_fma_f32 v156, -v229, v155, v144
	v_fma_f32 v157, v229, v154, v145
	v_fma_f32 v66, v228, v154, v156
	v_fma_f32 v67, v228, v155, v157
	ds_write2st64_b32 v185, v66, v67 offset0:22 offset1:23
	s_waitcnt lgkmcnt(12)
	v_fma_f32 v156, -v229, v67, v146
	v_fma_f32 v157, v229, v66, v147
	v_fma_f32 v154, v228, v66, v156
	v_fma_f32 v155, v228, v67, v157
	ds_write2st64_b32 v186, v154, v155 offset0:24 offset1:25
	v_fma_f32 v156, -v229, v155, v148
	v_fma_f32 v157, v229, v154, v149
	v_fma_f32 v66, v228, v154, v156
	v_fma_f32 v67, v228, v155, v157
	ds_write2st64_b32 v187, v66, v67 offset0:26 offset1:27
	s_waitcnt lgkmcnt(10)
	v_fma_f32 v156, -v229, v67, v150
	v_fma_f32 v157, v229, v66, v151
	v_fma_f32 v154, v228, v66, v156
	v_fma_f32 v155, v228, v67, v157
	ds_write2st64_b32 v188, v154, v155 offset0:28 offset1:29
	v_fma_f32 v156, -v229, v155, v152
	v_fma_f32 v157, v229, v154, v153
	v_fma_f32 v66, v228, v154, v156
	v_fma_f32 v67, v228, v155, v157
	ds_write2st64_b32 v189, v66, v67 offset0:30 offset1:31
	ds_read_b128 v[124:127], v75
	ds_read_b128 v[128:131], v75 offset:16
	ds_read_b128 v[132:135], v75 offset:128
	ds_read_b128 v[136:139], v75 offset:144
	ds_read_b128 v[140:143], v75 offset:256
	ds_read_b128 v[144:147], v75 offset:272
	ds_read_b128 v[148:151], v75 offset:384
	ds_read_b128 v[152:155], v75 offset:400
	s_waitcnt lgkmcnt(6)
	v_cvt_pk_bf16_f32 v160, v124, v125
	v_cvt_pk_bf16_f32 v161, v126, v127
	v_cvt_pk_bf16_f32 v162, v128, v129
	v_cvt_pk_bf16_f32 v163, v130, v131
	s_waitcnt lgkmcnt(4)
	v_cvt_pk_bf16_f32 v164, v132, v133
	v_cvt_pk_bf16_f32 v165, v134, v135
	v_cvt_pk_bf16_f32 v166, v136, v137
	v_cvt_pk_bf16_f32 v167, v138, v139
	v_mfma_f32_16x16x32_bf16 v[56:59], v[160:163], v[0:3], 0
	s_waitcnt lgkmcnt(2)
	v_cvt_pk_bf16_f32 v168, v140, v141
	v_cvt_pk_bf16_f32 v169, v142, v143
	v_cvt_pk_bf16_f32 v170, v144, v145
	v_cvt_pk_bf16_f32 v171, v146, v147
	v_mfma_f32_16x16x32_bf16 v[56:59], v[164:167], v[40:43], v[56:59]
	s_waitcnt lgkmcnt(0)
	v_cvt_pk_bf16_f32 v172, v148, v149
	v_cvt_pk_bf16_f32 v173, v150, v151
	v_cvt_pk_bf16_f32 v174, v152, v153
	v_cvt_pk_bf16_f32 v175, v154, v155
	v_mfma_f32_16x16x32_bf16 v[56:59], v[168:171], v[44:47], v[56:59]
	s_nop 1
	v_mfma_f32_16x16x32_bf16 v[56:59], v[172:175], v[48:51], v[56:59]
	v_add_u32_e32 v78, s2, v70
	v_cndmask_b32_e64 v76, v4, v78, s[4:5]
	v_add_u32_e32 v76, v76, v240
	v_ashrrev_i32_e32 v77, 31, v76
	v_lshlrev_b64 v[76:77], 10, v[76:77]
	s_nop 2
	v_cvt_pk_bf16_f32 v56, v56, s0
	v_lshl_add_u64 v[76:77], v[62:63], 0, v[76:77]
	global_store_short v[76:77], v56, off
	v_add_u32_e32 v56, 1, v78
	v_xad_u32 v76, v78, -2, v241
	v_cndmask_b32_e64 v56, v76, v56, s[4:5]
	v_add_u32_e32 v56, v56, v240
	v_cvt_pk_bf16_f32 v76, v57, s0
	v_ashrrev_i32_e32 v57, 31, v56
	v_lshlrev_b64 v[56:57], 10, v[56:57]
	v_lshl_add_u64 v[56:57], v[62:63], 0, v[56:57]
	global_store_short v[56:57], v76, off
	v_add_u32_e32 v56, 2, v78
	v_xad_u32 v57, v78, -3, v241
	v_cndmask_b32_e64 v56, v57, v56, s[4:5]
	v_add_u32_e32 v56, v56, v240
	v_ashrrev_i32_e32 v57, 31, v56
	v_lshlrev_b64 v[56:57], 10, v[56:57]
	v_cvt_pk_bf16_f32 v58, v58, s0
	v_lshl_add_u64 v[56:57], v[62:63], 0, v[56:57]
	global_store_short v[56:57], v58, off
	v_add_u32_e32 v56, 3, v78
	v_xad_u32 v57, v78, -4, v241
	v_cndmask_b32_e64 v56, v57, v56, s[4:5]
	v_add_u32_e32 v56, v56, v240
	v_ashrrev_i32_e32 v57, 31, v56
	v_lshlrev_b64 v[56:57], 10, v[56:57]
	v_cvt_pk_bf16_f32 v58, v59, s0
	v_lshl_add_u64 v[56:57], v[62:63], 0, v[56:57]
	global_store_short v[56:57], v58, off
	s_add_i32 s2, s2, 16
	s_waitcnt vmcnt(4)
	v_mov_b64_e32 v[58:59], v[54:55]
	v_add_u32_e32 v4, -16, v4
	s_or_b64 s[8:9], s[6:7], s[8:9]
	v_mov_b64_e32 v[56:57], v[52:53]
	s_andn2_b64 exec, exec, s[8:9]
	s_cbranch_execz .LBB0_3302

.LBB0_3572:
	s_or_b64 exec, exec, s[6:7]
	v_lshlrev_b32_e32 v60, 23, v55
	v_mov_b32_e32 v61, v5
	s_movk_i32 s2, 0x2100
	v_lshl_add_u64 v[62:63], s[52:53], 0, v[60:61]
	v_mul_lo_u32 v60, v243, s2
	v_readlane_b32 s6, v250, 22
	v_add_u32_e32 v64, 32, v60
	s_movk_i32 s2, 0x210
	v_lshlrev_b64 v[52:53], 1, v[52:53]
	v_readlane_b32 s7, v250, 23
	v_lshl_add_u32 v74, v242, 2, v64
	v_lshl_add_u32 v71, v244, 2, v64
	v_mad_u32_u24 v75, v242, s2, v64
	v_lshl_add_u64 v[62:63], v[62:63], 0, v[52:53]
	v_lshlrev_b32_e32 v64, 1, v242
	v_mov_b32_e32 v65, v5
	v_lshl_add_u64 v[52:53], s[6:7], 0, v[52:53]
	v_lshlrev_b32_e32 v70, 2, v54
	v_lshlrev_b32_e32 v76, 5, v54
	v_lshl_add_u64 v[62:63], v[62:63], 0, v[64:65]
	v_mul_u32_u24_e32 v54, 0x840, v54
	v_lshl_add_u64 v[64:65], v[52:53], 0, v[4:5]
	v_sub_u32_e32 v52, v241, v242
	v_cmp_eq_u32_e64 s[4:5], 0, v55
	v_subrev_u32_e32 v73, 17, v52
	v_add_u32_e32 v74, v74, v54
	s_waitcnt vmcnt(0)
	v_mov_b64_e32 v[52:53], v[56:57]
	v_lshrrev_b32_e32 v7, 4, v241
	v_pk_mov_b32 v[60:61], v[228:229], v[228:229] op_sel:[1,0]
	s_mov_b32 s2, 0
	v_xad_u32 v4, v70, -1, v241
	v_or_b32_e32 v72, 16, v242
	s_mov_b64 s[8:9], 0
	v_add_u32_e32 v75, v75, v76
	s_mov_b32 s10, 0
	v_mov_b64_e32 v[54:55], v[58:59]
	v_mov_b32_e32 v121, v71
	v_add_u32_e32 v122, 16, v71
	v_add_u32_e32 v123, 32, v71
	v_add_u32_e32 v140, 48, v71
	v_add_u32_e32 v141, 64, v71
	v_add_u32_e32 v142, 80, v71
	v_add_u32_e32 v143, 96, v71
	v_add_u32_e32 v144, 112, v71
	v_add_u32_e32 v145, 128, v71
	v_add_u32_e32 v146, 144, v71
	v_add_u32_e32 v147, 160, v71
	v_add_u32_e32 v148, 176, v71
	v_add_u32_e32 v149, 192, v71
	v_add_u32_e32 v150, 208, v71
	v_add_u32_e32 v151, 224, v71
	v_add_u32_e32 v152, 240, v71
	s_branch .LBB0_3574
.LBB0_3573:
	s_or_b64 exec, exec, s[6:7]
	v_mfma_f32_16x16x32_bf16 v[76:79], v[56:59], v[8:11], 0
	v_add_u32_e32 v84, 0x400, v74
	v_cmp_eq_u32_e64 s[6:7], s10, v7
	v_add_u32_e32 v73, -16, v73
	v_mfma_f32_16x16x32_bf16 v[80:83], v[56:59], v[12:15], 0
	s_nop 7
	ds_write2_b32 v74, v76, v80 offset1:16
	ds_write2_b32 v74, v77, v81 offset0:132 offset1:148
	ds_write2_b32 v84, v78, v82 offset0:8 offset1:24
	ds_write2_b32 v84, v79, v83 offset0:140 offset1:156
	v_mfma_f32_16x16x32_bf16 v[76:79], v[56:59], v[16:19], 0
	v_mfma_f32_16x16x32_bf16 v[80:83], v[56:59], v[20:23], 0
	s_nop 7
	ds_write2_b32 v74, v76, v80 offset0:32 offset1:48
	ds_write2_b32 v74, v77, v81 offset0:164 offset1:180
	ds_write2_b32 v84, v78, v82 offset0:40 offset1:56
	ds_write2_b32 v84, v79, v83 offset0:172 offset1:188
	v_mfma_f32_16x16x32_bf16 v[76:79], v[56:59], v[24:27], 0
	v_mfma_f32_16x16x32_bf16 v[80:83], v[56:59], v[28:31], 0
	s_nop 7
	ds_write2_b32 v74, v76, v80 offset0:64 offset1:80
	ds_write2_b32 v74, v77, v81 offset0:196 offset1:212
	ds_write2_b32 v84, v78, v82 offset0:72 offset1:88
	ds_write2_b32 v84, v79, v83 offset0:204 offset1:220
	v_mfma_f32_16x16x32_bf16 v[76:79], v[56:59], v[32:35], 0
	v_add_u32_e32 v80, 32, v71
	v_mfma_f32_16x16x32_bf16 v[56:59], v[56:59], v[36:39], 0
	s_nop 7
	ds_write2_b32 v74, v76, v56 offset0:96 offset1:112
	ds_write2_b32 v74, v77, v57 offset0:228 offset1:244
	ds_write2_b32 v84, v78, v58 offset0:104 offset1:120
	ds_write2_b32 v84, v79, v59 offset0:236 offset1:252
	ds_read2st64_b32 v[86:87], v121 offset1:1
	ds_read2st64_b32 v[88:89], v122 offset0:2 offset1:3
	ds_read2st64_b32 v[90:91], v123 offset0:4 offset1:5
	ds_read2st64_b32 v[92:93], v140 offset0:6 offset1:7
	ds_read2st64_b32 v[94:95], v141 offset0:8 offset1:9
	ds_read2st64_b32 v[96:97], v142 offset0:10 offset1:11
	ds_read2st64_b32 v[98:99], v143 offset0:12 offset1:13
	ds_read2st64_b32 v[100:101], v144 offset0:14 offset1:15
	ds_read2st64_b32 v[102:103], v145 offset0:16 offset1:17
	ds_read2st64_b32 v[104:105], v146 offset0:18 offset1:19
	ds_read2st64_b32 v[106:107], v147 offset0:20 offset1:21
	ds_read2st64_b32 v[108:109], v148 offset0:22 offset1:23
	s_waitcnt lgkmcnt(10)
	v_fma_f32 v119, -v229, v67, v86
	v_fma_f32 v120, v229, v66, v87
	v_fma_f32 v85, v228, v66, v119
	v_fma_f32 v118, v228, v67, v120
	ds_write2st64_b32 v121, v85, v118 offset1:1
	ds_read2st64_b32 v[110:111], v149 offset0:24 offset1:25
	v_fma_f32 v119, -v229, v118, v88
	v_fma_f32 v120, v229, v85, v89
	v_fma_f32 v66, v228, v85, v119
	v_fma_f32 v67, v228, v118, v120
	ds_write2st64_b32 v122, v66, v67 offset0:2 offset1:3
	s_waitcnt lgkmcnt(11)
	ds_read2st64_b32 v[112:113], v150 offset0:26 offset1:27
	v_fma_f32 v119, -v229, v67, v90
	v_fma_f32 v120, v229, v66, v91
	v_fma_f32 v85, v228, v66, v119
	v_fma_f32 v118, v228, v67, v120
	ds_write2st64_b32 v123, v85, v118 offset0:4 offset1:5
	s_waitcnt lgkmcnt(11)
	ds_read2st64_b32 v[114:115], v151 offset0:28 offset1:29
	v_fma_f32 v119, -v229, v118, v92
	v_fma_f32 v120, v229, v85, v93
	v_fma_f32 v66, v228, v85, v119
	v_fma_f32 v67, v228, v118, v120
	ds_write2st64_b32 v140, v66, v67 offset0:6 offset1:7
	s_waitcnt lgkmcnt(11)
	ds_read2st64_b32 v[116:117], v152 offset0:30 offset1:31
	v_fma_f32 v119, -v229, v67, v94
	v_fma_f32 v120, v229, v66, v95
	v_fma_f32 v85, v228, v66, v119
	v_fma_f32 v118, v228, v67, v120
	ds_write2st64_b32 v141, v85, v118 offset0:8 offset1:9
	v_fma_f32 v119, -v229, v118, v96
	v_fma_f32 v120, v229, v85, v97
	v_fma_f32 v66, v228, v85, v119
	v_fma_f32 v67, v228, v118, v120
	ds_write2st64_b32 v142, v66, v67 offset0:10 offset1:11
	v_fma_f32 v119, -v229, v67, v98
	v_fma_f32 v120, v229, v66, v99
	v_fma_f32 v85, v228, v66, v119
	v_fma_f32 v118, v228, v67, v120
	ds_write2st64_b32 v143, v85, v118 offset0:12 offset1:13
	v_fma_f32 v119, -v229, v118, v100
	v_fma_f32 v120, v229, v85, v101
	v_fma_f32 v66, v228, v85, v119
	v_fma_f32 v67, v228, v118, v120
	ds_write2st64_b32 v144, v66, v67 offset0:14 offset1:15
	s_waitcnt lgkmcnt(14)
	v_fma_f32 v119, -v229, v67, v102
	v_fma_f32 v120, v229, v66, v103
	v_fma_f32 v85, v228, v66, v119
	v_fma_f32 v118, v228, v67, v120
	ds_write2st64_b32 v145, v85, v118 offset0:16 offset1:17
	v_fma_f32 v119, -v229, v118, v104
	v_fma_f32 v120, v229, v85, v105
	v_fma_f32 v66, v228, v85, v119
	v_fma_f32 v67, v228, v118, v120
	ds_write2st64_b32 v146, v66, v67 offset0:18 offset1:19
	s_waitcnt lgkmcnt(14)
	v_fma_f32 v119, -v229, v67, v106
	v_fma_f32 v120, v229, v66, v107
	v_fma_f32 v85, v228, v66, v119
	v_fma_f32 v118, v228, v67, v120
	ds_write2st64_b32 v147, v85, v118 offset0:20 offset1:21
	v_fma_f32 v119, -v229, v118, v108
	v_fma_f32 v120, v229, v85, v109
	v_fma_f32 v66, v228, v85, v119
	v_fma_f32 v67, v228, v118, v120
	ds_write2st64_b32 v148, v66, v67 offset0:22 offset1:23
	s_waitcnt lgkmcnt(12)
	v_fma_f32 v119, -v229, v67, v110
	v_fma_f32 v120, v229, v66, v111
	v_fma_f32 v85, v228, v66, v119
	v_fma_f32 v118, v228, v67, v120
	ds_write2st64_b32 v149, v85, v118 offset0:24 offset1:25
	v_fma_f32 v119, -v229, v118, v112
	v_fma_f32 v120, v229, v85, v113
	v_fma_f32 v66, v228, v85, v119
	v_fma_f32 v67, v228, v118, v120
	ds_write2st64_b32 v150, v66, v67 offset0:26 offset1:27
	s_waitcnt lgkmcnt(10)
	v_fma_f32 v119, -v229, v67, v114
	v_fma_f32 v120, v229, v66, v115
	v_fma_f32 v85, v228, v66, v119
	v_fma_f32 v118, v228, v67, v120
	ds_write2st64_b32 v151, v85, v118 offset0:28 offset1:29
	v_fma_f32 v119, -v229, v118, v116
	v_fma_f32 v120, v229, v85, v117
	v_fma_f32 v66, v228, v85, v119
	v_fma_f32 v67, v228, v118, v120
	ds_write2st64_b32 v152, v66, v67 offset0:30 offset1:31
	ds_read_b128 v[88:91], v75
	ds_read_b128 v[92:95], v75 offset:16
	ds_read_b128 v[96:99], v75 offset:128
	ds_read_b128 v[100:103], v75 offset:144
	ds_read_b128 v[104:107], v75 offset:256
	ds_read_b128 v[108:111], v75 offset:272
	ds_read_b128 v[112:115], v75 offset:384
	ds_read_b128 v[116:119], v75 offset:400
	s_waitcnt lgkmcnt(6)
	v_cvt_pk_bf16_f32 v124, v88, v89
	v_cvt_pk_bf16_f32 v125, v90, v91
	v_cvt_pk_bf16_f32 v126, v92, v93
	v_cvt_pk_bf16_f32 v127, v94, v95
	s_waitcnt lgkmcnt(4)
	v_cvt_pk_bf16_f32 v128, v96, v97
	v_cvt_pk_bf16_f32 v129, v98, v99
	v_cvt_pk_bf16_f32 v130, v100, v101
	v_cvt_pk_bf16_f32 v131, v102, v103
	v_mfma_f32_16x16x32_bf16 v[56:59], v[124:127], v[0:3], 0
	s_waitcnt lgkmcnt(2)
	v_cvt_pk_bf16_f32 v132, v104, v105
	v_cvt_pk_bf16_f32 v133, v106, v107
	v_cvt_pk_bf16_f32 v134, v108, v109
	v_cvt_pk_bf16_f32 v135, v110, v111
	v_mfma_f32_16x16x32_bf16 v[56:59], v[128:131], v[40:43], v[56:59]
	s_waitcnt lgkmcnt(0)
	v_cvt_pk_bf16_f32 v136, v112, v113
	v_cvt_pk_bf16_f32 v137, v114, v115
	v_cvt_pk_bf16_f32 v138, v116, v117
	v_cvt_pk_bf16_f32 v139, v118, v119
	v_mfma_f32_16x16x32_bf16 v[56:59], v[132:135], v[44:47], v[56:59]
	s_nop 1
	v_mfma_f32_16x16x32_bf16 v[56:59], v[136:139], v[48:51], v[56:59]
	v_add_u32_e32 v78, s2, v70
	v_cndmask_b32_e64 v76, v4, v78, s[4:5]
	v_add_u32_e32 v76, v76, v240
	v_ashrrev_i32_e32 v77, 31, v76
	v_lshlrev_b64 v[76:77], 10, v[76:77]
	s_nop 2
	v_cvt_pk_bf16_f32 v56, v56, s0
	v_lshl_add_u64 v[76:77], v[62:63], 0, v[76:77]
	global_store_short v[76:77], v56, off
	v_add_u32_e32 v56, 1, v78
	v_xad_u32 v76, v78, -2, v241
	v_cndmask_b32_e64 v56, v76, v56, s[4:5]
	v_add_u32_e32 v56, v56, v240
	v_cvt_pk_bf16_f32 v76, v57, s0
	v_ashrrev_i32_e32 v57, 31, v56
	v_lshlrev_b64 v[56:57], 10, v[56:57]
	v_lshl_add_u64 v[56:57], v[62:63], 0, v[56:57]
	global_store_short v[56:57], v76, off
	v_add_u32_e32 v56, 2, v78
	v_xad_u32 v57, v78, -3, v241
	v_cndmask_b32_e64 v56, v57, v56, s[4:5]
	v_add_u32_e32 v56, v56, v240
	v_ashrrev_i32_e32 v57, 31, v56
	v_lshlrev_b64 v[56:57], 10, v[56:57]
	v_cvt_pk_bf16_f32 v58, v58, s0
	v_lshl_add_u64 v[56:57], v[62:63], 0, v[56:57]
	global_store_short v[56:57], v58, off
	v_add_u32_e32 v56, 3, v78
	v_xad_u32 v57, v78, -4, v241
	v_cndmask_b32_e64 v56, v57, v56, s[4:5]
	v_add_u32_e32 v56, v56, v240
	v_ashrrev_i32_e32 v57, 31, v56
	v_lshlrev_b64 v[56:57], 10, v[56:57]
	v_cvt_pk_bf16_f32 v58, v59, s0
	v_lshl_add_u64 v[56:57], v[62:63], 0, v[56:57]
	global_store_short v[56:57], v58, off
	s_add_i32 s2, s2, 16
	s_waitcnt vmcnt(4)
	v_mov_b64_e32 v[58:59], v[54:55]
	v_add_u32_e32 v4, -16, v4
	s_or_b64 s[8:9], s[6:7], s[8:9]
	v_mov_b64_e32 v[56:57], v[52:53]
	s_andn2_b64 exec, exec, s[8:9]
	s_cbranch_execz .LBB0_3588

.LBB0_3734:
	s_setprio 1
	ds_read_b128 v[148:151], v112
	ds_read_b128 v[152:155], v113 offset:36864
	ds_read_b128 v[156:159], v112 offset:32
	ds_read_b128 v[160:163], v113 offset:36896
	ds_read_b128 v[164:167], v113 offset:41472
	ds_read_b128 v[168:171], v113 offset:41504
	s_waitcnt lgkmcnt(4)
	v_mfma_f32_32x32x16_bf16 v[48:63], v[148:151], v[152:155], v[48:63]
	global_load_dwordx4 v[116:119], v176, s[98:99] offset:256
	global_load_dwordx4 v[120:123], v180, s[98:99] offset:256
	s_waitcnt lgkmcnt(1)
	v_mfma_f32_32x32x16_bf16 v[32:47], v[148:151], v[164:167], v[32:47]
	global_load_dwordx4 v[124:127], v182, s[98:99] offset:256
	global_load_dwordx4 v[128:131], v184, s[98:99] offset:256
	ds_read_b128 v[148:151], v112 offset:4608
	ds_read_b128 v[172:175], v112 offset:4640
	s_waitcnt lgkmcnt(1)
	v_mfma_f32_32x32x16_bf16 v[16:31], v[148:151], v[152:155], v[16:31]
	global_load_dwordx4 v[132:135], v178, s[98:99]
	global_load_dwordx4 v[136:139], v98, s[98:99]
	v_mfma_f32_32x32x16_bf16 v[0:15], v[148:151], v[164:167], v[0:15]
	global_load_dwordx4 v[140:143], v186, s[98:99]
	global_load_dwordx4 v[144:147], v188, s[98:99] offset:-128
	v_mfma_f32_32x32x16_bf16 v[48:63], v[156:159], v[160:163], v[48:63]
	v_mfma_f32_32x32x16_bf16 v[32:47], v[156:159], v[168:171], v[32:47]
	s_waitcnt lgkmcnt(0)
	v_mfma_f32_32x32x16_bf16 v[16:31], v[172:175], v[160:163], v[16:31]
	ds_read_b128 v[148:151], v112 offset:64
	ds_read_b128 v[152:155], v113 offset:36928
	ds_read_b128 v[156:159], v112 offset:96
	ds_read_b128 v[160:163], v113 offset:36960
	v_mfma_f32_32x32x16_bf16 v[0:15], v[172:175], v[168:171], v[0:15]
	s_waitcnt vmcnt(15)
	ds_write_b128 v114, v[64:67] offset:18432
	ds_read_b128 v[164:167], v113 offset:41536
	ds_read_b128 v[168:171], v113 offset:41568
	s_waitcnt lgkmcnt(5)
	v_mfma_f32_32x32x16_bf16 v[48:63], v[148:151], v[152:155], v[48:63]
	s_waitcnt vmcnt(14)
	ds_write_b128 v114, v[68:71] offset:23040
	s_waitcnt lgkmcnt(2)
	v_mfma_f32_32x32x16_bf16 v[32:47], v[148:151], v[164:167], v[32:47]
	s_waitcnt vmcnt(13)
	ds_write_b128 v114, v[72:75] offset:27648
	ds_read_b128 v[148:151], v112 offset:4672
	ds_read_b128 v[172:175], v112 offset:4704
	s_waitcnt lgkmcnt(1)
	v_mfma_f32_32x32x16_bf16 v[16:31], v[148:151], v[152:155], v[16:31]
	s_waitcnt vmcnt(12)
	ds_write_b128 v114, v[76:79] offset:32256
	v_mfma_f32_32x32x16_bf16 v[0:15], v[148:151], v[164:167], v[0:15]
	s_waitcnt vmcnt(11)
	ds_write_b128 v114, v[80:83] offset:55296
	v_mfma_f32_32x32x16_bf16 v[48:63], v[156:159], v[160:163], v[48:63]
	s_waitcnt vmcnt(10)
	ds_write_b128 v114, v[84:87] offset:59904
	v_mfma_f32_32x32x16_bf16 v[32:47], v[156:159], v[168:171], v[32:47]
	s_waitcnt vmcnt(9)
	ds_write_b128 v114, v[88:91] offset:64512
	s_waitcnt lgkmcnt(4)
	v_mfma_f32_32x32x16_bf16 v[16:31], v[172:175], v[160:163], v[16:31]
	s_waitcnt vmcnt(8)
	ds_write_b128 v115, v[92:95] offset:13824
	v_mfma_f32_32x32x16_bf16 v[0:15], v[172:175], v[168:171], v[0:15]
	s_setprio 0
	s_waitcnt lgkmcnt(0)
	s_barrier
	s_setprio 1
	ds_read_b128 v[148:151], v112 offset:18432
	ds_read_b128 v[152:155], v113 offset:55296
	ds_read_b128 v[156:159], v112 offset:18464
	ds_read_b128 v[160:163], v113 offset:55328
	ds_read_b128 v[164:167], v113 offset:59904
	ds_read_b128 v[168:171], v113 offset:59936
	s_waitcnt lgkmcnt(4)
	v_mfma_f32_32x32x16_bf16 v[48:63], v[148:151], v[152:155], v[48:63]
	global_load_dwordx4 v[64:67], v176, s[98:99] offset:384
	global_load_dwordx4 v[68:71], v180, s[98:99] offset:384
	s_waitcnt lgkmcnt(1)
	v_mfma_f32_32x32x16_bf16 v[32:47], v[148:151], v[164:167], v[32:47]
	global_load_dwordx4 v[72:75], v182, s[98:99] offset:384
	global_load_dwordx4 v[76:79], v184, s[98:99] offset:384
	ds_read_b128 v[148:151], v112 offset:23040
	ds_read_b128 v[172:175], v112 offset:23072
	s_waitcnt lgkmcnt(1)
	v_mfma_f32_32x32x16_bf16 v[16:31], v[148:151], v[152:155], v[16:31]
	global_load_dwordx4 v[80:83], v178, s[98:99] offset:128
	global_load_dwordx4 v[84:87], v99, s[98:99]
	v_mfma_f32_32x32x16_bf16 v[0:15], v[148:151], v[164:167], v[0:15]
	global_load_dwordx4 v[88:91], v186, s[98:99] offset:128
	global_load_dwordx4 v[92:95], v188, s[98:99]
	v_mfma_f32_32x32x16_bf16 v[48:63], v[156:159], v[160:163], v[48:63]
	v_mfma_f32_32x32x16_bf16 v[32:47], v[156:159], v[168:171], v[32:47]
	s_waitcnt lgkmcnt(0)
	v_mfma_f32_32x32x16_bf16 v[16:31], v[172:175], v[160:163], v[16:31]
	ds_read_b128 v[148:151], v112 offset:18496
	ds_read_b128 v[152:155], v113 offset:55360
	ds_read_b128 v[156:159], v112 offset:18528
	ds_read_b128 v[160:163], v113 offset:55392
	v_mfma_f32_32x32x16_bf16 v[0:15], v[172:175], v[168:171], v[0:15]
	s_add_u32 s98, s98, 0x100
	s_addc_u32 s99, s99, 0
	s_add_i32 s0, s0, 2
	s_cmp_lt_u32 s0, 3
	s_waitcnt vmcnt(15)
	ds_write_b128 v114, v[116:119]
	ds_read_b128 v[164:167], v113 offset:59968
	ds_read_b128 v[168:171], v113 offset:60000
	s_waitcnt lgkmcnt(5)
	v_mfma_f32_32x32x16_bf16 v[48:63], v[148:151], v[152:155], v[48:63]
	s_waitcnt vmcnt(14)
	ds_write_b128 v114, v[120:123] offset:4608
	s_waitcnt lgkmcnt(2)
	v_mfma_f32_32x32x16_bf16 v[32:47], v[148:151], v[164:167], v[32:47]
	s_waitcnt vmcnt(13)
	ds_write_b128 v114, v[124:127] offset:9216
	ds_read_b128 v[148:151], v112 offset:23104
	ds_read_b128 v[172:175], v112 offset:23136
	s_waitcnt lgkmcnt(1)
	v_mfma_f32_32x32x16_bf16 v[16:31], v[148:151], v[152:155], v[16:31]
	s_waitcnt vmcnt(12)
	ds_write_b128 v114, v[128:131] offset:13824
	v_mfma_f32_32x32x16_bf16 v[0:15], v[148:151], v[164:167], v[0:15]
	s_waitcnt vmcnt(11)
	ds_write_b128 v114, v[132:135] offset:36864
	v_mfma_f32_32x32x16_bf16 v[48:63], v[156:159], v[160:163], v[48:63]
	s_waitcnt vmcnt(10)
	ds_write_b128 v114, v[136:139] offset:41472
	v_mfma_f32_32x32x16_bf16 v[32:47], v[156:159], v[168:171], v[32:47]
	s_waitcnt vmcnt(9)
	ds_write_b128 v114, v[140:143] offset:46080
	s_waitcnt lgkmcnt(4)
	v_mfma_f32_32x32x16_bf16 v[16:31], v[172:175], v[160:163], v[16:31]
	s_waitcnt vmcnt(8)
	ds_write_b128 v114, v[144:147] offset:50688
	v_mfma_f32_32x32x16_bf16 v[0:15], v[172:175], v[168:171], v[0:15]
	s_setprio 0
	s_waitcnt lgkmcnt(0)
	s_barrier
	s_cbranch_scc1 .LBB0_3734
	s_setprio 1
	ds_read_b128 v[98:101], v112
	ds_read_b128 v[102:105], v113 offset:36864
	ds_read_b128 v[106:109], v112 offset:32
	ds_read_b128 v[116:119], v113 offset:36896
	ds_read_b128 v[120:123], v113 offset:41472
	ds_read_b128 v[124:127], v113 offset:41504
	s_waitcnt lgkmcnt(4)
	v_mfma_f32_32x32x16_bf16 v[48:63], v[98:101], v[102:105], v[48:63]
	s_waitcnt lgkmcnt(1)
	v_mfma_f32_32x32x16_bf16 v[32:47], v[98:101], v[120:123], v[32:47]
	ds_read_b128 v[98:101], v112 offset:4608
	ds_read_b128 v[128:131], v112 offset:4640
	s_waitcnt lgkmcnt(1)
	v_mfma_f32_32x32x16_bf16 v[16:31], v[98:101], v[102:105], v[16:31]
	v_mfma_f32_32x32x16_bf16 v[0:15], v[98:101], v[120:123], v[0:15]
	v_mfma_f32_32x32x16_bf16 v[48:63], v[106:109], v[116:119], v[48:63]
	v_mfma_f32_32x32x16_bf16 v[32:47], v[106:109], v[124:127], v[32:47]
	s_waitcnt lgkmcnt(0)
	v_mfma_f32_32x32x16_bf16 v[16:31], v[128:131], v[116:119], v[16:31]
	ds_read_b128 v[98:101], v112 offset:64
	ds_read_b128 v[102:105], v113 offset:36928
	ds_read_b128 v[106:109], v112 offset:96
	ds_read_b128 v[116:119], v113 offset:36960
	v_mfma_f32_32x32x16_bf16 v[0:15], v[128:131], v[124:127], v[0:15]
	s_waitcnt vmcnt(7)
	ds_write_b128 v114, v[64:67] offset:18432
	ds_read_b128 v[120:123], v113 offset:41536
	ds_read_b128 v[124:127], v113 offset:41568
	s_waitcnt lgkmcnt(5)
	v_mfma_f32_32x32x16_bf16 v[48:63], v[98:101], v[102:105], v[48:63]
	s_waitcnt vmcnt(6)
	ds_write_b128 v114, v[68:71] offset:23040
	s_waitcnt lgkmcnt(2)
	v_mfma_f32_32x32x16_bf16 v[32:47], v[98:101], v[120:123], v[32:47]
	s_waitcnt vmcnt(5)
	ds_write_b128 v114, v[72:75] offset:27648
	ds_read_b128 v[98:101], v112 offset:4672
	ds_read_b128 v[128:131], v112 offset:4704
	s_waitcnt lgkmcnt(1)
	v_mfma_f32_32x32x16_bf16 v[16:31], v[98:101], v[102:105], v[16:31]
	s_waitcnt vmcnt(4)
	ds_write_b128 v114, v[76:79] offset:32256
	v_mfma_f32_32x32x16_bf16 v[0:15], v[98:101], v[120:123], v[0:15]
	s_waitcnt vmcnt(3)
	ds_write_b128 v114, v[80:83] offset:55296
	s_waitcnt lgkmcnt(2)
	v_mfma_f32_32x32x16_bf16 v[16:31], v[128:131], v[116:119], v[16:31]
	s_waitcnt vmcnt(2)
	ds_write_b128 v114, v[84:87] offset:59904
	v_mfma_f32_32x32x16_bf16 v[0:15], v[128:131], v[124:127], v[0:15]
	s_waitcnt vmcnt(1)
	ds_write_b128 v114, v[88:91] offset:64512
	v_mfma_f32_32x32x16_bf16 v[48:63], v[106:109], v[116:119], v[48:63]
	s_waitcnt vmcnt(0)
	ds_write_b128 v115, v[92:95] offset:13824
	v_mfma_f32_32x32x16_bf16 v[32:47], v[106:109], v[124:127], v[32:47]
	s_setprio 0
	s_waitcnt lgkmcnt(0)
	s_barrier
	s_setprio 1
	ds_read_b128 v[64:67], v112 offset:18432
	ds_read_b128 v[68:71], v113 offset:55296
	ds_read_b128 v[72:75], v112 offset:18464
	ds_read_b128 v[76:79], v113 offset:55328
	ds_read_b128 v[80:83], v113 offset:59904
	ds_read_b128 v[84:87], v113 offset:59936
	s_waitcnt lgkmcnt(4)
	v_mfma_f32_32x32x16_bf16 v[48:63], v[64:67], v[68:71], v[48:63]
	s_waitcnt lgkmcnt(1)
	v_mfma_f32_32x32x16_bf16 v[32:47], v[64:67], v[80:83], v[32:47]
	ds_read_b128 v[64:67], v112 offset:23040
	ds_read_b128 v[88:91], v112 offset:23072
	s_waitcnt lgkmcnt(1)
	v_mfma_f32_32x32x16_bf16 v[16:31], v[64:67], v[68:71], v[16:31]
	v_mfma_f32_32x32x16_bf16 v[0:15], v[64:67], v[80:83], v[0:15]
	v_mfma_f32_32x32x16_bf16 v[48:63], v[72:75], v[76:79], v[48:63]
	v_mfma_f32_32x32x16_bf16 v[32:47], v[72:75], v[84:87], v[32:47]
	s_waitcnt lgkmcnt(0)
	v_mfma_f32_32x32x16_bf16 v[16:31], v[88:91], v[76:79], v[16:31]
	ds_read_b128 v[64:67], v112 offset:18496
	ds_read_b128 v[68:71], v113 offset:55360
	ds_read_b128 v[72:75], v112 offset:18528
	ds_read_b128 v[76:79], v113 offset:55392
	v_mfma_f32_32x32x16_bf16 v[0:15], v[88:91], v[84:87], v[0:15]
	ds_read_b128 v[80:83], v113 offset:59968
	ds_read_b128 v[84:87], v113 offset:60000
	s_waitcnt lgkmcnt(4)
	v_mfma_f32_32x32x16_bf16 v[48:63], v[64:67], v[68:71], v[48:63]
	s_waitcnt lgkmcnt(1)
	v_mfma_f32_32x32x16_bf16 v[32:47], v[64:67], v[80:83], v[32:47]
	ds_read_b128 v[64:67], v112 offset:23104
	ds_read_b128 v[88:91], v112 offset:23136
	s_waitcnt lgkmcnt(1)
	v_mfma_f32_32x32x16_bf16 v[16:31], v[64:67], v[68:71], v[16:31]
	v_mfma_f32_32x32x16_bf16 v[0:15], v[64:67], v[80:83], v[0:15]
	s_waitcnt lgkmcnt(0)
	v_mfma_f32_32x32x16_bf16 v[16:31], v[88:91], v[76:79], v[16:31]
	v_mfma_f32_32x32x16_bf16 v[0:15], v[88:91], v[84:87], v[0:15]
	v_mfma_f32_32x32x16_bf16 v[48:63], v[72:75], v[76:79], v[48:63]
	v_mfma_f32_32x32x16_bf16 v[32:47], v[72:75], v[84:87], v[32:47]
	s_setprio 0
	s_nop 10
	v_cvt_pk_bf16_f32 v32, v32, s0
	v_cvt_pk_bf16_f32 v0, v0, s0
	s_barrier
	ds_write_b16 v111, v32 offset:64
	v_cvt_pk_bf16_f32 v32, v49, s0
	ds_write_b16 v111, v0 offset:8768
	v_cvt_pk_bf16_f32 v0, v17, s0
	ds_write_b16 v111, v32 offset:272
	v_cvt_pk_bf16_f32 v32, v33, s0
	ds_write_b16 v111, v0 offset:8976
	v_cvt_pk_bf16_f32 v0, v1, s0
	ds_write_b16 v111, v32 offset:336
	v_cvt_pk_bf16_f32 v32, v50, s0
	ds_write_b16 v111, v0 offset:9040
	v_cvt_pk_bf16_f32 v0, v18, s0
	ds_write_b16 v111, v32 offset:544
	v_cvt_pk_bf16_f32 v32, v34, s0
	ds_write_b16 v111, v0 offset:9248
	v_cvt_pk_bf16_f32 v0, v2, s0
	ds_write_b16 v111, v32 offset:608
	v_cvt_pk_bf16_f32 v32, v51, s0
	ds_write_b16 v111, v0 offset:9312
	v_cvt_pk_bf16_f32 v0, v19, s0
	ds_write_b16 v111, v32 offset:816
	v_cvt_pk_bf16_f32 v32, v35, s0
	ds_write_b16 v111, v0 offset:9520
	v_cvt_pk_bf16_f32 v0, v3, s0
	ds_write_b16 v111, v32 offset:880
	v_cvt_pk_bf16_f32 v32, v52, s0
	ds_write_b16 v111, v0 offset:9584
	v_cvt_pk_bf16_f32 v0, v20, s0
	ds_write_b16 v111, v32 offset:2176
	v_cvt_pk_bf16_f32 v32, v36, s0
	ds_write_b16 v111, v0 offset:10880
	v_cvt_pk_bf16_f32 v0, v4, s0
	ds_write_b16 v111, v32 offset:2240
	v_cvt_pk_bf16_f32 v32, v53, s0
	ds_write_b16 v111, v0 offset:10944
	v_cvt_pk_bf16_f32 v0, v21, s0
	ds_write_b16 v111, v32 offset:2448
	v_cvt_pk_bf16_f32 v32, v37, s0
	ds_write_b16 v111, v0 offset:11152
	v_cvt_pk_bf16_f32 v0, v5, s0
	ds_write_b16 v111, v32 offset:2512
	v_cvt_pk_bf16_f32 v32, v54, s0
	ds_write_b16 v111, v0 offset:11216
	v_cvt_pk_bf16_f32 v0, v22, s0
	ds_write_b16 v111, v32 offset:2720
	v_cvt_pk_bf16_f32 v32, v38, s0
	ds_write_b16 v111, v0 offset:11424
	v_cvt_pk_bf16_f32 v0, v6, s0
	ds_write_b16 v111, v32 offset:2784
	v_cvt_pk_bf16_f32 v32, v55, s0
	ds_write_b16 v111, v0 offset:11488
	v_cvt_pk_bf16_f32 v0, v23, s0
	ds_write_b16 v111, v32 offset:2992
	v_cvt_pk_bf16_f32 v32, v39, s0
	ds_write_b16 v111, v0 offset:11696
	v_cvt_pk_bf16_f32 v0, v7, s0
	ds_write_b16 v111, v32 offset:3056
	v_cvt_pk_bf16_f32 v32, v56, s0
	ds_write_b16 v111, v0 offset:11760
	v_cvt_pk_bf16_f32 v0, v24, s0
	ds_write_b16 v111, v32 offset:4352
	v_cvt_pk_bf16_f32 v32, v40, s0
	ds_write_b16 v111, v0 offset:13056
	v_cvt_pk_bf16_f32 v0, v8, s0
	ds_write_b16 v111, v32 offset:4416
	v_cvt_pk_bf16_f32 v32, v57, s0
	ds_write_b16 v111, v0 offset:13120
	v_cvt_pk_bf16_f32 v0, v25, s0
	ds_write_b16 v111, v32 offset:4624
	v_cvt_pk_bf16_f32 v32, v41, s0
	ds_write_b16 v111, v0 offset:13328
	v_cvt_pk_bf16_f32 v0, v9, s0
	ds_write_b16 v111, v32 offset:4688
	v_cvt_pk_bf16_f32 v32, v58, s0
	ds_write_b16 v111, v0 offset:13392
	v_cvt_pk_bf16_f32 v0, v26, s0
	ds_write_b16 v111, v32 offset:4896
	v_cvt_pk_bf16_f32 v32, v42, s0
	ds_write_b16 v111, v0 offset:13600
	v_cvt_pk_bf16_f32 v0, v10, s0
	ds_write_b16 v111, v32 offset:4960
	v_cvt_pk_bf16_f32 v32, v59, s0
	ds_write_b16 v111, v0 offset:13664
	v_cvt_pk_bf16_f32 v0, v27, s0
	ds_write_b16 v111, v32 offset:5168
	v_cvt_pk_bf16_f32 v32, v43, s0
	ds_write_b16 v111, v0 offset:13872
	v_cvt_pk_bf16_f32 v0, v11, s0
	ds_write_b16 v111, v32 offset:5232
	v_cvt_pk_bf16_f32 v32, v60, s0
	ds_write_b16 v111, v0 offset:13936
	v_cvt_pk_bf16_f32 v0, v28, s0
	ds_write_b16 v111, v32 offset:6528
	v_cvt_pk_bf16_f32 v32, v44, s0
	ds_write_b16 v111, v0 offset:15232
	v_cvt_pk_bf16_f32 v0, v12, s0
	ds_write_b16 v111, v32 offset:6592
	v_cvt_pk_bf16_f32 v32, v61, s0
	ds_write_b16 v111, v0 offset:15296
	v_cvt_pk_bf16_f32 v0, v29, s0
	ds_write_b16 v111, v32 offset:6800
	v_cvt_pk_bf16_f32 v32, v45, s0
	ds_write_b16 v111, v0 offset:15504
	v_cvt_pk_bf16_f32 v0, v13, s0
	ds_write_b16 v111, v32 offset:6864
	v_cvt_pk_bf16_f32 v32, v62, s0
	ds_write_b16 v111, v0 offset:15568
	v_cvt_pk_bf16_f32 v0, v30, s0
	ds_write_b16 v111, v32 offset:7072
	v_cvt_pk_bf16_f32 v32, v46, s0
	ds_write_b16 v111, v0 offset:15776
	v_cvt_pk_bf16_f32 v0, v14, s0
	ds_write_b16 v111, v32 offset:7136
	v_cvt_pk_bf16_f32 v32, v63, s0
	ds_write_b16 v111, v0 offset:15840
	v_cvt_pk_bf16_f32 v0, v31, s0
	v_cvt_pk_bf16_f32 v48, v48, s0
	ds_write_b16 v111, v32 offset:7344
	v_cvt_pk_bf16_f32 v32, v47, s0
	v_cvt_pk_bf16_f32 v16, v16, s0
	ds_write_b16 v111, v0 offset:16048
	v_cvt_pk_bf16_f32 v0, v15, s0
	v_mov_b32_e32 v15, v110
	ds_write_b16 v111, v48
	ds_write_b16 v111, v32 offset:7408
	ds_write_b16 v111, v16 offset:8704
	ds_write_b16 v111, v0 offset:16112
	s_waitcnt lgkmcnt(0)
	s_barrier
	v_mov_b64_e32 v[2:3], s[4:5]
	v_lshlrev_b32_e32 v0, 3, v15
	v_and_b32_e32 v0, 0x78, v0
	v_ashrrev_i32_e32 v1, 4, v15
	v_lshlrev_b32_e32 v96, 1, v0
	v_add_u32_e32 v0, s63, v1
	s_lshl_b32 s16, s26, 10
	v_mad_i64_i32 v[2:3], s[0:1], v0, s60, v[2:3]
	v_lshl_add_u64 v[2:3], s[16:17], 1, v[2:3]
	v_lshl_add_u64 v[2:3], s[22:23], 1, v[2:3]
	v_lshl_add_u64 v[2:3], v[2:3], 0, v[96:97]
	global_load_dwordx4 v[6:9], v[2:3], off
	v_add_co_u32_e32 v80, vcc, 0x18000, v2
	s_nop 1
	v_addc_co_u32_e32 v81, vcc, 0, v3, vcc
	global_load_dwordx4 v[24:27], v[80:81], off
	v_add_co_u32_e32 v80, vcc, 0x30000, v2
	s_nop 1
	v_addc_co_u32_e32 v81, vcc, 0, v3, vcc
	global_load_dwordx4 v[28:31], v[80:81], off
	v_add_co_u32_e32 v80, vcc, 0x48000, v2
	s_nop 1
	v_addc_co_u32_e32 v81, vcc, 0, v3, vcc
	global_load_dwordx4 v[32:35], v[80:81], off
	v_add_co_u32_e32 v80, vcc, 0x60000, v2
	s_nop 1
	v_addc_co_u32_e32 v81, vcc, 0, v3, vcc
	global_load_dwordx4 v[36:39], v[80:81], off
	v_add_co_u32_e32 v80, vcc, 0x78000, v2
	s_nop 1
	v_addc_co_u32_e32 v81, vcc, 0, v3, vcc
	global_load_dwordx4 v[40:43], v[80:81], off
	v_add_co_u32_e32 v80, vcc, 0x90000, v2
	s_nop 1
	v_addc_co_u32_e32 v81, vcc, 0, v3, vcc
	global_load_dwordx4 v[44:47], v[80:81], off
	v_add_co_u32_e32 v80, vcc, 0xa8000, v2
	s_nop 1
	v_addc_co_u32_e32 v81, vcc, 0, v3, vcc
	global_load_dwordx4 v[48:51], v[80:81], off
	v_add_u32_e32 v14, 32, v96
	v_mad_u64_u32 v[2:3], s[0:1], v1, s54, v[14:15]
	ds_read_b128 v[2:5], v2
	v_ashrrev_i32_e32 v1, 31, v0
	v_lshlrev_b64 v[0:1], 11, v[0:1]
	v_lshl_add_u64 v[0:1], s[24:25], 0, v[0:1]
	v_lshl_add_u64 v[16:17], v[0:1], 0, v[96:97]
	v_cndmask_b32_e64 v1, 0, 1, s[44:45]
	v_mov_b32_e32 v0, 0
	v_cmp_ne_u32_e64 s[0:1], 1, v1
	s_andn2_b64 vcc, exec, s[44:45]
	v_mov_b32_e32 v10, 0
	v_mov_b32_e32 v11, 0
	v_mov_b32_e32 v12, 0
	v_mov_b32_e32 v13, 0
	s_cbranch_vccnz .LBB0_3737
	global_load_dwordx4 v[10:13], v[16:17], off
	v_add_co_u32_e32 v80, vcc, 0x8000, v16
	s_nop 1
	v_addc_co_u32_e32 v81, vcc, 0, v17, vcc
	global_load_dwordx4 v[52:55], v[80:81], off
	v_add_co_u32_e32 v80, vcc, 0x10000, v16
	s_nop 1
	v_addc_co_u32_e32 v81, vcc, 0, v17, vcc
	global_load_dwordx4 v[56:59], v[80:81], off
	v_add_co_u32_e32 v80, vcc, 0x18000, v16
	s_nop 1
	v_addc_co_u32_e32 v81, vcc, 0, v17, vcc
	global_load_dwordx4 v[60:63], v[80:81], off
	v_add_co_u32_e32 v80, vcc, 0x20000, v16
	s_nop 1
	v_addc_co_u32_e32 v81, vcc, 0, v17, vcc
	global_load_dwordx4 v[64:67], v[80:81], off
	v_add_co_u32_e32 v80, vcc, 0x28000, v16
	s_nop 1
	v_addc_co_u32_e32 v81, vcc, 0, v17, vcc
	global_load_dwordx4 v[68:71], v[80:81], off
	v_add_co_u32_e32 v80, vcc, 0x30000, v16
	s_nop 1
	v_addc_co_u32_e32 v81, vcc, 0, v17, vcc
	global_load_dwordx4 v[72:75], v[80:81], off
	v_add_co_u32_e32 v80, vcc, 0x38000, v16
	s_nop 1
	v_addc_co_u32_e32 v81, vcc, 0, v17, vcc
	global_load_dwordx4 v[76:79], v[80:81], off
.LBB0_3737:
	s_waitcnt vmcnt(0)
	v_lshlrev_b32_e32 v18, 16, v6
	v_and_b32_e32 v19, 0xffff0000, v6
	s_waitcnt lgkmcnt(0)
	v_lshlrev_b32_e32 v20, 16, v2
	v_and_b32_e32 v21, 0xffff0000, v2
	v_lshlrev_b32_e32 v22, 16, v10
	v_and_b32_e32 v23, 0xffff0000, v10
	v_pk_fma_f32 v[18:19], v[18:19], v[20:21], v[22:23]
	v_lshlrev_b32_e32 v6, 16, v7
	v_cvt_pk_bf16_f32 v2, v18, v19
	v_and_b32_e32 v7, 0xffff0000, v7
	v_lshlrev_b32_e32 v18, 16, v3
	v_and_b32_e32 v19, 0xffff0000, v3
	v_lshlrev_b32_e32 v10, 16, v11
	v_and_b32_e32 v11, 0xffff0000, v11
	v_pk_fma_f32 v[6:7], v[6:7], v[18:19], v[10:11]
	v_lshlrev_b32_e32 v10, 16, v4
	v_cvt_pk_bf16_f32 v3, v6, v7
	v_lshlrev_b32_e32 v6, 16, v8
	v_and_b32_e32 v7, 0xffff0000, v8
	v_and_b32_e32 v11, 0xffff0000, v4
	v_lshlrev_b32_e32 v18, 16, v12
	v_and_b32_e32 v19, 0xffff0000, v12
	v_pk_fma_f32 v[6:7], v[6:7], v[10:11], v[18:19]
	v_lshlrev_b32_e32 v8, 16, v5
	v_cvt_pk_bf16_f32 v4, v6, v7
	v_lshlrev_b32_e32 v6, 16, v9
	v_and_b32_e32 v7, 0xffff0000, v9
	v_and_b32_e32 v9, 0xffff0000, v5
	v_lshlrev_b32_e32 v10, 16, v13
	v_and_b32_e32 v11, 0xffff0000, v13
	v_pk_fma_f32 v[6:7], v[6:7], v[8:9], v[10:11]
	v_add_u32_e32 v1, 0x100, v15
	v_cvt_pk_bf16_f32 v5, v6, v7
	v_ashrrev_i32_e32 v1, 4, v1
	global_store_dwordx4 v[16:17], v[2:5], off
	s_and_b64 vcc, exec, s[0:1]
	s_nop 0
	v_add_u32_e32 v2, s63, v1
	v_mov_b64_e32 v[4:5], s[4:5]
	v_mad_i64_i32 v[4:5], s[44:45], v2, s60, v[4:5]
	v_lshl_add_u64 v[4:5], s[16:17], 1, v[4:5]
	v_lshl_add_u64 v[4:5], s[22:23], 1, v[4:5]
	v_lshl_add_u64 v[4:5], v[4:5], 0, v[96:97]
	v_mov_b64_e32 v[8:9], v[24:25]
	v_mov_b64_e32 v[10:11], v[26:27]
	v_mad_u64_u32 v[4:5], s[44:45], v1, s54, v[14:15]
	ds_read_b128 v[4:7], v4
	v_ashrrev_i32_e32 v3, 31, v2
	v_lshlrev_b64 v[2:3], 11, v[2:3]
	v_lshl_add_u64 v[2:3], s[24:25], 0, v[2:3]
	v_lshl_add_u64 v[12:13], v[2:3], 0, v[96:97]
	v_mov_b32_e32 v1, 0
	v_mov_b32_e32 v2, 0
	v_mov_b32_e32 v3, 0
	s_cbranch_vccnz .LBB0_3739
	v_mov_b64_e32 v[0:1], v[52:53]
	v_mov_b64_e32 v[2:3], v[54:55]
.LBB0_3739:
	s_waitcnt vmcnt(0)
	v_lshlrev_b32_e32 v16, 16, v8
	v_and_b32_e32 v17, 0xffff0000, v8
	s_waitcnt lgkmcnt(0)
	v_lshlrev_b32_e32 v18, 16, v4
	v_and_b32_e32 v19, 0xffff0000, v4
	v_lshlrev_b32_e32 v20, 16, v0
	v_and_b32_e32 v21, 0xffff0000, v0
	v_pk_fma_f32 v[16:17], v[16:17], v[18:19], v[20:21]
	v_lshlrev_b32_e32 v8, 16, v9
	v_cvt_pk_bf16_f32 v0, v16, v17
	v_and_b32_e32 v9, 0xffff0000, v9
	v_lshlrev_b32_e32 v4, 16, v5
	v_and_b32_e32 v5, 0xffff0000, v5
	v_lshlrev_b32_e32 v16, 16, v1
	v_and_b32_e32 v17, 0xffff0000, v1
	v_pk_fma_f32 v[4:5], v[8:9], v[4:5], v[16:17]
	v_lshlrev_b32_e32 v8, 16, v6
	v_cvt_pk_bf16_f32 v1, v4, v5
	v_lshlrev_b32_e32 v4, 16, v10
	v_and_b32_e32 v5, 0xffff0000, v10
	v_and_b32_e32 v9, 0xffff0000, v6
	v_lshlrev_b32_e32 v16, 16, v2
	v_and_b32_e32 v17, 0xffff0000, v2
	v_pk_fma_f32 v[4:5], v[4:5], v[8:9], v[16:17]
	v_lshlrev_b32_e32 v6, 16, v7
	v_cvt_pk_bf16_f32 v2, v4, v5
	v_lshlrev_b32_e32 v4, 16, v11
	v_and_b32_e32 v5, 0xffff0000, v11
	v_and_b32_e32 v7, 0xffff0000, v7
	v_lshlrev_b32_e32 v8, 16, v3
	v_and_b32_e32 v9, 0xffff0000, v3
	v_pk_fma_f32 v[4:5], v[4:5], v[6:7], v[8:9]
	s_and_b64 vcc, exec, s[0:1]
	v_cvt_pk_bf16_f32 v3, v4, v5
	global_store_dwordx4 v[12:13], v[0:3], off
	v_mov_b32_e32 v10, 0
	v_mov_b32_e32 v11, 0
	v_add_u32_e32 v0, 0x200, v15
	v_ashrrev_i32_e32 v1, 4, v0
	v_add_u32_e32 v0, s63, v1
	v_mov_b64_e32 v[2:3], s[4:5]
	v_mad_i64_i32 v[2:3], s[44:45], v0, s60, v[2:3]
	v_lshl_add_u64 v[2:3], s[16:17], 1, v[2:3]
	v_lshl_add_u64 v[2:3], s[22:23], 1, v[2:3]
	v_lshl_add_u64 v[2:3], v[2:3], 0, v[96:97]
	v_mov_b64_e32 v[6:7], v[28:29]
	v_mov_b64_e32 v[8:9], v[30:31]
	v_mad_u64_u32 v[2:3], s[44:45], v1, s54, v[14:15]
	ds_read_b128 v[2:5], v2
	v_ashrrev_i32_e32 v1, 31, v0
	v_lshlrev_b64 v[0:1], 11, v[0:1]
	v_lshl_add_u64 v[0:1], s[24:25], 0, v[0:1]
	v_lshl_add_u64 v[16:17], v[0:1], 0, v[96:97]
	v_mov_b32_e32 v0, 0
	v_mov_b32_e32 v12, 0
	v_mov_b32_e32 v13, 0
	s_cbranch_vccnz .LBB0_3741
	v_mov_b64_e32 v[10:11], v[56:57]
	v_mov_b64_e32 v[12:13], v[58:59]
.LBB0_3741:
	s_waitcnt vmcnt(0)
	v_lshlrev_b32_e32 v18, 16, v6
	v_and_b32_e32 v19, 0xffff0000, v6
	s_waitcnt lgkmcnt(0)
	v_lshlrev_b32_e32 v20, 16, v2
	v_and_b32_e32 v21, 0xffff0000, v2
	v_lshlrev_b32_e32 v22, 16, v10
	v_and_b32_e32 v23, 0xffff0000, v10
	v_pk_fma_f32 v[18:19], v[18:19], v[20:21], v[22:23]
	v_lshlrev_b32_e32 v6, 16, v7
	v_cvt_pk_bf16_f32 v2, v18, v19
	v_and_b32_e32 v7, 0xffff0000, v7
	v_lshlrev_b32_e32 v18, 16, v3
	v_and_b32_e32 v19, 0xffff0000, v3
	v_lshlrev_b32_e32 v10, 16, v11
	v_and_b32_e32 v11, 0xffff0000, v11
	v_pk_fma_f32 v[6:7], v[6:7], v[18:19], v[10:11]
	v_lshlrev_b32_e32 v10, 16, v4
	v_cvt_pk_bf16_f32 v3, v6, v7
	v_lshlrev_b32_e32 v6, 16, v8
	v_and_b32_e32 v7, 0xffff0000, v8
	v_and_b32_e32 v11, 0xffff0000, v4
	v_lshlrev_b32_e32 v18, 16, v12
	v_and_b32_e32 v19, 0xffff0000, v12
	v_pk_fma_f32 v[6:7], v[6:7], v[10:11], v[18:19]
	v_lshlrev_b32_e32 v8, 16, v5
	v_cvt_pk_bf16_f32 v4, v6, v7
	v_lshlrev_b32_e32 v6, 16, v9
	v_and_b32_e32 v7, 0xffff0000, v9
	v_and_b32_e32 v9, 0xffff0000, v5
	v_lshlrev_b32_e32 v10, 16, v13
	v_and_b32_e32 v11, 0xffff0000, v13
	v_pk_fma_f32 v[6:7], v[6:7], v[8:9], v[10:11]
	v_add_u32_e32 v1, 0x300, v15
	v_cvt_pk_bf16_f32 v5, v6, v7
	v_ashrrev_i32_e32 v1, 4, v1
	global_store_dwordx4 v[16:17], v[2:5], off
	s_and_b64 vcc, exec, s[0:1]
	s_nop 0
	v_add_u32_e32 v2, s63, v1
	v_mov_b64_e32 v[4:5], s[4:5]
	v_mad_i64_i32 v[4:5], s[44:45], v2, s60, v[4:5]
	v_lshl_add_u64 v[4:5], s[16:17], 1, v[4:5]
	v_lshl_add_u64 v[4:5], s[22:23], 1, v[4:5]
	v_lshl_add_u64 v[4:5], v[4:5], 0, v[96:97]
	v_mov_b64_e32 v[8:9], v[32:33]
	v_mov_b64_e32 v[10:11], v[34:35]
	v_mad_u64_u32 v[4:5], s[44:45], v1, s54, v[14:15]
	ds_read_b128 v[4:7], v4
	v_ashrrev_i32_e32 v3, 31, v2
	v_lshlrev_b64 v[2:3], 11, v[2:3]
	v_lshl_add_u64 v[2:3], s[24:25], 0, v[2:3]
	v_lshl_add_u64 v[12:13], v[2:3], 0, v[96:97]
	v_mov_b32_e32 v1, 0
	v_mov_b32_e32 v2, 0
	v_mov_b32_e32 v3, 0
	s_cbranch_vccnz .LBB0_3743
	v_mov_b64_e32 v[0:1], v[60:61]
	v_mov_b64_e32 v[2:3], v[62:63]
.LBB0_3743:
	s_waitcnt vmcnt(0)
	v_lshlrev_b32_e32 v16, 16, v8
	v_and_b32_e32 v17, 0xffff0000, v8
	s_waitcnt lgkmcnt(0)
	v_lshlrev_b32_e32 v18, 16, v4
	v_and_b32_e32 v19, 0xffff0000, v4
	v_lshlrev_b32_e32 v20, 16, v0
	v_and_b32_e32 v21, 0xffff0000, v0
	v_pk_fma_f32 v[16:17], v[16:17], v[18:19], v[20:21]
	v_lshlrev_b32_e32 v8, 16, v9
	v_cvt_pk_bf16_f32 v0, v16, v17
	v_and_b32_e32 v9, 0xffff0000, v9
	v_lshlrev_b32_e32 v4, 16, v5
	v_and_b32_e32 v5, 0xffff0000, v5
	v_lshlrev_b32_e32 v16, 16, v1
	v_and_b32_e32 v17, 0xffff0000, v1
	v_pk_fma_f32 v[4:5], v[8:9], v[4:5], v[16:17]
	v_lshlrev_b32_e32 v8, 16, v6
	v_cvt_pk_bf16_f32 v1, v4, v5
	v_lshlrev_b32_e32 v4, 16, v10
	v_and_b32_e32 v5, 0xffff0000, v10
	v_and_b32_e32 v9, 0xffff0000, v6
	v_lshlrev_b32_e32 v16, 16, v2
	v_and_b32_e32 v17, 0xffff0000, v2
	v_pk_fma_f32 v[4:5], v[4:5], v[8:9], v[16:17]
	v_lshlrev_b32_e32 v6, 16, v7
	v_cvt_pk_bf16_f32 v2, v4, v5
	v_lshlrev_b32_e32 v4, 16, v11
	v_and_b32_e32 v5, 0xffff0000, v11
	v_and_b32_e32 v7, 0xffff0000, v7
	v_lshlrev_b32_e32 v8, 16, v3
	v_and_b32_e32 v9, 0xffff0000, v3
	v_pk_fma_f32 v[4:5], v[4:5], v[6:7], v[8:9]
	s_and_b64 vcc, exec, s[0:1]
	v_cvt_pk_bf16_f32 v3, v4, v5
	global_store_dwordx4 v[12:13], v[0:3], off
	v_mov_b32_e32 v10, 0
	v_mov_b32_e32 v11, 0
	v_add_u32_e32 v0, 0x400, v15
	v_ashrrev_i32_e32 v1, 4, v0
	v_add_u32_e32 v0, s63, v1
	v_mov_b64_e32 v[2:3], s[4:5]
	v_mad_i64_i32 v[2:3], s[44:45], v0, s60, v[2:3]
	v_lshl_add_u64 v[2:3], s[16:17], 1, v[2:3]
	v_lshl_add_u64 v[2:3], s[22:23], 1, v[2:3]
	v_lshl_add_u64 v[2:3], v[2:3], 0, v[96:97]
	v_mov_b64_e32 v[6:7], v[36:37]
	v_mov_b64_e32 v[8:9], v[38:39]
	v_mad_u64_u32 v[2:3], s[44:45], v1, s54, v[14:15]
	ds_read_b128 v[2:5], v2
	v_ashrrev_i32_e32 v1, 31, v0
	v_lshlrev_b64 v[0:1], 11, v[0:1]
	v_lshl_add_u64 v[0:1], s[24:25], 0, v[0:1]
	v_lshl_add_u64 v[16:17], v[0:1], 0, v[96:97]
	v_mov_b32_e32 v0, 0
	v_mov_b32_e32 v12, 0
	v_mov_b32_e32 v13, 0
	s_cbranch_vccnz .LBB0_3745
	v_mov_b64_e32 v[10:11], v[64:65]
	v_mov_b64_e32 v[12:13], v[66:67]
.LBB0_3745:
	s_waitcnt vmcnt(0)
	v_lshlrev_b32_e32 v18, 16, v6
	v_and_b32_e32 v19, 0xffff0000, v6
	s_waitcnt lgkmcnt(0)
	v_lshlrev_b32_e32 v20, 16, v2
	v_and_b32_e32 v21, 0xffff0000, v2
	v_lshlrev_b32_e32 v22, 16, v10
	v_and_b32_e32 v23, 0xffff0000, v10
	v_pk_fma_f32 v[18:19], v[18:19], v[20:21], v[22:23]
	v_lshlrev_b32_e32 v6, 16, v7
	v_cvt_pk_bf16_f32 v2, v18, v19
	v_and_b32_e32 v7, 0xffff0000, v7
	v_lshlrev_b32_e32 v18, 16, v3
	v_and_b32_e32 v19, 0xffff0000, v3
	v_lshlrev_b32_e32 v10, 16, v11
	v_and_b32_e32 v11, 0xffff0000, v11
	v_pk_fma_f32 v[6:7], v[6:7], v[18:19], v[10:11]
	v_lshlrev_b32_e32 v10, 16, v4
	v_cvt_pk_bf16_f32 v3, v6, v7
	v_lshlrev_b32_e32 v6, 16, v8
	v_and_b32_e32 v7, 0xffff0000, v8
	v_and_b32_e32 v11, 0xffff0000, v4
	v_lshlrev_b32_e32 v18, 16, v12
	v_and_b32_e32 v19, 0xffff0000, v12
	v_pk_fma_f32 v[6:7], v[6:7], v[10:11], v[18:19]
	v_lshlrev_b32_e32 v8, 16, v5
	v_cvt_pk_bf16_f32 v4, v6, v7
	v_lshlrev_b32_e32 v6, 16, v9
	v_and_b32_e32 v7, 0xffff0000, v9
	v_and_b32_e32 v9, 0xffff0000, v5
	v_lshlrev_b32_e32 v10, 16, v13
	v_and_b32_e32 v11, 0xffff0000, v13
	v_pk_fma_f32 v[6:7], v[6:7], v[8:9], v[10:11]
	v_add_u32_e32 v1, 0x500, v15
	v_cvt_pk_bf16_f32 v5, v6, v7
	v_ashrrev_i32_e32 v1, 4, v1
	global_store_dwordx4 v[16:17], v[2:5], off
	s_and_b64 vcc, exec, s[0:1]
	s_nop 0
	v_add_u32_e32 v2, s63, v1
	v_mov_b64_e32 v[4:5], s[4:5]
	v_mad_i64_i32 v[4:5], s[44:45], v2, s60, v[4:5]
	v_lshl_add_u64 v[4:5], s[16:17], 1, v[4:5]
	v_lshl_add_u64 v[4:5], s[22:23], 1, v[4:5]
	v_lshl_add_u64 v[4:5], v[4:5], 0, v[96:97]
	v_mov_b64_e32 v[8:9], v[40:41]
	v_mov_b64_e32 v[10:11], v[42:43]
	v_mad_u64_u32 v[4:5], s[44:45], v1, s54, v[14:15]
	ds_read_b128 v[4:7], v4
	v_ashrrev_i32_e32 v3, 31, v2
	v_lshlrev_b64 v[2:3], 11, v[2:3]
	v_lshl_add_u64 v[2:3], s[24:25], 0, v[2:3]
	v_lshl_add_u64 v[12:13], v[2:3], 0, v[96:97]
	v_mov_b32_e32 v1, 0
	v_mov_b32_e32 v2, 0
	v_mov_b32_e32 v3, 0
	s_cbranch_vccnz .LBB0_3747
	v_mov_b64_e32 v[0:1], v[68:69]
	v_mov_b64_e32 v[2:3], v[70:71]
.LBB0_3747:
	s_waitcnt vmcnt(0)
	v_lshlrev_b32_e32 v16, 16, v8
	v_and_b32_e32 v17, 0xffff0000, v8
	s_waitcnt lgkmcnt(0)
	v_lshlrev_b32_e32 v18, 16, v4
	v_and_b32_e32 v19, 0xffff0000, v4
	v_lshlrev_b32_e32 v20, 16, v0
	v_and_b32_e32 v21, 0xffff0000, v0
	v_pk_fma_f32 v[16:17], v[16:17], v[18:19], v[20:21]
	v_lshlrev_b32_e32 v8, 16, v9
	v_cvt_pk_bf16_f32 v0, v16, v17
	v_and_b32_e32 v9, 0xffff0000, v9
	v_lshlrev_b32_e32 v4, 16, v5
	v_and_b32_e32 v5, 0xffff0000, v5
	v_lshlrev_b32_e32 v16, 16, v1
	v_and_b32_e32 v17, 0xffff0000, v1
	v_pk_fma_f32 v[4:5], v[8:9], v[4:5], v[16:17]
	v_lshlrev_b32_e32 v8, 16, v6
	v_cvt_pk_bf16_f32 v1, v4, v5
	v_lshlrev_b32_e32 v4, 16, v10
	v_and_b32_e32 v5, 0xffff0000, v10
	v_and_b32_e32 v9, 0xffff0000, v6
	v_lshlrev_b32_e32 v16, 16, v2
	v_and_b32_e32 v17, 0xffff0000, v2
	v_pk_fma_f32 v[4:5], v[4:5], v[8:9], v[16:17]
	v_lshlrev_b32_e32 v6, 16, v7
	v_cvt_pk_bf16_f32 v2, v4, v5
	v_lshlrev_b32_e32 v4, 16, v11
	v_and_b32_e32 v5, 0xffff0000, v11
	v_and_b32_e32 v7, 0xffff0000, v7
	v_lshlrev_b32_e32 v8, 16, v3
	v_and_b32_e32 v9, 0xffff0000, v3
	v_pk_fma_f32 v[4:5], v[4:5], v[6:7], v[8:9]
	s_and_b64 vcc, exec, s[0:1]
	v_cvt_pk_bf16_f32 v3, v4, v5
	global_store_dwordx4 v[12:13], v[0:3], off
	v_mov_b32_e32 v10, 0
	v_mov_b32_e32 v11, 0
	v_add_u32_e32 v0, 0x600, v15
	v_ashrrev_i32_e32 v1, 4, v0
	v_add_u32_e32 v0, s63, v1
	v_mov_b64_e32 v[2:3], s[4:5]
	v_mad_i64_i32 v[2:3], s[44:45], v0, s60, v[2:3]
	v_lshl_add_u64 v[2:3], s[16:17], 1, v[2:3]
	v_lshl_add_u64 v[2:3], s[22:23], 1, v[2:3]
	v_lshl_add_u64 v[2:3], v[2:3], 0, v[96:97]
	v_mov_b64_e32 v[6:7], v[44:45]
	v_mov_b64_e32 v[8:9], v[46:47]
	v_mad_u64_u32 v[2:3], s[44:45], v1, s54, v[14:15]
	ds_read_b128 v[2:5], v2
	v_ashrrev_i32_e32 v1, 31, v0
	v_lshlrev_b64 v[0:1], 11, v[0:1]
	v_lshl_add_u64 v[0:1], s[24:25], 0, v[0:1]
	v_lshl_add_u64 v[16:17], v[0:1], 0, v[96:97]
	v_mov_b32_e32 v0, 0
	v_mov_b32_e32 v12, 0
	v_mov_b32_e32 v13, 0
	s_cbranch_vccnz .LBB0_3749
	v_mov_b64_e32 v[10:11], v[72:73]
	v_mov_b64_e32 v[12:13], v[74:75]
.LBB0_3749:
	s_waitcnt vmcnt(0)
	v_lshlrev_b32_e32 v18, 16, v6
	v_and_b32_e32 v19, 0xffff0000, v6
	s_waitcnt lgkmcnt(0)
	v_lshlrev_b32_e32 v20, 16, v2
	v_and_b32_e32 v21, 0xffff0000, v2
	v_lshlrev_b32_e32 v22, 16, v10
	v_and_b32_e32 v23, 0xffff0000, v10
	v_pk_fma_f32 v[18:19], v[18:19], v[20:21], v[22:23]
	v_lshlrev_b32_e32 v6, 16, v7
	v_cvt_pk_bf16_f32 v2, v18, v19
	v_and_b32_e32 v7, 0xffff0000, v7
	v_lshlrev_b32_e32 v18, 16, v3
	v_and_b32_e32 v19, 0xffff0000, v3
	v_lshlrev_b32_e32 v10, 16, v11
	v_and_b32_e32 v11, 0xffff0000, v11
	v_pk_fma_f32 v[6:7], v[6:7], v[18:19], v[10:11]
	v_lshlrev_b32_e32 v10, 16, v4
	v_cvt_pk_bf16_f32 v3, v6, v7
	v_lshlrev_b32_e32 v6, 16, v8
	v_and_b32_e32 v7, 0xffff0000, v8
	v_and_b32_e32 v11, 0xffff0000, v4
	v_lshlrev_b32_e32 v18, 16, v12
	v_and_b32_e32 v19, 0xffff0000, v12
	v_pk_fma_f32 v[6:7], v[6:7], v[10:11], v[18:19]
	v_lshlrev_b32_e32 v8, 16, v5
	v_cvt_pk_bf16_f32 v4, v6, v7
	v_lshlrev_b32_e32 v6, 16, v9
	v_and_b32_e32 v7, 0xffff0000, v9
	v_and_b32_e32 v9, 0xffff0000, v5
	v_lshlrev_b32_e32 v10, 16, v13
	v_and_b32_e32 v11, 0xffff0000, v13
	v_pk_fma_f32 v[6:7], v[6:7], v[8:9], v[10:11]
	v_add_u32_e32 v1, 0x700, v15
	v_cvt_pk_bf16_f32 v5, v6, v7
	v_ashrrev_i32_e32 v1, 4, v1
	global_store_dwordx4 v[16:17], v[2:5], off
	s_and_b64 vcc, exec, s[0:1]
	s_nop 0
	v_add_u32_e32 v2, s63, v1
	v_mov_b64_e32 v[4:5], s[4:5]
	v_mad_i64_i32 v[4:5], s[44:45], v2, s60, v[4:5]
	v_lshl_add_u64 v[4:5], s[16:17], 1, v[4:5]
	v_lshl_add_u64 v[4:5], s[22:23], 1, v[4:5]
	v_lshl_add_u64 v[4:5], v[4:5], 0, v[96:97]
	v_mov_b64_e32 v[8:9], v[48:49]
	v_mov_b64_e32 v[10:11], v[50:51]
	v_mad_u64_u32 v[4:5], s[44:45], v1, s54, v[14:15]
	ds_read_b128 v[4:7], v4
	v_ashrrev_i32_e32 v3, 31, v2
	v_lshlrev_b64 v[2:3], 11, v[2:3]
	v_lshl_add_u64 v[2:3], s[24:25], 0, v[2:3]
	v_lshl_add_u64 v[12:13], v[2:3], 0, v[96:97]
	v_mov_b32_e32 v1, 0
	v_mov_b32_e32 v2, 0
	v_mov_b32_e32 v3, 0
	s_cbranch_vccnz .LBB0_3732
	v_mov_b64_e32 v[0:1], v[76:77]
	v_mov_b64_e32 v[2:3], v[78:79]
	s_branch .LBB0_3732

.LBB0_3809:
	v_lshl_add_u64 v[28:29], s[30:31], 0, v[22:23]
	v_add_co_u32_e32 v26, vcc, 0x4c000, v28
	s_nop 1
	v_addc_co_u32_e32 v27, vcc, 0, v29, vcc
	global_load_dwordx2 v[40:41], v[26:27], off
	v_lshl_add_u64 v[26:27], v[8:9], 0, s[22:23]
	s_waitcnt lgkmcnt(0)
	global_load_dwordx4 v[36:39], v[26:27], off
	s_waitcnt vmcnt(1)
	v_pk_mul_f32 v[44:45], v[40:41], s[16:17] op_sel:[1,0] op_sel_hi:[0,0]
	v_fma_f32 v40, -v45, v45, v44
	v_max_f32_e32 v40, 0, v40
	v_add_f32_e32 v40, 0x3727c5ac, v40
	v_mul_f32_e32 v41, 0x4b800000, v40
	v_cmp_gt_f32_e32 vcc, s53, v40
	s_waitcnt vmcnt(0)
	v_pk_add_f32 v[36:37], v[36:37], v[44:45] op_sel:[0,1] neg_lo:[0,1] neg_hi:[0,1]
	v_pk_add_f32 v[38:39], v[38:39], v[44:45] op_sel:[0,1] neg_lo:[0,1] neg_hi:[0,1]
	v_cndmask_b32_e32 v40, v40, v41, vcc
	v_rsq_f32_e32 v46, v40
	ds_read_b128 v[40:43], v35
	v_mul_f32_e32 v44, 0x45800000, v46
	v_cndmask_b32_e32 v44, v46, v44, vcc
	v_pk_mul_f32 v[36:37], v[36:37], v[44:45] op_sel_hi:[1,0]
	v_pk_mul_f32 v[38:39], v[38:39], v[44:45] op_sel_hi:[1,0]
	v_pk_fma_f32 v[36:37], v[0:1], v[36:37], v[4:5]
	v_pk_fma_f32 v[38:39], v[2:3], v[38:39], v[6:7]
	s_waitcnt lgkmcnt(0)
	v_pk_fma_f32 v[40:41], v[36:37], s[18:19], v[40:41] op_sel_hi:[1,0,1]
	v_pk_fma_f32 v[42:43], v[38:39], s[18:19], v[42:43] op_sel_hi:[1,0,1]
	v_pk_mul_f32 v[36:37], v[40:41], v[40:41]
	v_add_f32_e32 v44, v41, v40
	v_pk_mul_f32 v[38:39], v[42:43], v[42:43]
	v_add_f32_e32 v36, v37, v36
	v_add_f32_e32 v44, v42, v44
	v_add_f32_e32 v36, v38, v36
	v_add_f32_e32 v37, v43, v44
	v_add_f32_e32 v36, v39, v36
	ds_bpermute_b32 v38, v30, v37
	ds_bpermute_b32 v39, v30, v36
	v_lshl_add_u64 v[44:45], s[30:31], 0, v[24:25]
	v_add_co_u32_e32 v44, vcc, s54, v44
	s_waitcnt lgkmcnt(1)
	v_add_f32_e32 v37, v37, v38
	s_waitcnt lgkmcnt(0)
	v_add_f32_e32 v36, v36, v39
	ds_bpermute_b32 v38, v31, v37
	ds_bpermute_b32 v39, v31, v36
	v_addc_co_u32_e32 v45, vcc, 0, v45, vcc
	global_store_dwordx4 v[44:45], v[40:43], off offset:3584
	s_waitcnt lgkmcnt(1)
	v_add_f32_e32 v37, v37, v38
	s_waitcnt lgkmcnt(0)
	v_add_f32_e32 v36, v36, v39
	ds_bpermute_b32 v38, v32, v37
	ds_bpermute_b32 v39, v32, v36
	s_waitcnt lgkmcnt(1)
	v_add_f32_e32 v37, v37, v38
	s_waitcnt lgkmcnt(0)
	v_add_f32_e32 v38, v36, v39
	ds_bpermute_b32 v36, v33, v37
	ds_bpermute_b32 v39, v33, v38
	s_waitcnt lgkmcnt(1)
	v_add_f32_e32 v36, v37, v36
	s_waitcnt lgkmcnt(0)
	v_add_f32_e32 v37, v38, v39
	ds_bpermute_b32 v38, v34, v36
	ds_bpermute_b32 v39, v34, v37
	s_and_saveexec_b64 s[24:25], s[0:1]
	s_cbranch_execz .LBB0_3811
	v_add_co_u32_e32 v28, vcc, 0x5c000, v28
	s_waitcnt lgkmcnt(1)
	v_add_f32_e32 v36, v36, v38
	v_addc_co_u32_e32 v29, vcc, 0, v29, vcc
	s_waitcnt lgkmcnt(0)
	v_add_f32_e32 v37, v37, v39
	v_mov_b32_e32 v92, v28
	v_mov_b32_e32 v93, v29
	v_and_b32_e32 v90, 0x3ff, v28
	v_add_u32_e32 v90, 68608, v90
	ds_write2_b32 v90, v36, v37 offset1:1
.LBB0_3811:
	s_or_b64 exec, exec, s[24:25]
	v_lshl_add_u64 v[28:29], s[30:31], 0, v[20:21]
	v_add_co_u32_e32 v36, vcc, 0x4c000, v28
	s_nop 1
	v_addc_co_u32_e32 v37, vcc, 0, v29, vcc
	global_load_dwordx2 v[40:41], v[36:37], off
	v_add_co_u32_e32 v36, vcc, s55, v26
	s_waitcnt vmcnt(0)
	v_pk_mul_f32 v[44:45], v[40:41], s[16:17] op_sel:[1,0] op_sel_hi:[0,0]
	v_addc_co_u32_e32 v37, vcc, 0, v27, vcc
	s_waitcnt lgkmcnt(0)
	global_load_dwordx4 v[36:39], v[36:37], off
	v_fma_f32 v40, -v45, v45, v44
	v_max_f32_e32 v40, 0, v40
	v_add_f32_e32 v40, 0x3727c5ac, v40
	v_mul_f32_e32 v41, 0x4b800000, v40
	v_cmp_gt_f32_e32 vcc, s53, v40
	s_waitcnt vmcnt(0)
	v_pk_add_f32 v[36:37], v[36:37], v[44:45] op_sel:[0,1] neg_lo:[0,1] neg_hi:[0,1]
	v_cndmask_b32_e32 v40, v40, v41, vcc
	v_rsq_f32_e32 v46, v40
	ds_read_b128 v[40:43], v35 offset:4224
	v_pk_add_f32 v[38:39], v[38:39], v[44:45] op_sel:[0,1] neg_lo:[0,1] neg_hi:[0,1]
	v_mul_f32_e32 v44, 0x45800000, v46
	v_cndmask_b32_e32 v44, v46, v44, vcc
	v_pk_mul_f32 v[36:37], v[36:37], v[44:45] op_sel_hi:[1,0]
	v_pk_mul_f32 v[38:39], v[38:39], v[44:45] op_sel_hi:[1,0]
	v_pk_fma_f32 v[36:37], v[0:1], v[36:37], v[4:5]
	v_pk_fma_f32 v[38:39], v[2:3], v[38:39], v[6:7]
	s_waitcnt lgkmcnt(0)
	v_pk_fma_f32 v[40:41], v[36:37], s[18:19], v[40:41] op_sel_hi:[1,0,1]
	v_pk_fma_f32 v[42:43], v[38:39], s[18:19], v[42:43] op_sel_hi:[1,0,1]
	v_pk_mul_f32 v[36:37], v[40:41], v[40:41]
	v_add_f32_e32 v44, v41, v40
	v_pk_mul_f32 v[38:39], v[42:43], v[42:43]
	v_add_f32_e32 v36, v37, v36
	v_add_f32_e32 v44, v42, v44
	v_add_f32_e32 v36, v38, v36
	v_add_f32_e32 v37, v43, v44
	v_add_f32_e32 v36, v39, v36
	ds_bpermute_b32 v38, v30, v37
	ds_bpermute_b32 v39, v30, v36
	v_lshl_add_u64 v[44:45], s[30:31], 0, v[18:19]
	v_add_co_u32_e32 v44, vcc, s54, v44
	s_waitcnt lgkmcnt(1)
	v_add_f32_e32 v37, v37, v38
	s_waitcnt lgkmcnt(0)
	v_add_f32_e32 v36, v36, v39
	ds_bpermute_b32 v38, v31, v37
	ds_bpermute_b32 v39, v31, v36
	v_addc_co_u32_e32 v45, vcc, 0, v45, vcc
	global_store_dwordx4 v[44:45], v[40:43], off offset:3584
	s_waitcnt lgkmcnt(1)
	v_add_f32_e32 v37, v37, v38
	s_waitcnt lgkmcnt(0)
	v_add_f32_e32 v36, v36, v39
	ds_bpermute_b32 v38, v32, v37
	ds_bpermute_b32 v39, v32, v36
	s_waitcnt lgkmcnt(1)
	v_add_f32_e32 v37, v37, v38
	s_waitcnt lgkmcnt(0)
	v_add_f32_e32 v38, v36, v39
	ds_bpermute_b32 v36, v33, v37
	ds_bpermute_b32 v39, v33, v38
	s_waitcnt lgkmcnt(1)
	v_add_f32_e32 v36, v37, v36
	s_waitcnt lgkmcnt(0)
	v_add_f32_e32 v37, v38, v39
	ds_bpermute_b32 v38, v34, v36
	ds_bpermute_b32 v39, v34, v37
	s_and_saveexec_b64 s[24:25], s[0:1]
	s_cbranch_execz .LBB0_3813
	v_add_co_u32_e32 v28, vcc, 0x5c000, v28
	s_waitcnt lgkmcnt(1)
	v_add_f32_e32 v36, v36, v38
	v_addc_co_u32_e32 v29, vcc, 0, v29, vcc
	s_waitcnt lgkmcnt(0)
	v_add_f32_e32 v37, v37, v39
	v_mov_b32_e32 v92, v28
	v_mov_b32_e32 v93, v29
	v_and_b32_e32 v90, 0x3ff, v28
	v_add_u32_e32 v90, 68608, v90
	ds_write2_b32 v90, v36, v37 offset1:1
.LBB0_3813:
	s_or_b64 exec, exec, s[24:25]
	v_lshl_add_u64 v[28:29], s[30:31], 0, v[16:17]
	v_add_co_u32_e32 v36, vcc, 0x4c000, v28
	s_nop 1
	v_addc_co_u32_e32 v37, vcc, 0, v29, vcc
	global_load_dwordx2 v[40:41], v[36:37], off
	v_add_co_u32_e32 v36, vcc, s38, v26
	s_waitcnt vmcnt(0)
	v_pk_mul_f32 v[44:45], v[40:41], s[16:17] op_sel:[1,0] op_sel_hi:[0,0]
	v_addc_co_u32_e32 v37, vcc, 0, v27, vcc
	s_waitcnt lgkmcnt(0)
	global_load_dwordx4 v[36:39], v[36:37], off
	v_fma_f32 v40, -v45, v45, v44
	v_max_f32_e32 v40, 0, v40
	v_add_f32_e32 v40, 0x3727c5ac, v40
	v_mul_f32_e32 v41, 0x4b800000, v40
	v_cmp_gt_f32_e32 vcc, s53, v40
	s_waitcnt vmcnt(0)
	v_pk_add_f32 v[36:37], v[36:37], v[44:45] op_sel:[0,1] neg_lo:[0,1] neg_hi:[0,1]
	v_cndmask_b32_e32 v40, v40, v41, vcc
	v_rsq_f32_e32 v46, v40
	ds_read_b128 v[40:43], v35 offset:8448
	v_pk_add_f32 v[38:39], v[38:39], v[44:45] op_sel:[0,1] neg_lo:[0,1] neg_hi:[0,1]
	v_mul_f32_e32 v44, 0x45800000, v46
	v_cndmask_b32_e32 v44, v46, v44, vcc
	v_pk_mul_f32 v[36:37], v[36:37], v[44:45] op_sel_hi:[1,0]
	v_pk_mul_f32 v[38:39], v[38:39], v[44:45] op_sel_hi:[1,0]
	v_pk_fma_f32 v[36:37], v[0:1], v[36:37], v[4:5]
	v_pk_fma_f32 v[38:39], v[2:3], v[38:39], v[6:7]
	s_waitcnt lgkmcnt(0)
	v_pk_fma_f32 v[40:41], v[36:37], s[18:19], v[40:41] op_sel_hi:[1,0,1]
	v_pk_fma_f32 v[42:43], v[38:39], s[18:19], v[42:43] op_sel_hi:[1,0,1]
	v_pk_mul_f32 v[36:37], v[40:41], v[40:41]
	v_add_f32_e32 v44, v41, v40
	v_pk_mul_f32 v[38:39], v[42:43], v[42:43]
	v_add_f32_e32 v36, v37, v36
	v_add_f32_e32 v44, v42, v44
	v_add_f32_e32 v36, v38, v36
	v_add_f32_e32 v37, v43, v44
	v_add_f32_e32 v36, v39, v36
	ds_bpermute_b32 v38, v30, v37
	ds_bpermute_b32 v39, v30, v36
	v_lshl_add_u64 v[44:45], s[30:31], 0, v[14:15]
	v_add_co_u32_e32 v44, vcc, s54, v44
	s_waitcnt lgkmcnt(1)
	v_add_f32_e32 v37, v37, v38
	s_waitcnt lgkmcnt(0)
	v_add_f32_e32 v36, v36, v39
	ds_bpermute_b32 v38, v31, v37
	ds_bpermute_b32 v39, v31, v36
	v_addc_co_u32_e32 v45, vcc, 0, v45, vcc
	global_store_dwordx4 v[44:45], v[40:43], off offset:3584
	s_waitcnt lgkmcnt(1)
	v_add_f32_e32 v37, v37, v38
	s_waitcnt lgkmcnt(0)
	v_add_f32_e32 v36, v36, v39
	ds_bpermute_b32 v38, v32, v37
	ds_bpermute_b32 v39, v32, v36
	s_waitcnt lgkmcnt(1)
	v_add_f32_e32 v37, v37, v38
	s_waitcnt lgkmcnt(0)
	v_add_f32_e32 v38, v36, v39
	ds_bpermute_b32 v36, v33, v37
	ds_bpermute_b32 v39, v33, v38
	s_waitcnt lgkmcnt(1)
	v_add_f32_e32 v36, v37, v36
	s_waitcnt lgkmcnt(0)
	v_add_f32_e32 v37, v38, v39
	ds_bpermute_b32 v38, v34, v36
	ds_bpermute_b32 v39, v34, v37
	s_and_saveexec_b64 s[24:25], s[0:1]
	s_cbranch_execz .LBB0_3815
	v_add_co_u32_e32 v28, vcc, 0x5c000, v28
	s_waitcnt lgkmcnt(1)
	v_add_f32_e32 v36, v36, v38
	v_addc_co_u32_e32 v29, vcc, 0, v29, vcc
	s_waitcnt lgkmcnt(0)
	v_add_f32_e32 v37, v37, v39
	v_mov_b32_e32 v92, v28
	v_mov_b32_e32 v93, v29
	v_and_b32_e32 v90, 0x3ff, v28
	v_add_u32_e32 v90, 68608, v90
	ds_write2_b32 v90, v36, v37 offset1:1
.LBB0_3815:
	s_or_b64 exec, exec, s[24:25]
	v_lshl_add_u64 v[28:29], s[30:31], 0, v[12:13]
	v_add_co_u32_e32 v36, vcc, 0x4c000, v28
	s_nop 1
	v_addc_co_u32_e32 v37, vcc, 0, v29, vcc
	global_load_dwordx2 v[40:41], v[36:37], off
	v_add_co_u32_e32 v26, vcc, s56, v26
	s_nop 1
	v_addc_co_u32_e32 v27, vcc, 0, v27, vcc
	s_waitcnt lgkmcnt(0)
	global_load_dwordx4 v[36:39], v[26:27], off
	s_waitcnt vmcnt(1)
	v_pk_mul_f32 v[26:27], v[40:41], s[16:17] op_sel:[1,0] op_sel_hi:[0,0]
	v_fma_f32 v40, -v27, v27, v26
	v_max_f32_e32 v40, 0, v40
	v_add_f32_e32 v40, 0x3727c5ac, v40
	v_mul_f32_e32 v41, 0x4b800000, v40
	v_cmp_gt_f32_e32 vcc, s53, v40
	s_waitcnt vmcnt(0)
	v_pk_add_f32 v[36:37], v[36:37], v[26:27] op_sel:[0,1] neg_lo:[0,1] neg_hi:[0,1]
	v_pk_add_f32 v[26:27], v[38:39], v[26:27] op_sel:[0,1] neg_lo:[0,1] neg_hi:[0,1]
	v_cndmask_b32_e32 v40, v40, v41, vcc
	v_rsq_f32_e32 v44, v40
	ds_read_b128 v[40:43], v35 offset:12672
	v_mul_f32_e32 v38, 0x45800000, v44
	v_cndmask_b32_e32 v38, v44, v38, vcc
	v_pk_mul_f32 v[36:37], v[36:37], v[38:39] op_sel_hi:[1,0]
	v_pk_mul_f32 v[26:27], v[26:27], v[38:39] op_sel_hi:[1,0]
	v_pk_fma_f32 v[36:37], v[0:1], v[36:37], v[4:5]
	v_pk_fma_f32 v[26:27], v[2:3], v[26:27], v[6:7]
	s_waitcnt lgkmcnt(0)
	v_pk_fma_f32 v[38:39], v[36:37], s[18:19], v[40:41] op_sel_hi:[1,0,1]
	v_pk_fma_f32 v[40:41], v[26:27], s[18:19], v[42:43] op_sel_hi:[1,0,1]
	v_pk_mul_f32 v[26:27], v[38:39], v[38:39]
	v_add_f32_e32 v42, v39, v38
	v_pk_mul_f32 v[36:37], v[40:41], v[40:41]
	v_add_f32_e32 v26, v27, v26
	v_add_f32_e32 v42, v40, v42
	v_add_f32_e32 v26, v36, v26
	v_add_f32_e32 v27, v41, v42
	v_add_f32_e32 v26, v37, v26
	ds_bpermute_b32 v36, v30, v27
	ds_bpermute_b32 v37, v30, v26
	v_lshl_add_u64 v[42:43], s[30:31], 0, v[10:11]
	v_add_co_u32_e32 v42, vcc, s54, v42
	s_waitcnt lgkmcnt(1)
	v_add_f32_e32 v27, v27, v36
	s_waitcnt lgkmcnt(0)
	v_add_f32_e32 v26, v26, v37
	ds_bpermute_b32 v36, v31, v27
	ds_bpermute_b32 v37, v31, v26
	v_addc_co_u32_e32 v43, vcc, 0, v43, vcc
	global_store_dwordx4 v[42:43], v[38:41], off offset:3584
	s_waitcnt lgkmcnt(1)
	v_add_f32_e32 v27, v27, v36
	s_waitcnt lgkmcnt(0)
	v_add_f32_e32 v26, v26, v37
	ds_bpermute_b32 v36, v32, v27
	ds_bpermute_b32 v37, v32, v26
	s_waitcnt lgkmcnt(1)
	v_add_f32_e32 v27, v27, v36
	s_waitcnt lgkmcnt(0)
	v_add_f32_e32 v36, v26, v37
	ds_bpermute_b32 v26, v33, v27
	ds_bpermute_b32 v37, v33, v36
	s_waitcnt lgkmcnt(1)
	v_add_f32_e32 v26, v27, v26
	s_waitcnt lgkmcnt(0)
	v_add_f32_e32 v27, v36, v37
	ds_bpermute_b32 v36, v34, v26
	ds_bpermute_b32 v37, v34, v27
	s_and_saveexec_b64 s[24:25], s[0:1]
	s_cbranch_execz .LBB0_3808
	s_waitcnt lgkmcnt(1)
	v_add_f32_e32 v36, v26, v36
	v_add_co_u32_e32 v26, vcc, 0x5c000, v28
	s_waitcnt lgkmcnt(0)
	v_add_f32_e32 v37, v27, v37
	v_addc_co_u32_e32 v27, vcc, 0, v29, vcc
	v_mov_b32_e32 v92, v26
	v_mov_b32_e32 v93, v27
	v_and_b32_e32 v90, 0x3ff, v26
	v_add_u32_e32 v90, 68608, v90
	ds_write2_b32 v90, v36, v37 offset1:1
	s_branch .LBB0_3808

.LBB0_4054:
	v_lshl_add_u64 v[30:31], v[12:13], 0, s[24:25]
	v_add_co_u32_e32 v28, vcc, 0x5c000, v30
	s_nop 1
	v_addc_co_u32_e32 v29, vcc, 0, v31, vcc
	global_load_dwordx2 v[42:43], v[28:29], off
	v_lshl_add_u64 v[28:29], v[10:11], 0, v[8:9]
	s_waitcnt lgkmcnt(0)
	global_load_dwordx4 v[38:41], v[28:29], off
	s_waitcnt vmcnt(1)
	v_pk_mul_f32 v[46:47], v[42:43], s[18:19] op_sel:[1,0] op_sel_hi:[0,0]
	v_fma_f32 v42, -v47, v47, v46
	v_max_f32_e32 v42, 0, v42
	v_add_f32_e32 v42, 0x3727c5ac, v42
	v_mul_f32_e32 v43, 0x4b800000, v42
	v_cmp_gt_f32_e32 vcc, s58, v42
	s_waitcnt vmcnt(0)
	v_pk_add_f32 v[38:39], v[38:39], v[46:47] op_sel:[0,1] neg_lo:[0,1] neg_hi:[0,1]
	v_pk_add_f32 v[40:41], v[40:41], v[46:47] op_sel:[0,1] neg_lo:[0,1] neg_hi:[0,1]
	v_cndmask_b32_e32 v42, v42, v43, vcc
	v_rsq_f32_e32 v48, v42
	ds_read_b128 v[42:45], v37
	v_mul_f32_e32 v46, 0x45800000, v48
	v_cndmask_b32_e32 v46, v48, v46, vcc
	v_pk_mul_f32 v[38:39], v[38:39], v[46:47] op_sel_hi:[1,0]
	v_pk_mul_f32 v[40:41], v[40:41], v[46:47] op_sel_hi:[1,0]
	v_pk_fma_f32 v[38:39], v[0:1], v[38:39], v[4:5]
	v_pk_fma_f32 v[40:41], v[2:3], v[40:41], v[6:7]
	s_waitcnt lgkmcnt(0)
	v_pk_fma_f32 v[42:43], v[38:39], s[20:21], v[42:43] op_sel_hi:[1,0,1]
	v_pk_fma_f32 v[44:45], v[40:41], s[20:21], v[44:45] op_sel_hi:[1,0,1]
	v_pk_mul_f32 v[38:39], v[42:43], v[42:43]
	v_add_f32_e32 v46, v43, v42
	v_pk_mul_f32 v[40:41], v[44:45], v[44:45]
	v_add_f32_e32 v38, v39, v38
	v_add_f32_e32 v46, v44, v46
	v_add_f32_e32 v38, v40, v38
	v_add_f32_e32 v39, v45, v46
	v_add_f32_e32 v38, v41, v38
	ds_bpermute_b32 v40, v32, v39
	ds_bpermute_b32 v41, v32, v38
	v_lshl_add_u64 v[46:47], v[26:27], 0, v[8:9]
	global_store_dwordx4 v[46:47], v[42:45], off offset:-8
	s_waitcnt lgkmcnt(1)
	v_add_f32_e32 v39, v39, v40
	s_waitcnt lgkmcnt(0)
	v_add_f32_e32 v38, v38, v41
	ds_bpermute_b32 v40, v33, v39
	ds_bpermute_b32 v41, v33, v38
	s_waitcnt lgkmcnt(1)
	v_add_f32_e32 v39, v39, v40
	s_waitcnt lgkmcnt(0)
	v_add_f32_e32 v38, v38, v41
	ds_bpermute_b32 v40, v34, v39
	ds_bpermute_b32 v41, v34, v38
	s_waitcnt lgkmcnt(1)
	v_add_f32_e32 v39, v39, v40
	s_waitcnt lgkmcnt(0)
	v_add_f32_e32 v40, v38, v41
	ds_bpermute_b32 v38, v35, v39
	ds_bpermute_b32 v41, v35, v40
	s_waitcnt lgkmcnt(1)
	v_add_f32_e32 v38, v39, v38
	s_waitcnt lgkmcnt(0)
	v_add_f32_e32 v39, v40, v41
	ds_bpermute_b32 v40, v36, v38
	ds_bpermute_b32 v41, v36, v39
	s_and_saveexec_b64 s[26:27], s[0:1]
	s_cbranch_execz .LBB0_4056
	v_add_co_u32_e32 v30, vcc, 0x6c000, v30
	s_waitcnt lgkmcnt(1)
	v_add_f32_e32 v38, v38, v40
	v_addc_co_u32_e32 v31, vcc, 0, v31, vcc
	s_waitcnt lgkmcnt(0)
	v_add_f32_e32 v39, v39, v41
	v_mov_b32_e32 v92, v30
	v_mov_b32_e32 v93, v31
	v_and_b32_e32 v90, 0x3ff, v30
	v_add_u32_e32 v90, 68608, v90
	ds_write2_b32 v90, v38, v39 offset1:1
.LBB0_4056:
	s_or_b64 exec, exec, s[26:27]
	v_lshl_add_u64 v[30:31], v[24:25], 0, s[24:25]
	v_add_co_u32_e32 v38, vcc, 0x5c000, v30
	s_nop 1
	v_addc_co_u32_e32 v39, vcc, 0, v31, vcc
	global_load_dwordx2 v[42:43], v[38:39], off
	v_add_co_u32_e32 v38, vcc, s59, v28
	s_waitcnt vmcnt(0)
	v_pk_mul_f32 v[46:47], v[42:43], s[18:19] op_sel:[1,0] op_sel_hi:[0,0]
	v_addc_co_u32_e32 v39, vcc, 0, v29, vcc
	s_waitcnt lgkmcnt(0)
	global_load_dwordx4 v[38:41], v[38:39], off
	v_fma_f32 v42, -v47, v47, v46
	v_max_f32_e32 v42, 0, v42
	v_add_f32_e32 v42, 0x3727c5ac, v42
	v_mul_f32_e32 v43, 0x4b800000, v42
	v_cmp_gt_f32_e32 vcc, s58, v42
	s_waitcnt vmcnt(0)
	v_pk_add_f32 v[38:39], v[38:39], v[46:47] op_sel:[0,1] neg_lo:[0,1] neg_hi:[0,1]
	v_cndmask_b32_e32 v42, v42, v43, vcc
	v_rsq_f32_e32 v48, v42
	ds_read_b128 v[42:45], v37 offset:4224
	v_pk_add_f32 v[40:41], v[40:41], v[46:47] op_sel:[0,1] neg_lo:[0,1] neg_hi:[0,1]
	v_mul_f32_e32 v46, 0x45800000, v48
	v_cndmask_b32_e32 v46, v48, v46, vcc
	v_pk_mul_f32 v[38:39], v[38:39], v[46:47] op_sel_hi:[1,0]
	v_pk_mul_f32 v[40:41], v[40:41], v[46:47] op_sel_hi:[1,0]
	v_pk_fma_f32 v[38:39], v[0:1], v[38:39], v[4:5]
	v_pk_fma_f32 v[40:41], v[2:3], v[40:41], v[6:7]
	s_waitcnt lgkmcnt(0)
	v_pk_fma_f32 v[42:43], v[38:39], s[20:21], v[42:43] op_sel_hi:[1,0,1]
	v_pk_fma_f32 v[44:45], v[40:41], s[20:21], v[44:45] op_sel_hi:[1,0,1]
	v_pk_mul_f32 v[38:39], v[42:43], v[42:43]
	v_add_f32_e32 v46, v43, v42
	v_pk_mul_f32 v[40:41], v[44:45], v[44:45]
	v_add_f32_e32 v38, v39, v38
	v_add_f32_e32 v46, v44, v46
	v_add_f32_e32 v38, v40, v38
	v_add_f32_e32 v39, v45, v46
	v_add_f32_e32 v38, v41, v38
	ds_bpermute_b32 v40, v32, v39
	ds_bpermute_b32 v41, v32, v38
	v_lshl_add_u64 v[46:47], v[22:23], 0, v[8:9]
	global_store_dwordx4 v[46:47], v[42:45], off
	s_waitcnt lgkmcnt(1)
	v_add_f32_e32 v39, v39, v40
	s_waitcnt lgkmcnt(0)
	v_add_f32_e32 v38, v38, v41
	ds_bpermute_b32 v40, v33, v39
	ds_bpermute_b32 v41, v33, v38
	s_waitcnt lgkmcnt(1)
	v_add_f32_e32 v39, v39, v40
	s_waitcnt lgkmcnt(0)
	v_add_f32_e32 v38, v38, v41
	ds_bpermute_b32 v40, v34, v39
	ds_bpermute_b32 v41, v34, v38
	s_waitcnt lgkmcnt(1)
	v_add_f32_e32 v39, v39, v40
	s_waitcnt lgkmcnt(0)
	v_add_f32_e32 v40, v38, v41
	ds_bpermute_b32 v38, v35, v39
	ds_bpermute_b32 v41, v35, v40
	s_waitcnt lgkmcnt(1)
	v_add_f32_e32 v38, v39, v38
	s_waitcnt lgkmcnt(0)
	v_add_f32_e32 v39, v40, v41
	ds_bpermute_b32 v40, v36, v38
	ds_bpermute_b32 v41, v36, v39
	s_and_saveexec_b64 s[26:27], s[0:1]
	s_cbranch_execz .LBB0_4058
	v_add_co_u32_e32 v30, vcc, 0x6c000, v30
	s_waitcnt lgkmcnt(1)
	v_add_f32_e32 v38, v38, v40
	v_addc_co_u32_e32 v31, vcc, 0, v31, vcc
	s_waitcnt lgkmcnt(0)
	v_add_f32_e32 v39, v39, v41
	v_mov_b32_e32 v92, v30
	v_mov_b32_e32 v93, v31
	v_and_b32_e32 v90, 0x3ff, v30
	v_add_u32_e32 v90, 68608, v90
	ds_write2_b32 v90, v38, v39 offset1:1
.LBB0_4058:
	s_or_b64 exec, exec, s[26:27]
	v_lshl_add_u64 v[30:31], v[20:21], 0, s[24:25]
	v_add_co_u32_e32 v38, vcc, 0x5c000, v30
	s_nop 1
	v_addc_co_u32_e32 v39, vcc, 0, v31, vcc
	global_load_dwordx2 v[42:43], v[38:39], off
	v_add_co_u32_e32 v38, vcc, s60, v28
	s_waitcnt vmcnt(0)
	v_pk_mul_f32 v[46:47], v[42:43], s[18:19] op_sel:[1,0] op_sel_hi:[0,0]
	v_addc_co_u32_e32 v39, vcc, 0, v29, vcc
	s_waitcnt lgkmcnt(0)
	global_load_dwordx4 v[38:41], v[38:39], off
	v_fma_f32 v42, -v47, v47, v46
	v_max_f32_e32 v42, 0, v42
	v_add_f32_e32 v42, 0x3727c5ac, v42
	v_mul_f32_e32 v43, 0x4b800000, v42
	v_cmp_gt_f32_e32 vcc, s58, v42
	s_waitcnt vmcnt(0)
	v_pk_add_f32 v[38:39], v[38:39], v[46:47] op_sel:[0,1] neg_lo:[0,1] neg_hi:[0,1]
	v_cndmask_b32_e32 v42, v42, v43, vcc
	v_rsq_f32_e32 v48, v42
	ds_read_b128 v[42:45], v37 offset:8448
	v_pk_add_f32 v[40:41], v[40:41], v[46:47] op_sel:[0,1] neg_lo:[0,1] neg_hi:[0,1]
	v_mul_f32_e32 v46, 0x45800000, v48
	v_cndmask_b32_e32 v46, v48, v46, vcc
	v_pk_mul_f32 v[38:39], v[38:39], v[46:47] op_sel_hi:[1,0]
	v_pk_mul_f32 v[40:41], v[40:41], v[46:47] op_sel_hi:[1,0]
	v_pk_fma_f32 v[38:39], v[0:1], v[38:39], v[4:5]
	v_pk_fma_f32 v[40:41], v[2:3], v[40:41], v[6:7]
	s_waitcnt lgkmcnt(0)
	v_pk_fma_f32 v[42:43], v[38:39], s[20:21], v[42:43] op_sel_hi:[1,0,1]
	v_pk_fma_f32 v[44:45], v[40:41], s[20:21], v[44:45] op_sel_hi:[1,0,1]
	v_pk_mul_f32 v[38:39], v[42:43], v[42:43]
	v_add_f32_e32 v46, v43, v42
	v_pk_mul_f32 v[40:41], v[44:45], v[44:45]
	v_add_f32_e32 v38, v39, v38
	v_add_f32_e32 v46, v44, v46
	v_add_f32_e32 v38, v40, v38
	v_add_f32_e32 v39, v45, v46
	v_add_f32_e32 v38, v41, v38
	ds_bpermute_b32 v40, v32, v39
	ds_bpermute_b32 v41, v32, v38
	v_lshl_add_u64 v[46:47], v[18:19], 0, v[8:9]
	global_store_dwordx4 v[46:47], v[42:45], off
	s_waitcnt lgkmcnt(1)
	v_add_f32_e32 v39, v39, v40
	s_waitcnt lgkmcnt(0)
	v_add_f32_e32 v38, v38, v41
	ds_bpermute_b32 v40, v33, v39
	ds_bpermute_b32 v41, v33, v38
	s_waitcnt lgkmcnt(1)
	v_add_f32_e32 v39, v39, v40
	s_waitcnt lgkmcnt(0)
	v_add_f32_e32 v38, v38, v41
	ds_bpermute_b32 v40, v34, v39
	ds_bpermute_b32 v41, v34, v38
	s_waitcnt lgkmcnt(1)
	v_add_f32_e32 v39, v39, v40
	s_waitcnt lgkmcnt(0)
	v_add_f32_e32 v40, v38, v41
	ds_bpermute_b32 v38, v35, v39
	ds_bpermute_b32 v41, v35, v40
	s_waitcnt lgkmcnt(1)
	v_add_f32_e32 v38, v39, v38
	s_waitcnt lgkmcnt(0)
	v_add_f32_e32 v39, v40, v41
	ds_bpermute_b32 v40, v36, v38
	ds_bpermute_b32 v41, v36, v39
	s_and_saveexec_b64 s[26:27], s[0:1]
	s_cbranch_execz .LBB0_4060
	v_add_co_u32_e32 v30, vcc, 0x6c000, v30
	s_waitcnt lgkmcnt(1)
	v_add_f32_e32 v38, v38, v40
	v_addc_co_u32_e32 v31, vcc, 0, v31, vcc
	s_waitcnt lgkmcnt(0)
	v_add_f32_e32 v39, v39, v41
	v_mov_b32_e32 v92, v30
	v_mov_b32_e32 v93, v31
	v_and_b32_e32 v90, 0x3ff, v30
	v_add_u32_e32 v90, 68608, v90
	ds_write2_b32 v90, v38, v39 offset1:1
.LBB0_4060:
	s_or_b64 exec, exec, s[26:27]
	v_lshl_add_u64 v[30:31], v[16:17], 0, s[24:25]
	v_add_co_u32_e32 v38, vcc, 0x5c000, v30
	s_nop 1
	v_addc_co_u32_e32 v39, vcc, 0, v31, vcc
	global_load_dwordx2 v[42:43], v[38:39], off
	v_add_co_u32_e32 v28, vcc, s61, v28
	s_nop 1
	v_addc_co_u32_e32 v29, vcc, 0, v29, vcc
	s_waitcnt lgkmcnt(0)
	global_load_dwordx4 v[38:41], v[28:29], off
	s_waitcnt vmcnt(1)
	v_pk_mul_f32 v[28:29], v[42:43], s[18:19] op_sel:[1,0] op_sel_hi:[0,0]
	v_fma_f32 v42, -v29, v29, v28
	v_max_f32_e32 v42, 0, v42
	v_add_f32_e32 v42, 0x3727c5ac, v42
	v_mul_f32_e32 v43, 0x4b800000, v42
	v_cmp_gt_f32_e32 vcc, s58, v42
	s_waitcnt vmcnt(0)
	v_pk_add_f32 v[38:39], v[38:39], v[28:29] op_sel:[0,1] neg_lo:[0,1] neg_hi:[0,1]
	v_pk_add_f32 v[28:29], v[40:41], v[28:29] op_sel:[0,1] neg_lo:[0,1] neg_hi:[0,1]
	v_cndmask_b32_e32 v42, v42, v43, vcc
	v_rsq_f32_e32 v46, v42
	ds_read_b128 v[42:45], v37 offset:12672
	v_mul_f32_e32 v40, 0x45800000, v46
	v_cndmask_b32_e32 v40, v46, v40, vcc
	v_pk_mul_f32 v[38:39], v[38:39], v[40:41] op_sel_hi:[1,0]
	v_pk_mul_f32 v[28:29], v[28:29], v[40:41] op_sel_hi:[1,0]
	v_pk_fma_f32 v[38:39], v[0:1], v[38:39], v[4:5]
	v_pk_fma_f32 v[28:29], v[2:3], v[28:29], v[6:7]
	s_waitcnt lgkmcnt(0)
	v_pk_fma_f32 v[40:41], v[38:39], s[20:21], v[42:43] op_sel_hi:[1,0,1]
	v_pk_fma_f32 v[42:43], v[28:29], s[20:21], v[44:45] op_sel_hi:[1,0,1]
	v_pk_mul_f32 v[28:29], v[40:41], v[40:41]
	v_add_f32_e32 v44, v41, v40
	v_pk_mul_f32 v[38:39], v[42:43], v[42:43]
	v_add_f32_e32 v28, v29, v28
	v_add_f32_e32 v44, v42, v44
	v_add_f32_e32 v28, v38, v28
	v_add_f32_e32 v29, v43, v44
	v_add_f32_e32 v28, v39, v28
	ds_bpermute_b32 v38, v32, v29
	ds_bpermute_b32 v39, v32, v28
	v_lshl_add_u64 v[44:45], v[14:15], 0, v[8:9]
	global_store_dwordx4 v[44:45], v[40:43], off
	s_waitcnt lgkmcnt(1)
	v_add_f32_e32 v29, v29, v38
	s_waitcnt lgkmcnt(0)
	v_add_f32_e32 v28, v28, v39
	ds_bpermute_b32 v38, v33, v29
	ds_bpermute_b32 v39, v33, v28
	s_waitcnt lgkmcnt(1)
	v_add_f32_e32 v29, v29, v38
	s_waitcnt lgkmcnt(0)
	v_add_f32_e32 v28, v28, v39
	ds_bpermute_b32 v38, v34, v29
	ds_bpermute_b32 v39, v34, v28
	s_waitcnt lgkmcnt(1)
	v_add_f32_e32 v29, v29, v38
	s_waitcnt lgkmcnt(0)
	v_add_f32_e32 v38, v28, v39
	ds_bpermute_b32 v28, v35, v29
	ds_bpermute_b32 v39, v35, v38
	s_waitcnt lgkmcnt(1)
	v_add_f32_e32 v28, v29, v28
	s_waitcnt lgkmcnt(0)
	v_add_f32_e32 v29, v38, v39
	ds_bpermute_b32 v38, v36, v28
	ds_bpermute_b32 v39, v36, v29
	s_and_saveexec_b64 s[26:27], s[0:1]
	s_cbranch_execz .LBB0_4053
	s_waitcnt lgkmcnt(1)
	v_add_f32_e32 v38, v28, v38
	v_add_co_u32_e32 v28, vcc, 0x6c000, v30
	s_waitcnt lgkmcnt(0)
	v_add_f32_e32 v39, v29, v39
	v_addc_co_u32_e32 v29, vcc, 0, v31, vcc
	v_mov_b32_e32 v92, v28
	v_mov_b32_e32 v93, v29
	v_and_b32_e32 v90, 0x3ff, v28
	v_add_u32_e32 v90, 68608, v90
	ds_write2_b32 v90, v38, v39 offset1:1
	s_branch .LBB0_4053
